# O1+F2 EpiResid epilogues: batched src loads (16 in flight, rolling), counted vmcnt
# speedup vs baseline: 1.0087x; 1.0087x over previous
; __device__ __forceinline__ float fast_rcp(float x) { return __builtin_amdgcn_rcpf(x); }
;     __device__ __forceinline__ void mid(f32x4 (&acc)[2][2][4][2], const Unit& u, int wr, int wc, int fr, int fq, int t) const {
;         int fr_ = fr; asm volatile("" : "+v"(fr_));
;         const int row0 = u.pm * 256 + wr * 64 + fr_, col0 = u.pn * 256 + wc * 32 + 8 * fq, noff = C_GATE + (t == 8 ? 0 : 2048);
; #pragma unroll
;         for (int ai = 0; ai < 2; ++ai)
; #pragma unroll
;             for (int m = 0; m < 4; ++m) {
;                 const bf16_t* gp = P + (size_t)(row0 + ai * 128 + m * 16) * PS + noff + col0;
; #pragma unroll
;                 for (int bj = 0; bj < 2; ++bj) {
;                     const u32x4 gn = *(const u32x4*)(gp + bj * 128), gd = *(const u32x4*)(gp + bj * 128 + 2048);
;                     f32x4 r0, r1;
;                     r0[0] = bflo(gn.x) * fast_rcp(fmaxf(bflo(gd.x), 1e-20f)); r0[1] = bfhi(gn.x) * fast_rcp(fmaxf(bfhi(gd.x), 1e-20f));
;                     r0[2] = bflo(gn.y) * fast_rcp(fmaxf(bflo(gd.y), 1e-20f)); r0[3] = bfhi(gn.y) * fast_rcp(fmaxf(bfhi(gd.y), 1e-20f));
;                     r1[0] = bflo(gn.z) * fast_rcp(fmaxf(bflo(gd.z), 1e-20f)); r1[1] = bfhi(gn.z) * fast_rcp(fmaxf(bfhi(gd.z), 1e-20f));
;                     r1[2] = bflo(gn.w) * fast_rcp(fmaxf(bflo(gd.w), 1e-20f)); r1[3] = bfhi(gn.w) * fast_rcp(fmaxf(bfhi(gd.w), 1e-20f));
;                     acc[ai][bj][m][0] *= r0; acc[ai][bj][m][1] *= r1;
;                 }
;                 if (m == 1 || m == 3) __builtin_amdgcn_sched_barrier(0);
.LBB0_759:
	s_andn2_b64 vcc, exec, s[6:7]
	s_cbranch_vccnz .LBB0_761
	v_add_u32_e32 v34, s68, v173
	s_cmp_eq_u32 s12, 8
	v_mov_b64_e32 v[36:37], s[42:43]
	s_cselect_b32 s24, s20, 0x4000
	v_mad_i64_i32 v[36:37], vcc, v34, s90, v[36:37]
	s_mov_b32 s5, 0
	v_lshl_add_u64 v[36:37], v[36:37], 0, s[24:25]
	s_movk_i32 s4, 0x800
	v_lshl_add_u64 v[36:37], v[36:37], 0, v[164:165]
	v_lshl_add_u64 v[36:37], v[36:37], 0, s[4:5]
	s_mov_b32 s4, 0x60000
	global_load_dwordx4 v[134:137], v[36:37], off offset:-2048
	global_load_dwordx4 v[138:141], v[36:37], off offset:2048
	global_load_dwordx4 v[178:181], v[36:37], off offset:-1792
	global_load_dwordx4 v[182:185], v[36:37], off offset:2304
	v_lshl_add_u64 v[36:37], v[36:37], 0, s[4:5]
	global_load_dwordx4 v[186:189], v[36:37], off offset:-2048
	global_load_dwordx4 v[190:193], v[36:37], off offset:2048
	global_load_dwordx4 v[194:197], v[36:37], off offset:-1792
	global_load_dwordx4 v[198:201], v[36:37], off offset:2304
	v_lshl_add_u64 v[36:37], v[36:37], 0, s[4:5]
	global_load_dwordx4 v[202:205], v[36:37], off offset:-2048
	global_load_dwordx4 v[206:209], v[36:37], off offset:2048
	global_load_dwordx4 v[210:213], v[36:37], off offset:-1792
	global_load_dwordx4 v[214:217], v[36:37], off offset:2304
	v_lshl_add_u64 v[36:37], v[36:37], 0, s[4:5]
	global_load_dwordx4 v[218:221], v[36:37], off offset:-2048
	global_load_dwordx4 v[222:225], v[36:37], off offset:2048
	global_load_dwordx4 v[226:229], v[36:37], off offset:-1792
	global_load_dwordx4 v[230:233], v[36:37], off offset:2304
	v_lshl_add_u64 v[36:37], v[36:37], 0, s[4:5]
	s_mov_b32 s4, 0x180000
	v_lshl_add_u64 v[36:37], v[36:37], 0, s[4:5]
	s_mov_b32 s4, 0x60000
	s_waitcnt vmcnt(14)
	v_lshlrev_b32_e32 v248, 16, v138
	v_and_b32_e32 v249, 0xffff0000, v138
	v_lshlrev_b32_e32 v250, 16, v139
	v_and_b32_e32 v251, 0xffff0000, v139
	v_max_f32_e32 v248, v248, v248
	v_max_f32_e32 v249, v249, v249
	v_max_f32_e32 v250, v250, v250
	v_max_f32_e32 v251, v251, v251
	v_max_f32_e32 v248, 0x1e3ce508, v248
	v_max_f32_e32 v249, 0x1e3ce508, v249
	v_max_f32_e32 v250, 0x1e3ce508, v250
	v_max_f32_e32 v251, 0x1e3ce508, v251
	v_rcp_f32_e32 v248, v248
	v_rcp_f32_e32 v249, v249
	v_rcp_f32_e32 v250, v250
	v_rcp_f32_e32 v251, v251
	v_lshlrev_b32_e32 v252, 16, v134
	v_and_b32_e32 v253, 0xffff0000, v134
	v_lshlrev_b32_e32 v254, 16, v135
	v_and_b32_e32 v255, 0xffff0000, v135
	v_pk_mul_f32 v[248:249], v[248:249], v[252:253]
	v_pk_mul_f32 v[250:251], v[250:251], v[254:255]
	v_pk_mul_f32 v[130:131], v[130:131], v[248:249]
	v_pk_mul_f32 v[132:133], v[132:133], v[250:251]
	v_lshlrev_b32_e32 v248, 16, v140
	v_and_b32_e32 v249, 0xffff0000, v140
	v_lshlrev_b32_e32 v250, 16, v141
	v_and_b32_e32 v251, 0xffff0000, v141
	v_max_f32_e32 v248, v248, v248
	v_max_f32_e32 v249, v249, v249
	v_max_f32_e32 v250, v250, v250
	v_max_f32_e32 v251, v251, v251
	v_max_f32_e32 v248, 0x1e3ce508, v248
	v_max_f32_e32 v249, 0x1e3ce508, v249
	v_max_f32_e32 v250, 0x1e3ce508, v250
	v_max_f32_e32 v251, 0x1e3ce508, v251
	v_rcp_f32_e32 v248, v248
	v_rcp_f32_e32 v249, v249
	v_rcp_f32_e32 v250, v250
	v_rcp_f32_e32 v251, v251
	v_lshlrev_b32_e32 v252, 16, v136
	v_and_b32_e32 v253, 0xffff0000, v136
	v_lshlrev_b32_e32 v254, 16, v137
	v_and_b32_e32 v255, 0xffff0000, v137
	v_pk_mul_f32 v[248:249], v[248:249], v[252:253]
	v_pk_mul_f32 v[250:251], v[250:251], v[254:255]
	v_pk_mul_f32 v[126:127], v[126:127], v[248:249]
	v_pk_mul_f32 v[128:129], v[128:129], v[250:251]
	global_load_dwordx4 v[134:137], v[36:37], off offset:-2048
	global_load_dwordx4 v[138:141], v[36:37], off offset:2048
	s_waitcnt vmcnt(14)
	v_lshlrev_b32_e32 v248, 16, v182
	v_and_b32_e32 v249, 0xffff0000, v182
	v_lshlrev_b32_e32 v250, 16, v183
	v_and_b32_e32 v251, 0xffff0000, v183
	v_max_f32_e32 v248, v248, v248
	v_max_f32_e32 v249, v249, v249
	v_max_f32_e32 v250, v250, v250
	v_max_f32_e32 v251, v251, v251
	v_max_f32_e32 v248, 0x1e3ce508, v248
	v_max_f32_e32 v249, 0x1e3ce508, v249
	v_max_f32_e32 v250, 0x1e3ce508, v250
	v_max_f32_e32 v251, 0x1e3ce508, v251
	v_rcp_f32_e32 v248, v248
	v_rcp_f32_e32 v249, v249
	v_rcp_f32_e32 v250, v250
	v_rcp_f32_e32 v251, v251
	v_lshlrev_b32_e32 v252, 16, v178
	v_and_b32_e32 v253, 0xffff0000, v178
	v_lshlrev_b32_e32 v254, 16, v179
	v_and_b32_e32 v255, 0xffff0000, v179
	v_pk_mul_f32 v[248:249], v[248:249], v[252:253]
	v_pk_mul_f32 v[250:251], v[250:251], v[254:255]
	v_pk_mul_f32 v[122:123], v[122:123], v[248:249]
	v_pk_mul_f32 v[124:125], v[124:125], v[250:251]
	v_lshlrev_b32_e32 v248, 16, v184
	v_and_b32_e32 v249, 0xffff0000, v184
	v_lshlrev_b32_e32 v250, 16, v185
	v_and_b32_e32 v251, 0xffff0000, v185
	v_max_f32_e32 v248, v248, v248
	v_max_f32_e32 v249, v249, v249
	v_max_f32_e32 v250, v250, v250
	v_max_f32_e32 v251, v251, v251
	v_max_f32_e32 v248, 0x1e3ce508, v248
	v_max_f32_e32 v249, 0x1e3ce508, v249
	v_max_f32_e32 v250, 0x1e3ce508, v250
	v_max_f32_e32 v251, 0x1e3ce508, v251
	v_rcp_f32_e32 v248, v248
	v_rcp_f32_e32 v249, v249
	v_rcp_f32_e32 v250, v250
	v_rcp_f32_e32 v251, v251
	v_lshlrev_b32_e32 v252, 16, v180
	v_and_b32_e32 v253, 0xffff0000, v180
	v_lshlrev_b32_e32 v254, 16, v181
	v_and_b32_e32 v255, 0xffff0000, v181
	v_pk_mul_f32 v[248:249], v[248:249], v[252:253]
	v_pk_mul_f32 v[250:251], v[250:251], v[254:255]
	v_pk_mul_f32 v[118:119], v[118:119], v[248:249]
	v_pk_mul_f32 v[120:121], v[120:121], v[250:251]
	global_load_dwordx4 v[178:181], v[36:37], off offset:-1792
	global_load_dwordx4 v[182:185], v[36:37], off offset:2304
	v_lshl_add_u64 v[36:37], v[36:37], 0, s[4:5]
	s_waitcnt vmcnt(14)
; __device__ __forceinline__ float fast_rcp(float x) { return __builtin_amdgcn_rcpf(x); }
;     __device__ __forceinline__ void mid(f32x4 (&acc)[2][2][4][2], const Unit& u, int wr, int wc, int fr, int fq, int t) const {
;     ...
;                     const u32x4 gn = *(const u32x4*)(gp + bj * 128), gd = *(const u32x4*)(gp + bj * 128 + 2048);
;                     f32x4 r0, r1;
;                     r0[0] = bflo(gn.x) * fast_rcp(fmaxf(bflo(gd.x), 1e-20f)); r0[1] = bfhi(gn.x) * fast_rcp(fmaxf(bfhi(gd.x), 1e-20f));
;                     r0[2] = bflo(gn.y) * fast_rcp(fmaxf(bflo(gd.y), 1e-20f)); r0[3] = bfhi(gn.y) * fast_rcp(fmaxf(bfhi(gd.y), 1e-20f));
;                     r1[0] = bflo(gn.z) * fast_rcp(fmaxf(bflo(gd.z), 1e-20f)); r1[1] = bfhi(gn.z) * fast_rcp(fmaxf(bfhi(gd.z), 1e-20f));
;                     r1[2] = bflo(gn.w) * fast_rcp(fmaxf(bflo(gd.w), 1e-20f)); r1[3] = bfhi(gn.w) * fast_rcp(fmaxf(bfhi(gd.w), 1e-20f));
;                     acc[ai][bj][m][0] *= r0; acc[ai][bj][m][1] *= r1;
;                 }
;                 if (m == 1 || m == 3) __builtin_amdgcn_sched_barrier(0);
	v_lshlrev_b32_e32 v248, 16, v190
	v_and_b32_e32 v249, 0xffff0000, v190
	v_lshlrev_b32_e32 v250, 16, v191
	v_and_b32_e32 v251, 0xffff0000, v191
	v_max_f32_e32 v248, v248, v248
	v_max_f32_e32 v249, v249, v249
	v_max_f32_e32 v250, v250, v250
	v_max_f32_e32 v251, v251, v251
	v_max_f32_e32 v248, 0x1e3ce508, v248
	v_max_f32_e32 v249, 0x1e3ce508, v249
	v_max_f32_e32 v250, 0x1e3ce508, v250
	v_max_f32_e32 v251, 0x1e3ce508, v251
	v_rcp_f32_e32 v248, v248
	v_rcp_f32_e32 v249, v249
	v_rcp_f32_e32 v250, v250
	v_rcp_f32_e32 v251, v251
	v_lshlrev_b32_e32 v252, 16, v186
	v_and_b32_e32 v253, 0xffff0000, v186
	v_lshlrev_b32_e32 v254, 16, v187
	v_and_b32_e32 v255, 0xffff0000, v187
	v_pk_mul_f32 v[248:249], v[248:249], v[252:253]
	v_pk_mul_f32 v[250:251], v[250:251], v[254:255]
	v_pk_mul_f32 v[114:115], v[114:115], v[248:249]
	v_pk_mul_f32 v[116:117], v[116:117], v[250:251]
	v_lshlrev_b32_e32 v248, 16, v192
	v_and_b32_e32 v249, 0xffff0000, v192
	v_lshlrev_b32_e32 v250, 16, v193
	v_and_b32_e32 v251, 0xffff0000, v193
	v_max_f32_e32 v248, v248, v248
	v_max_f32_e32 v249, v249, v249
	v_max_f32_e32 v250, v250, v250
	v_max_f32_e32 v251, v251, v251
	v_max_f32_e32 v248, 0x1e3ce508, v248
	v_max_f32_e32 v249, 0x1e3ce508, v249
	v_max_f32_e32 v250, 0x1e3ce508, v250
	v_max_f32_e32 v251, 0x1e3ce508, v251
	v_rcp_f32_e32 v248, v248
	v_rcp_f32_e32 v249, v249
	v_rcp_f32_e32 v250, v250
	v_rcp_f32_e32 v251, v251
	v_lshlrev_b32_e32 v252, 16, v188
	v_and_b32_e32 v253, 0xffff0000, v188
	v_lshlrev_b32_e32 v254, 16, v189
	v_and_b32_e32 v255, 0xffff0000, v189
	v_pk_mul_f32 v[248:249], v[248:249], v[252:253]
	v_pk_mul_f32 v[250:251], v[250:251], v[254:255]
	v_pk_mul_f32 v[110:111], v[110:111], v[248:249]
	v_pk_mul_f32 v[112:113], v[112:113], v[250:251]
	global_load_dwordx4 v[186:189], v[36:37], off offset:-2048
	global_load_dwordx4 v[190:193], v[36:37], off offset:2048
	s_waitcnt vmcnt(14)
	v_lshlrev_b32_e32 v248, 16, v198
	v_and_b32_e32 v249, 0xffff0000, v198
	v_lshlrev_b32_e32 v250, 16, v199
	v_and_b32_e32 v251, 0xffff0000, v199
	v_max_f32_e32 v248, v248, v248
	v_max_f32_e32 v249, v249, v249
	v_max_f32_e32 v250, v250, v250
	v_max_f32_e32 v251, v251, v251
	v_max_f32_e32 v248, 0x1e3ce508, v248
	v_max_f32_e32 v249, 0x1e3ce508, v249
	v_max_f32_e32 v250, 0x1e3ce508, v250
	v_max_f32_e32 v251, 0x1e3ce508, v251
	v_rcp_f32_e32 v248, v248
	v_rcp_f32_e32 v249, v249
	v_rcp_f32_e32 v250, v250
	v_rcp_f32_e32 v251, v251
	v_lshlrev_b32_e32 v252, 16, v194
	v_and_b32_e32 v253, 0xffff0000, v194
	v_lshlrev_b32_e32 v254, 16, v195
	v_and_b32_e32 v255, 0xffff0000, v195
	v_pk_mul_f32 v[248:249], v[248:249], v[252:253]
	v_pk_mul_f32 v[250:251], v[250:251], v[254:255]
	v_pk_mul_f32 v[106:107], v[106:107], v[248:249]
	v_pk_mul_f32 v[108:109], v[108:109], v[250:251]
	v_lshlrev_b32_e32 v248, 16, v200
	v_and_b32_e32 v249, 0xffff0000, v200
	v_lshlrev_b32_e32 v250, 16, v201
	v_and_b32_e32 v251, 0xffff0000, v201
	v_max_f32_e32 v248, v248, v248
	v_max_f32_e32 v249, v249, v249
	v_max_f32_e32 v250, v250, v250
	v_max_f32_e32 v251, v251, v251
	v_max_f32_e32 v248, 0x1e3ce508, v248
	v_max_f32_e32 v249, 0x1e3ce508, v249
	v_max_f32_e32 v250, 0x1e3ce508, v250
	v_max_f32_e32 v251, 0x1e3ce508, v251
	v_rcp_f32_e32 v248, v248
	v_rcp_f32_e32 v249, v249
	v_rcp_f32_e32 v250, v250
	v_rcp_f32_e32 v251, v251
	v_lshlrev_b32_e32 v252, 16, v196
	v_and_b32_e32 v253, 0xffff0000, v196
	v_lshlrev_b32_e32 v254, 16, v197
	v_and_b32_e32 v255, 0xffff0000, v197
	v_pk_mul_f32 v[248:249], v[248:249], v[252:253]
	v_pk_mul_f32 v[250:251], v[250:251], v[254:255]
	v_pk_mul_f32 v[102:103], v[102:103], v[248:249]
	v_pk_mul_f32 v[104:105], v[104:105], v[250:251]
	global_load_dwordx4 v[194:197], v[36:37], off offset:-1792
	global_load_dwordx4 v[198:201], v[36:37], off offset:2304
	v_lshl_add_u64 v[36:37], v[36:37], 0, s[4:5]
	s_waitcnt vmcnt(14)
	v_lshlrev_b32_e32 v248, 16, v206
	v_and_b32_e32 v249, 0xffff0000, v206
	v_lshlrev_b32_e32 v250, 16, v207
	v_and_b32_e32 v251, 0xffff0000, v207
	v_max_f32_e32 v248, v248, v248
	v_max_f32_e32 v249, v249, v249
	v_max_f32_e32 v250, v250, v250
	v_max_f32_e32 v251, v251, v251
	v_max_f32_e32 v248, 0x1e3ce508, v248
	v_max_f32_e32 v249, 0x1e3ce508, v249
	v_max_f32_e32 v250, 0x1e3ce508, v250
	v_max_f32_e32 v251, 0x1e3ce508, v251
	v_rcp_f32_e32 v248, v248
	v_rcp_f32_e32 v249, v249
	v_rcp_f32_e32 v250, v250
	v_rcp_f32_e32 v251, v251
	v_lshlrev_b32_e32 v252, 16, v202
	v_and_b32_e32 v253, 0xffff0000, v202
	v_lshlrev_b32_e32 v254, 16, v203
	v_and_b32_e32 v255, 0xffff0000, v203
	v_pk_mul_f32 v[248:249], v[248:249], v[252:253]
	v_pk_mul_f32 v[250:251], v[250:251], v[254:255]
	v_pk_mul_f32 v[98:99], v[98:99], v[248:249]
	v_pk_mul_f32 v[100:101], v[100:101], v[250:251]
	v_lshlrev_b32_e32 v248, 16, v208
	v_and_b32_e32 v249, 0xffff0000, v208
	v_lshlrev_b32_e32 v250, 16, v209
	v_and_b32_e32 v251, 0xffff0000, v209
	v_max_f32_e32 v248, v248, v248
	v_max_f32_e32 v249, v249, v249
	v_max_f32_e32 v250, v250, v250
	v_max_f32_e32 v251, v251, v251
	v_max_f32_e32 v248, 0x1e3ce508, v248
	v_max_f32_e32 v249, 0x1e3ce508, v249
	v_max_f32_e32 v250, 0x1e3ce508, v250
	v_max_f32_e32 v251, 0x1e3ce508, v251
	v_rcp_f32_e32 v248, v248
	v_rcp_f32_e32 v249, v249
	v_rcp_f32_e32 v250, v250
	v_rcp_f32_e32 v251, v251
	v_lshlrev_b32_e32 v252, 16, v204
	v_and_b32_e32 v253, 0xffff0000, v204
	v_lshlrev_b32_e32 v254, 16, v205
	v_and_b32_e32 v255, 0xffff0000, v205
	v_pk_mul_f32 v[248:249], v[248:249], v[252:253]
	v_pk_mul_f32 v[250:251], v[250:251], v[254:255]
	v_pk_mul_f32 v[94:95], v[94:95], v[248:249]
	v_pk_mul_f32 v[96:97], v[96:97], v[250:251]
	global_load_dwordx4 v[202:205], v[36:37], off offset:-2048
	global_load_dwordx4 v[206:209], v[36:37], off offset:2048
	s_waitcnt vmcnt(14)
; __device__ __forceinline__ float fast_rcp(float x) { return __builtin_amdgcn_rcpf(x); }
;     __device__ __forceinline__ void mid(f32x4 (&acc)[2][2][4][2], const Unit& u, int wr, int wc, int fr, int fq, int t) const {
;     ...
;                     const u32x4 gn = *(const u32x4*)(gp + bj * 128), gd = *(const u32x4*)(gp + bj * 128 + 2048);
;                     f32x4 r0, r1;
;                     r0[0] = bflo(gn.x) * fast_rcp(fmaxf(bflo(gd.x), 1e-20f)); r0[1] = bfhi(gn.x) * fast_rcp(fmaxf(bfhi(gd.x), 1e-20f));
;                     r0[2] = bflo(gn.y) * fast_rcp(fmaxf(bflo(gd.y), 1e-20f)); r0[3] = bfhi(gn.y) * fast_rcp(fmaxf(bfhi(gd.y), 1e-20f));
;                     r1[0] = bflo(gn.z) * fast_rcp(fmaxf(bflo(gd.z), 1e-20f)); r1[1] = bfhi(gn.z) * fast_rcp(fmaxf(bfhi(gd.z), 1e-20f));
;                     r1[2] = bflo(gn.w) * fast_rcp(fmaxf(bflo(gd.w), 1e-20f)); r1[3] = bfhi(gn.w) * fast_rcp(fmaxf(bfhi(gd.w), 1e-20f));
;                     acc[ai][bj][m][0] *= r0; acc[ai][bj][m][1] *= r1;
;                 }
;                 if (m == 1 || m == 3) __builtin_amdgcn_sched_barrier(0);
	v_lshlrev_b32_e32 v248, 16, v214
	v_and_b32_e32 v249, 0xffff0000, v214
	v_lshlrev_b32_e32 v250, 16, v215
	v_and_b32_e32 v251, 0xffff0000, v215
	v_max_f32_e32 v248, v248, v248
	v_max_f32_e32 v249, v249, v249
	v_max_f32_e32 v250, v250, v250
	v_max_f32_e32 v251, v251, v251
	v_max_f32_e32 v248, 0x1e3ce508, v248
	v_max_f32_e32 v249, 0x1e3ce508, v249
	v_max_f32_e32 v250, 0x1e3ce508, v250
	v_max_f32_e32 v251, 0x1e3ce508, v251
	v_rcp_f32_e32 v248, v248
	v_rcp_f32_e32 v249, v249
	v_rcp_f32_e32 v250, v250
	v_rcp_f32_e32 v251, v251
	v_lshlrev_b32_e32 v252, 16, v210
	v_and_b32_e32 v253, 0xffff0000, v210
	v_lshlrev_b32_e32 v254, 16, v211
	v_and_b32_e32 v255, 0xffff0000, v211
	v_pk_mul_f32 v[248:249], v[248:249], v[252:253]
	v_pk_mul_f32 v[250:251], v[250:251], v[254:255]
	v_pk_mul_f32 v[90:91], v[90:91], v[248:249]
	v_pk_mul_f32 v[92:93], v[92:93], v[250:251]
	v_lshlrev_b32_e32 v248, 16, v216
	v_and_b32_e32 v249, 0xffff0000, v216
	v_lshlrev_b32_e32 v250, 16, v217
	v_and_b32_e32 v251, 0xffff0000, v217
	v_max_f32_e32 v248, v248, v248
	v_max_f32_e32 v249, v249, v249
	v_max_f32_e32 v250, v250, v250
	v_max_f32_e32 v251, v251, v251
	v_max_f32_e32 v248, 0x1e3ce508, v248
	v_max_f32_e32 v249, 0x1e3ce508, v249
	v_max_f32_e32 v250, 0x1e3ce508, v250
	v_max_f32_e32 v251, 0x1e3ce508, v251
	v_rcp_f32_e32 v248, v248
	v_rcp_f32_e32 v249, v249
	v_rcp_f32_e32 v250, v250
	v_rcp_f32_e32 v251, v251
	v_lshlrev_b32_e32 v252, 16, v212
	v_and_b32_e32 v253, 0xffff0000, v212
	v_lshlrev_b32_e32 v254, 16, v213
	v_and_b32_e32 v255, 0xffff0000, v213
	v_pk_mul_f32 v[248:249], v[248:249], v[252:253]
	v_pk_mul_f32 v[250:251], v[250:251], v[254:255]
	v_pk_mul_f32 v[86:87], v[86:87], v[248:249]
	v_pk_mul_f32 v[88:89], v[88:89], v[250:251]
	global_load_dwordx4 v[210:213], v[36:37], off offset:-1792
	global_load_dwordx4 v[214:217], v[36:37], off offset:2304
	v_lshl_add_u64 v[36:37], v[36:37], 0, s[4:5]
	s_waitcnt vmcnt(14)
	v_lshlrev_b32_e32 v248, 16, v222
	v_and_b32_e32 v249, 0xffff0000, v222
	v_lshlrev_b32_e32 v250, 16, v223
	v_and_b32_e32 v251, 0xffff0000, v223
	v_max_f32_e32 v248, v248, v248
	v_max_f32_e32 v249, v249, v249
	v_max_f32_e32 v250, v250, v250
	v_max_f32_e32 v251, v251, v251
	v_max_f32_e32 v248, 0x1e3ce508, v248
	v_max_f32_e32 v249, 0x1e3ce508, v249
	v_max_f32_e32 v250, 0x1e3ce508, v250
	v_max_f32_e32 v251, 0x1e3ce508, v251
	v_rcp_f32_e32 v248, v248
	v_rcp_f32_e32 v249, v249
	v_rcp_f32_e32 v250, v250
	v_rcp_f32_e32 v251, v251
	v_lshlrev_b32_e32 v252, 16, v218
	v_and_b32_e32 v253, 0xffff0000, v218
	v_lshlrev_b32_e32 v254, 16, v219
	v_and_b32_e32 v255, 0xffff0000, v219
	v_pk_mul_f32 v[248:249], v[248:249], v[252:253]
	v_pk_mul_f32 v[250:251], v[250:251], v[254:255]
	v_pk_mul_f32 v[82:83], v[82:83], v[248:249]
	v_pk_mul_f32 v[84:85], v[84:85], v[250:251]
	v_lshlrev_b32_e32 v248, 16, v224
	v_and_b32_e32 v249, 0xffff0000, v224
	v_lshlrev_b32_e32 v250, 16, v225
	v_and_b32_e32 v251, 0xffff0000, v225
	v_max_f32_e32 v248, v248, v248
	v_max_f32_e32 v249, v249, v249
	v_max_f32_e32 v250, v250, v250
	v_max_f32_e32 v251, v251, v251
	v_max_f32_e32 v248, 0x1e3ce508, v248
	v_max_f32_e32 v249, 0x1e3ce508, v249
	v_max_f32_e32 v250, 0x1e3ce508, v250
	v_max_f32_e32 v251, 0x1e3ce508, v251
	v_rcp_f32_e32 v248, v248
	v_rcp_f32_e32 v249, v249
	v_rcp_f32_e32 v250, v250
	v_rcp_f32_e32 v251, v251
	v_lshlrev_b32_e32 v252, 16, v220
	v_and_b32_e32 v253, 0xffff0000, v220
	v_lshlrev_b32_e32 v254, 16, v221
	v_and_b32_e32 v255, 0xffff0000, v221
	v_pk_mul_f32 v[248:249], v[248:249], v[252:253]
	v_pk_mul_f32 v[250:251], v[250:251], v[254:255]
	v_pk_mul_f32 v[78:79], v[78:79], v[248:249]
	v_pk_mul_f32 v[80:81], v[80:81], v[250:251]
	global_load_dwordx4 v[218:221], v[36:37], off offset:-2048
	global_load_dwordx4 v[222:225], v[36:37], off offset:2048
	s_waitcnt vmcnt(14)
	v_lshlrev_b32_e32 v248, 16, v230
	v_and_b32_e32 v249, 0xffff0000, v230
	v_lshlrev_b32_e32 v250, 16, v231
	v_and_b32_e32 v251, 0xffff0000, v231
	v_max_f32_e32 v248, v248, v248
	v_max_f32_e32 v249, v249, v249
	v_max_f32_e32 v250, v250, v250
	v_max_f32_e32 v251, v251, v251
	v_max_f32_e32 v248, 0x1e3ce508, v248
	v_max_f32_e32 v249, 0x1e3ce508, v249
	v_max_f32_e32 v250, 0x1e3ce508, v250
	v_max_f32_e32 v251, 0x1e3ce508, v251
	v_rcp_f32_e32 v248, v248
	v_rcp_f32_e32 v249, v249
	v_rcp_f32_e32 v250, v250
	v_rcp_f32_e32 v251, v251
	v_lshlrev_b32_e32 v252, 16, v226
	v_and_b32_e32 v253, 0xffff0000, v226
	v_lshlrev_b32_e32 v254, 16, v227
	v_and_b32_e32 v255, 0xffff0000, v227
	v_pk_mul_f32 v[248:249], v[248:249], v[252:253]
	v_pk_mul_f32 v[250:251], v[250:251], v[254:255]
	v_pk_mul_f32 v[74:75], v[74:75], v[248:249]
	v_pk_mul_f32 v[76:77], v[76:77], v[250:251]
	v_lshlrev_b32_e32 v248, 16, v232
	v_and_b32_e32 v249, 0xffff0000, v232
	v_lshlrev_b32_e32 v250, 16, v233
	v_and_b32_e32 v251, 0xffff0000, v233
	v_max_f32_e32 v248, v248, v248
	v_max_f32_e32 v249, v249, v249
	v_max_f32_e32 v250, v250, v250
	v_max_f32_e32 v251, v251, v251
	v_max_f32_e32 v248, 0x1e3ce508, v248
	v_max_f32_e32 v249, 0x1e3ce508, v249
	v_max_f32_e32 v250, 0x1e3ce508, v250
	v_max_f32_e32 v251, 0x1e3ce508, v251
	v_rcp_f32_e32 v248, v248
	v_rcp_f32_e32 v249, v249
	v_rcp_f32_e32 v250, v250
	v_rcp_f32_e32 v251, v251
	v_lshlrev_b32_e32 v252, 16, v228
	v_and_b32_e32 v253, 0xffff0000, v228
	v_lshlrev_b32_e32 v254, 16, v229
	v_and_b32_e32 v255, 0xffff0000, v229
	v_pk_mul_f32 v[248:249], v[248:249], v[252:253]
	v_pk_mul_f32 v[250:251], v[250:251], v[254:255]
	v_pk_mul_f32 v[70:71], v[70:71], v[248:249]
	v_pk_mul_f32 v[72:73], v[72:73], v[250:251]
	global_load_dwordx4 v[226:229], v[36:37], off offset:-1792
	global_load_dwordx4 v[230:233], v[36:37], off offset:2304
	v_lshl_add_u64 v[36:37], v[36:37], 0, s[4:5]
	s_waitcnt vmcnt(14)
; __device__ __forceinline__ float fast_rcp(float x) { return __builtin_amdgcn_rcpf(x); }
;     __device__ __forceinline__ void mid(f32x4 (&acc)[2][2][4][2], const Unit& u, int wr, int wc, int fr, int fq, int t) const {
;     ...
;                     const u32x4 gn = *(const u32x4*)(gp + bj * 128), gd = *(const u32x4*)(gp + bj * 128 + 2048);
;                     f32x4 r0, r1;
;                     r0[0] = bflo(gn.x) * fast_rcp(fmaxf(bflo(gd.x), 1e-20f)); r0[1] = bfhi(gn.x) * fast_rcp(fmaxf(bfhi(gd.x), 1e-20f));
;                     r0[2] = bflo(gn.y) * fast_rcp(fmaxf(bflo(gd.y), 1e-20f)); r0[3] = bfhi(gn.y) * fast_rcp(fmaxf(bfhi(gd.y), 1e-20f));
;                     r1[0] = bflo(gn.z) * fast_rcp(fmaxf(bflo(gd.z), 1e-20f)); r1[1] = bfhi(gn.z) * fast_rcp(fmaxf(bfhi(gd.z), 1e-20f));
;                     r1[2] = bflo(gn.w) * fast_rcp(fmaxf(bflo(gd.w), 1e-20f)); r1[3] = bfhi(gn.w) * fast_rcp(fmaxf(bfhi(gd.w), 1e-20f));
;                     acc[ai][bj][m][0] *= r0; acc[ai][bj][m][1] *= r1;
;                 }
;                 if (m == 1 || m == 3) __builtin_amdgcn_sched_barrier(0);
	v_lshlrev_b32_e32 v248, 16, v138
	v_and_b32_e32 v249, 0xffff0000, v138
	v_lshlrev_b32_e32 v250, 16, v139
	v_and_b32_e32 v251, 0xffff0000, v139
	v_max_f32_e32 v248, v248, v248
	v_max_f32_e32 v249, v249, v249
	v_max_f32_e32 v250, v250, v250
	v_max_f32_e32 v251, v251, v251
	v_max_f32_e32 v248, 0x1e3ce508, v248
	v_max_f32_e32 v249, 0x1e3ce508, v249
	v_max_f32_e32 v250, 0x1e3ce508, v250
	v_max_f32_e32 v251, 0x1e3ce508, v251
	v_rcp_f32_e32 v248, v248
	v_rcp_f32_e32 v249, v249
	v_rcp_f32_e32 v250, v250
	v_rcp_f32_e32 v251, v251
	v_lshlrev_b32_e32 v252, 16, v134
	v_and_b32_e32 v253, 0xffff0000, v134
	v_lshlrev_b32_e32 v254, 16, v135
	v_and_b32_e32 v255, 0xffff0000, v135
	v_pk_mul_f32 v[248:249], v[248:249], v[252:253]
	v_pk_mul_f32 v[250:251], v[250:251], v[254:255]
	v_pk_mul_f32 v[66:67], v[66:67], v[248:249]
	v_pk_mul_f32 v[68:69], v[68:69], v[250:251]
	v_lshlrev_b32_e32 v248, 16, v140
	v_and_b32_e32 v249, 0xffff0000, v140
	v_lshlrev_b32_e32 v250, 16, v141
	v_and_b32_e32 v251, 0xffff0000, v141
	v_max_f32_e32 v248, v248, v248
	v_max_f32_e32 v249, v249, v249
	v_max_f32_e32 v250, v250, v250
	v_max_f32_e32 v251, v251, v251
	v_max_f32_e32 v248, 0x1e3ce508, v248
	v_max_f32_e32 v249, 0x1e3ce508, v249
	v_max_f32_e32 v250, 0x1e3ce508, v250
	v_max_f32_e32 v251, 0x1e3ce508, v251
	v_rcp_f32_e32 v248, v248
	v_rcp_f32_e32 v249, v249
	v_rcp_f32_e32 v250, v250
	v_rcp_f32_e32 v251, v251
	v_lshlrev_b32_e32 v252, 16, v136
	v_and_b32_e32 v253, 0xffff0000, v136
	v_lshlrev_b32_e32 v254, 16, v137
	v_and_b32_e32 v255, 0xffff0000, v137
	v_pk_mul_f32 v[248:249], v[248:249], v[252:253]
	v_pk_mul_f32 v[250:251], v[250:251], v[254:255]
	v_pk_mul_f32 v[62:63], v[62:63], v[248:249]
	v_pk_mul_f32 v[64:65], v[64:65], v[250:251]
	s_waitcnt vmcnt(12)
	v_lshlrev_b32_e32 v248, 16, v182
	v_and_b32_e32 v249, 0xffff0000, v182
	v_lshlrev_b32_e32 v250, 16, v183
	v_and_b32_e32 v251, 0xffff0000, v183
	v_max_f32_e32 v248, v248, v248
	v_max_f32_e32 v249, v249, v249
	v_max_f32_e32 v250, v250, v250
	v_max_f32_e32 v251, v251, v251
	v_max_f32_e32 v248, 0x1e3ce508, v248
	v_max_f32_e32 v249, 0x1e3ce508, v249
	v_max_f32_e32 v250, 0x1e3ce508, v250
	v_max_f32_e32 v251, 0x1e3ce508, v251
	v_rcp_f32_e32 v248, v248
	v_rcp_f32_e32 v249, v249
	v_rcp_f32_e32 v250, v250
	v_rcp_f32_e32 v251, v251
	v_lshlrev_b32_e32 v252, 16, v178
	v_and_b32_e32 v253, 0xffff0000, v178
	v_lshlrev_b32_e32 v254, 16, v179
	v_and_b32_e32 v255, 0xffff0000, v179
	v_pk_mul_f32 v[248:249], v[248:249], v[252:253]
	v_pk_mul_f32 v[250:251], v[250:251], v[254:255]
	v_pk_mul_f32 v[58:59], v[58:59], v[248:249]
	v_pk_mul_f32 v[60:61], v[60:61], v[250:251]
	v_lshlrev_b32_e32 v248, 16, v184
	v_and_b32_e32 v249, 0xffff0000, v184
	v_lshlrev_b32_e32 v250, 16, v185
	v_and_b32_e32 v251, 0xffff0000, v185
	v_max_f32_e32 v248, v248, v248
	v_max_f32_e32 v249, v249, v249
	v_max_f32_e32 v250, v250, v250
	v_max_f32_e32 v251, v251, v251
	v_max_f32_e32 v248, 0x1e3ce508, v248
	v_max_f32_e32 v249, 0x1e3ce508, v249
	v_max_f32_e32 v250, 0x1e3ce508, v250
	v_max_f32_e32 v251, 0x1e3ce508, v251
	v_rcp_f32_e32 v248, v248
	v_rcp_f32_e32 v249, v249
	v_rcp_f32_e32 v250, v250
	v_rcp_f32_e32 v251, v251
	v_lshlrev_b32_e32 v252, 16, v180
	v_and_b32_e32 v253, 0xffff0000, v180
	v_lshlrev_b32_e32 v254, 16, v181
	v_and_b32_e32 v255, 0xffff0000, v181
	v_pk_mul_f32 v[248:249], v[248:249], v[252:253]
	v_pk_mul_f32 v[250:251], v[250:251], v[254:255]
	v_pk_mul_f32 v[54:55], v[54:55], v[248:249]
	v_pk_mul_f32 v[56:57], v[56:57], v[250:251]
	s_waitcnt vmcnt(10)
	v_lshlrev_b32_e32 v248, 16, v190
	v_and_b32_e32 v249, 0xffff0000, v190
	v_lshlrev_b32_e32 v250, 16, v191
	v_and_b32_e32 v251, 0xffff0000, v191
	v_max_f32_e32 v248, v248, v248
	v_max_f32_e32 v249, v249, v249
	v_max_f32_e32 v250, v250, v250
	v_max_f32_e32 v251, v251, v251
	v_max_f32_e32 v248, 0x1e3ce508, v248
	v_max_f32_e32 v249, 0x1e3ce508, v249
	v_max_f32_e32 v250, 0x1e3ce508, v250
	v_max_f32_e32 v251, 0x1e3ce508, v251
	v_rcp_f32_e32 v248, v248
	v_rcp_f32_e32 v249, v249
	v_rcp_f32_e32 v250, v250
	v_rcp_f32_e32 v251, v251
	v_lshlrev_b32_e32 v252, 16, v186
	v_and_b32_e32 v253, 0xffff0000, v186
	v_lshlrev_b32_e32 v254, 16, v187
	v_and_b32_e32 v255, 0xffff0000, v187
	v_pk_mul_f32 v[248:249], v[248:249], v[252:253]
	v_pk_mul_f32 v[250:251], v[250:251], v[254:255]
	v_pk_mul_f32 v[50:51], v[50:51], v[248:249]
	v_pk_mul_f32 v[52:53], v[52:53], v[250:251]
	v_lshlrev_b32_e32 v248, 16, v192
	v_and_b32_e32 v249, 0xffff0000, v192
	v_lshlrev_b32_e32 v250, 16, v193
	v_and_b32_e32 v251, 0xffff0000, v193
	v_max_f32_e32 v248, v248, v248
	v_max_f32_e32 v249, v249, v249
	v_max_f32_e32 v250, v250, v250
	v_max_f32_e32 v251, v251, v251
	v_max_f32_e32 v248, 0x1e3ce508, v248
	v_max_f32_e32 v249, 0x1e3ce508, v249
	v_max_f32_e32 v250, 0x1e3ce508, v250
	v_max_f32_e32 v251, 0x1e3ce508, v251
	v_rcp_f32_e32 v248, v248
	v_rcp_f32_e32 v249, v249
	v_rcp_f32_e32 v250, v250
	v_rcp_f32_e32 v251, v251
	v_lshlrev_b32_e32 v252, 16, v188
	v_and_b32_e32 v253, 0xffff0000, v188
	v_lshlrev_b32_e32 v254, 16, v189
	v_and_b32_e32 v255, 0xffff0000, v189
	v_pk_mul_f32 v[248:249], v[248:249], v[252:253]
	v_pk_mul_f32 v[250:251], v[250:251], v[254:255]
	v_pk_mul_f32 v[46:47], v[46:47], v[248:249]
	v_pk_mul_f32 v[48:49], v[48:49], v[250:251]
	s_waitcnt vmcnt(8)
; __device__ __forceinline__ float fast_rcp(float x) { return __builtin_amdgcn_rcpf(x); }
;     __device__ __forceinline__ void mid(f32x4 (&acc)[2][2][4][2], const Unit& u, int wr, int wc, int fr, int fq, int t) const {
;     ...
;                     const u32x4 gn = *(const u32x4*)(gp + bj * 128), gd = *(const u32x4*)(gp + bj * 128 + 2048);
;                     f32x4 r0, r1;
;                     r0[0] = bflo(gn.x) * fast_rcp(fmaxf(bflo(gd.x), 1e-20f)); r0[1] = bfhi(gn.x) * fast_rcp(fmaxf(bfhi(gd.x), 1e-20f));
;                     r0[2] = bflo(gn.y) * fast_rcp(fmaxf(bflo(gd.y), 1e-20f)); r0[3] = bfhi(gn.y) * fast_rcp(fmaxf(bfhi(gd.y), 1e-20f));
;                     r1[0] = bflo(gn.z) * fast_rcp(fmaxf(bflo(gd.z), 1e-20f)); r1[1] = bfhi(gn.z) * fast_rcp(fmaxf(bfhi(gd.z), 1e-20f));
;                     r1[2] = bflo(gn.w) * fast_rcp(fmaxf(bflo(gd.w), 1e-20f)); r1[3] = bfhi(gn.w) * fast_rcp(fmaxf(bfhi(gd.w), 1e-20f));
;                     acc[ai][bj][m][0] *= r0; acc[ai][bj][m][1] *= r1;
;                 }
;                 if (m == 1 || m == 3) __builtin_amdgcn_sched_barrier(0);
	v_lshlrev_b32_e32 v248, 16, v198
	v_and_b32_e32 v249, 0xffff0000, v198
	v_lshlrev_b32_e32 v250, 16, v199
	v_and_b32_e32 v251, 0xffff0000, v199
	v_max_f32_e32 v248, v248, v248
	v_max_f32_e32 v249, v249, v249
	v_max_f32_e32 v250, v250, v250
	v_max_f32_e32 v251, v251, v251
	v_max_f32_e32 v248, 0x1e3ce508, v248
	v_max_f32_e32 v249, 0x1e3ce508, v249
	v_max_f32_e32 v250, 0x1e3ce508, v250
	v_max_f32_e32 v251, 0x1e3ce508, v251
	v_rcp_f32_e32 v248, v248
	v_rcp_f32_e32 v249, v249
	v_rcp_f32_e32 v250, v250
	v_rcp_f32_e32 v251, v251
	v_lshlrev_b32_e32 v252, 16, v194
	v_and_b32_e32 v253, 0xffff0000, v194
	v_lshlrev_b32_e32 v254, 16, v195
	v_and_b32_e32 v255, 0xffff0000, v195
	v_pk_mul_f32 v[248:249], v[248:249], v[252:253]
	v_pk_mul_f32 v[250:251], v[250:251], v[254:255]
	v_pk_mul_f32 v[42:43], v[42:43], v[248:249]
	v_pk_mul_f32 v[44:45], v[44:45], v[250:251]
	v_lshlrev_b32_e32 v248, 16, v200
	v_and_b32_e32 v249, 0xffff0000, v200
	v_lshlrev_b32_e32 v250, 16, v201
	v_and_b32_e32 v251, 0xffff0000, v201
	v_max_f32_e32 v248, v248, v248
	v_max_f32_e32 v249, v249, v249
	v_max_f32_e32 v250, v250, v250
	v_max_f32_e32 v251, v251, v251
	v_max_f32_e32 v248, 0x1e3ce508, v248
	v_max_f32_e32 v249, 0x1e3ce508, v249
	v_max_f32_e32 v250, 0x1e3ce508, v250
	v_max_f32_e32 v251, 0x1e3ce508, v251
	v_rcp_f32_e32 v248, v248
	v_rcp_f32_e32 v249, v249
	v_rcp_f32_e32 v250, v250
	v_rcp_f32_e32 v251, v251
	v_lshlrev_b32_e32 v252, 16, v196
	v_and_b32_e32 v253, 0xffff0000, v196
	v_lshlrev_b32_e32 v254, 16, v197
	v_and_b32_e32 v255, 0xffff0000, v197
	v_pk_mul_f32 v[248:249], v[248:249], v[252:253]
	v_pk_mul_f32 v[250:251], v[250:251], v[254:255]
	v_pk_mul_f32 v[38:39], v[38:39], v[248:249]
	v_pk_mul_f32 v[40:41], v[40:41], v[250:251]
	s_waitcnt vmcnt(6)
	v_lshlrev_b32_e32 v248, 16, v206
	v_and_b32_e32 v249, 0xffff0000, v206
	v_lshlrev_b32_e32 v250, 16, v207
	v_and_b32_e32 v251, 0xffff0000, v207
	v_max_f32_e32 v248, v248, v248
	v_max_f32_e32 v249, v249, v249
	v_max_f32_e32 v250, v250, v250
	v_max_f32_e32 v251, v251, v251
	v_max_f32_e32 v248, 0x1e3ce508, v248
	v_max_f32_e32 v249, 0x1e3ce508, v249
	v_max_f32_e32 v250, 0x1e3ce508, v250
	v_max_f32_e32 v251, 0x1e3ce508, v251
	v_rcp_f32_e32 v248, v248
	v_rcp_f32_e32 v249, v249
	v_rcp_f32_e32 v250, v250
	v_rcp_f32_e32 v251, v251
	v_lshlrev_b32_e32 v252, 16, v202
	v_and_b32_e32 v253, 0xffff0000, v202
	v_lshlrev_b32_e32 v254, 16, v203
	v_and_b32_e32 v255, 0xffff0000, v203
	v_pk_mul_f32 v[248:249], v[248:249], v[252:253]
	v_pk_mul_f32 v[250:251], v[250:251], v[254:255]
	v_pk_mul_f32 v[28:29], v[28:29], v[248:249]
	v_pk_mul_f32 v[30:31], v[30:31], v[250:251]
	v_lshlrev_b32_e32 v248, 16, v208
	v_and_b32_e32 v249, 0xffff0000, v208
	v_lshlrev_b32_e32 v250, 16, v209
	v_and_b32_e32 v251, 0xffff0000, v209
	v_max_f32_e32 v248, v248, v248
	v_max_f32_e32 v249, v249, v249
	v_max_f32_e32 v250, v250, v250
	v_max_f32_e32 v251, v251, v251
	v_max_f32_e32 v248, 0x1e3ce508, v248
	v_max_f32_e32 v249, 0x1e3ce508, v249
	v_max_f32_e32 v250, 0x1e3ce508, v250
	v_max_f32_e32 v251, 0x1e3ce508, v251
	v_rcp_f32_e32 v248, v248
	v_rcp_f32_e32 v249, v249
	v_rcp_f32_e32 v250, v250
	v_rcp_f32_e32 v251, v251
	v_lshlrev_b32_e32 v252, 16, v204
	v_and_b32_e32 v253, 0xffff0000, v204
	v_lshlrev_b32_e32 v254, 16, v205
	v_and_b32_e32 v255, 0xffff0000, v205
	v_pk_mul_f32 v[248:249], v[248:249], v[252:253]
	v_pk_mul_f32 v[250:251], v[250:251], v[254:255]
	v_pk_mul_f32 v[24:25], v[24:25], v[248:249]
	v_pk_mul_f32 v[26:27], v[26:27], v[250:251]
	s_waitcnt vmcnt(4)
; __device__ __forceinline__ float fast_rcp(float x) { return __builtin_amdgcn_rcpf(x); }
;     __device__ __forceinline__ void mid(f32x4 (&acc)[2][2][4][2], const Unit& u, int wr, int wc, int fr, int fq, int t) const {
;     ...
;                     const u32x4 gn = *(const u32x4*)(gp + bj * 128), gd = *(const u32x4*)(gp + bj * 128 + 2048);
;                     f32x4 r0, r1;
;                     r0[0] = bflo(gn.x) * fast_rcp(fmaxf(bflo(gd.x), 1e-20f)); r0[1] = bfhi(gn.x) * fast_rcp(fmaxf(bfhi(gd.x), 1e-20f));
;                     r0[2] = bflo(gn.y) * fast_rcp(fmaxf(bflo(gd.y), 1e-20f)); r0[3] = bfhi(gn.y) * fast_rcp(fmaxf(bfhi(gd.y), 1e-20f));
;                     r1[0] = bflo(gn.z) * fast_rcp(fmaxf(bflo(gd.z), 1e-20f)); r1[1] = bfhi(gn.z) * fast_rcp(fmaxf(bfhi(gd.z), 1e-20f));
;                     r1[2] = bflo(gn.w) * fast_rcp(fmaxf(bflo(gd.w), 1e-20f)); r1[3] = bfhi(gn.w) * fast_rcp(fmaxf(bfhi(gd.w), 1e-20f));
;                     acc[ai][bj][m][0] *= r0; acc[ai][bj][m][1] *= r1;
	v_lshlrev_b32_e32 v248, 16, v214
	v_and_b32_e32 v249, 0xffff0000, v214
	v_lshlrev_b32_e32 v250, 16, v215
	v_and_b32_e32 v251, 0xffff0000, v215
	v_max_f32_e32 v248, v248, v248
	v_max_f32_e32 v249, v249, v249
	v_max_f32_e32 v250, v250, v250
	v_max_f32_e32 v251, v251, v251
	v_max_f32_e32 v248, 0x1e3ce508, v248
	v_max_f32_e32 v249, 0x1e3ce508, v249
	v_max_f32_e32 v250, 0x1e3ce508, v250
	v_max_f32_e32 v251, 0x1e3ce508, v251
	v_rcp_f32_e32 v248, v248
	v_rcp_f32_e32 v249, v249
	v_rcp_f32_e32 v250, v250
	v_rcp_f32_e32 v251, v251
	v_lshlrev_b32_e32 v252, 16, v210
	v_and_b32_e32 v253, 0xffff0000, v210
	v_lshlrev_b32_e32 v254, 16, v211
	v_and_b32_e32 v255, 0xffff0000, v211
	v_pk_mul_f32 v[248:249], v[248:249], v[252:253]
	v_pk_mul_f32 v[250:251], v[250:251], v[254:255]
	v_pk_mul_f32 v[20:21], v[20:21], v[248:249]
	v_pk_mul_f32 v[22:23], v[22:23], v[250:251]
	v_lshlrev_b32_e32 v248, 16, v216
	v_and_b32_e32 v249, 0xffff0000, v216
	v_lshlrev_b32_e32 v250, 16, v217
	v_and_b32_e32 v251, 0xffff0000, v217
	v_max_f32_e32 v248, v248, v248
	v_max_f32_e32 v249, v249, v249
	v_max_f32_e32 v250, v250, v250
	v_max_f32_e32 v251, v251, v251
	v_max_f32_e32 v248, 0x1e3ce508, v248
	v_max_f32_e32 v249, 0x1e3ce508, v249
	v_max_f32_e32 v250, 0x1e3ce508, v250
	v_max_f32_e32 v251, 0x1e3ce508, v251
	v_rcp_f32_e32 v248, v248
	v_rcp_f32_e32 v249, v249
	v_rcp_f32_e32 v250, v250
	v_rcp_f32_e32 v251, v251
	v_lshlrev_b32_e32 v252, 16, v212
	v_and_b32_e32 v253, 0xffff0000, v212
	v_lshlrev_b32_e32 v254, 16, v213
	v_and_b32_e32 v255, 0xffff0000, v213
	v_pk_mul_f32 v[248:249], v[248:249], v[252:253]
	v_pk_mul_f32 v[250:251], v[250:251], v[254:255]
	v_pk_mul_f32 v[16:17], v[16:17], v[248:249]
	v_pk_mul_f32 v[18:19], v[18:19], v[250:251]
	s_waitcnt vmcnt(2)
	v_lshlrev_b32_e32 v248, 16, v222
	v_and_b32_e32 v249, 0xffff0000, v222
	v_lshlrev_b32_e32 v250, 16, v223
	v_and_b32_e32 v251, 0xffff0000, v223
	v_max_f32_e32 v248, v248, v248
	v_max_f32_e32 v249, v249, v249
	v_max_f32_e32 v250, v250, v250
	v_max_f32_e32 v251, v251, v251
	v_max_f32_e32 v248, 0x1e3ce508, v248
	v_max_f32_e32 v249, 0x1e3ce508, v249
	v_max_f32_e32 v250, 0x1e3ce508, v250
	v_max_f32_e32 v251, 0x1e3ce508, v251
	v_rcp_f32_e32 v248, v248
	v_rcp_f32_e32 v249, v249
	v_rcp_f32_e32 v250, v250
	v_rcp_f32_e32 v251, v251
	v_lshlrev_b32_e32 v252, 16, v218
	v_and_b32_e32 v253, 0xffff0000, v218
	v_lshlrev_b32_e32 v254, 16, v219
	v_and_b32_e32 v255, 0xffff0000, v219
	v_pk_mul_f32 v[248:249], v[248:249], v[252:253]
	v_pk_mul_f32 v[250:251], v[250:251], v[254:255]
	v_pk_mul_f32 v[12:13], v[12:13], v[248:249]
	v_pk_mul_f32 v[14:15], v[14:15], v[250:251]
	v_lshlrev_b32_e32 v248, 16, v224
	v_and_b32_e32 v249, 0xffff0000, v224
	v_lshlrev_b32_e32 v250, 16, v225
	v_and_b32_e32 v251, 0xffff0000, v225
	v_max_f32_e32 v248, v248, v248
	v_max_f32_e32 v249, v249, v249
	v_max_f32_e32 v250, v250, v250
	v_max_f32_e32 v251, v251, v251
	v_max_f32_e32 v248, 0x1e3ce508, v248
	v_max_f32_e32 v249, 0x1e3ce508, v249
	v_max_f32_e32 v250, 0x1e3ce508, v250
	v_max_f32_e32 v251, 0x1e3ce508, v251
	v_rcp_f32_e32 v248, v248
	v_rcp_f32_e32 v249, v249
	v_rcp_f32_e32 v250, v250
	v_rcp_f32_e32 v251, v251
	v_lshlrev_b32_e32 v252, 16, v220
	v_and_b32_e32 v253, 0xffff0000, v220
	v_lshlrev_b32_e32 v254, 16, v221
	v_and_b32_e32 v255, 0xffff0000, v221
	v_pk_mul_f32 v[248:249], v[248:249], v[252:253]
	v_pk_mul_f32 v[250:251], v[250:251], v[254:255]
	v_pk_mul_f32 v[8:9], v[8:9], v[248:249]
	v_pk_mul_f32 v[10:11], v[10:11], v[250:251]
	s_waitcnt vmcnt(0)
	v_lshlrev_b32_e32 v248, 16, v230
	v_and_b32_e32 v249, 0xffff0000, v230
	v_lshlrev_b32_e32 v250, 16, v231
	v_and_b32_e32 v251, 0xffff0000, v231
	v_max_f32_e32 v248, v248, v248
	v_max_f32_e32 v249, v249, v249
	v_max_f32_e32 v250, v250, v250
	v_max_f32_e32 v251, v251, v251
	v_max_f32_e32 v248, 0x1e3ce508, v248
	v_max_f32_e32 v249, 0x1e3ce508, v249
	v_max_f32_e32 v250, 0x1e3ce508, v250
	v_max_f32_e32 v251, 0x1e3ce508, v251
	v_rcp_f32_e32 v248, v248
	v_rcp_f32_e32 v249, v249
	v_rcp_f32_e32 v250, v250
	v_rcp_f32_e32 v251, v251
	v_lshlrev_b32_e32 v252, 16, v226
	v_and_b32_e32 v253, 0xffff0000, v226
	v_lshlrev_b32_e32 v254, 16, v227
	v_and_b32_e32 v255, 0xffff0000, v227
	v_pk_mul_f32 v[248:249], v[248:249], v[252:253]
	v_pk_mul_f32 v[250:251], v[250:251], v[254:255]
	v_pk_mul_f32 v[4:5], v[4:5], v[248:249]
	v_pk_mul_f32 v[6:7], v[6:7], v[250:251]
	v_lshlrev_b32_e32 v248, 16, v232
	v_and_b32_e32 v249, 0xffff0000, v232
	v_lshlrev_b32_e32 v250, 16, v233
	v_and_b32_e32 v251, 0xffff0000, v233
	v_max_f32_e32 v248, v248, v248
	v_max_f32_e32 v249, v249, v249
	v_max_f32_e32 v250, v250, v250
	v_max_f32_e32 v251, v251, v251
	v_max_f32_e32 v248, 0x1e3ce508, v248
	v_max_f32_e32 v249, 0x1e3ce508, v249
	v_max_f32_e32 v250, 0x1e3ce508, v250
	v_max_f32_e32 v251, 0x1e3ce508, v251
	v_rcp_f32_e32 v248, v248
	v_rcp_f32_e32 v249, v249
	v_rcp_f32_e32 v250, v250
	v_rcp_f32_e32 v251, v251
	v_lshlrev_b32_e32 v252, 16, v228
	v_and_b32_e32 v253, 0xffff0000, v228
	v_lshlrev_b32_e32 v254, 16, v229
	v_and_b32_e32 v255, 0xffff0000, v229
	v_pk_mul_f32 v[248:249], v[248:249], v[252:253]
	v_pk_mul_f32 v[250:251], v[250:251], v[254:255]
	v_pk_mul_f32 v[0:1], v[0:1], v[248:249]
	v_pk_mul_f32 v[2:3], v[2:3], v[250:251]

; __device__ __forceinline__ unsigned pk2(float lo, float hi) { f32x2 v = {lo, hi}; bf16x2_t b = __builtin_convertvector(v, bf16x2_t); return __builtin_bit_cast(unsigned, b); }
;     __device__ __forceinline__ void operator()(const f32x4 (&acc)[2][2][4][2], const Unit& u, int wr, int wc, int fr, int fq) const {
;         const int row0 = u.pm * 256 + wr * 64 + fr, col0 = u.pn * 256 + wc * 32 + 8 * fq;
; #pragma unroll
;         for (int ai = 0; ai < 2; ++ai)
; #pragma unroll
;             for (int m = 0; m < 4; ++m) {
;                 const size_t row = (size_t)(row0 + ai * 128 + m * 16);
; #pragma unroll
;                 for (int bj = 0; bj < 2; ++bj) {
;                     const int col = col0 + bj * 128;
;                     const u32x4 g = *(const u32x4*)(P + row * PS + C_GATE + 4096 + col);
;                     f32x4 v0 = acc[ai][bj][m][0], v1 = acc[ai][bj][m][1];
;                     v0[0] *= fmaxf(bflo(g.x), 1e-20f); v0[1] *= fmaxf(bfhi(g.x), 1e-20f); v0[2] *= fmaxf(bflo(g.y), 1e-20f); v0[3] *= fmaxf(bfhi(g.y), 1e-20f);
;                     v1[0] *= fmaxf(bflo(g.z), 1e-20f); v1[1] *= fmaxf(bfhi(g.z), 1e-20f); v1[2] *= fmaxf(bflo(g.w), 1e-20f); v1[3] *= fmaxf(bfhi(g.w), 1e-20f);
;                     u32x4 w; w.x = pk2(v0[0], v0[1]); w.y = pk2(v0[2], v0[3]); w.z = pk2(v1[0], v1[1]); w.w = pk2(v1[2], v1[3]);
;                     *(u32x4*)(Yb + row * DM + col) = w;
.LBB0_766:
	v_lshl_add_u32 v34, s18, 8, v174
	v_mov_b64_e32 v[36:37], s[42:43]
	v_ashrrev_i32_e32 v159, 31, v158
	v_mad_i64_i32 v[36:37], vcc, v34, s90, v[36:37]
	v_lshlrev_b64 v[160:161], 1, v[158:159]
	v_lshl_add_u64 v[36:37], v[36:37], 0, s[36:37]
	v_mov_b32_e32 v164, v34
	v_ashrrev_i32_e32 v165, 31, v34
	v_lshl_add_u64 v[36:37], v[36:37], 0, v[160:161]
	v_lshlrev_b64 v[164:165], 12, v[164:165]
	v_lshl_add_u64 v[162:163], s[40:41], 0, v[164:165]
	v_lshl_add_u64 v[162:163], v[162:163], 0, v[160:161]
	s_mov_b32 s4, 0x60000
	s_mov_b32 s5, 0
	global_load_dwordx4 v[134:137], v[36:37], off
	global_load_dwordx4 v[138:141], v[36:37], off offset:256
	v_lshl_add_u64 v[36:37], v[36:37], 0, s[4:5]
	global_load_dwordx4 v[178:181], v[36:37], off
	global_load_dwordx4 v[182:185], v[36:37], off offset:256
	v_lshl_add_u64 v[36:37], v[36:37], 0, s[4:5]
	global_load_dwordx4 v[186:189], v[36:37], off
	global_load_dwordx4 v[190:193], v[36:37], off offset:256
	v_lshl_add_u64 v[36:37], v[36:37], 0, s[4:5]
	global_load_dwordx4 v[194:197], v[36:37], off
	global_load_dwordx4 v[198:201], v[36:37], off offset:256
	s_mov_b32 s4, 0x1e0000
	v_lshl_add_u64 v[36:37], v[36:37], 0, s[4:5]
	s_mov_b32 s4, 0x60000
	global_load_dwordx4 v[202:205], v[36:37], off
	global_load_dwordx4 v[206:209], v[36:37], off offset:256
	v_lshl_add_u64 v[36:37], v[36:37], 0, s[4:5]
	global_load_dwordx4 v[210:213], v[36:37], off
	global_load_dwordx4 v[214:217], v[36:37], off offset:256
	v_lshl_add_u64 v[36:37], v[36:37], 0, s[4:5]
	global_load_dwordx4 v[218:221], v[36:37], off
	global_load_dwordx4 v[222:225], v[36:37], off offset:256
	v_lshl_add_u64 v[36:37], v[36:37], 0, s[4:5]
	global_load_dwordx4 v[226:229], v[36:37], off
	global_load_dwordx4 v[230:233], v[36:37], off offset:256
	s_mov_b32 s4, 0x10000
	s_waitcnt vmcnt(15)
	v_lshlrev_b32_e32 v248, 16, v134
	v_and_b32_e32 v249, 0xffff0000, v134
	v_lshlrev_b32_e32 v250, 16, v135
	v_and_b32_e32 v251, 0xffff0000, v135
	v_max_f32_e32 v248, v248, v248
	v_max_f32_e32 v249, v249, v249
	v_max_f32_e32 v250, v250, v250
	v_max_f32_e32 v251, v251, v251
	v_max_f32_e32 v248, 0x1e3ce508, v248
	v_max_f32_e32 v249, 0x1e3ce508, v249
	v_max_f32_e32 v250, 0x1e3ce508, v250
	v_max_f32_e32 v251, 0x1e3ce508, v251
	v_pk_mul_f32 v[130:131], v[130:131], v[248:249]
	v_pk_mul_f32 v[132:133], v[132:133], v[250:251]
	v_lshlrev_b32_e32 v248, 16, v136
	v_and_b32_e32 v249, 0xffff0000, v136
	v_lshlrev_b32_e32 v250, 16, v137
	v_and_b32_e32 v251, 0xffff0000, v137
	v_max_f32_e32 v248, v248, v248
	v_max_f32_e32 v249, v249, v249
	v_max_f32_e32 v250, v250, v250
	v_max_f32_e32 v251, v251, v251
	v_max_f32_e32 v248, 0x1e3ce508, v248
	v_max_f32_e32 v249, 0x1e3ce508, v249
	v_max_f32_e32 v250, 0x1e3ce508, v250
	v_max_f32_e32 v251, 0x1e3ce508, v251
	v_pk_mul_f32 v[126:127], v[126:127], v[248:249]
	v_pk_mul_f32 v[128:129], v[128:129], v[250:251]
	v_cvt_pk_bf16_f32 v134, v130, v131
	v_cvt_pk_bf16_f32 v135, v132, v133
	v_cvt_pk_bf16_f32 v136, v126, v127
	v_cvt_pk_bf16_f32 v137, v128, v129
	global_store_dwordx4 v[162:163], v[134:137], off
	s_waitcnt vmcnt(15)
	v_lshlrev_b32_e32 v248, 16, v138
	v_and_b32_e32 v249, 0xffff0000, v138
	v_lshlrev_b32_e32 v250, 16, v139
	v_and_b32_e32 v251, 0xffff0000, v139
	v_max_f32_e32 v248, v248, v248
	v_max_f32_e32 v249, v249, v249
	v_max_f32_e32 v250, v250, v250
	v_max_f32_e32 v251, v251, v251
	v_max_f32_e32 v248, 0x1e3ce508, v248
	v_max_f32_e32 v249, 0x1e3ce508, v249
	v_max_f32_e32 v250, 0x1e3ce508, v250
	v_max_f32_e32 v251, 0x1e3ce508, v251
	v_pk_mul_f32 v[122:123], v[122:123], v[248:249]
	v_pk_mul_f32 v[124:125], v[124:125], v[250:251]
	v_lshlrev_b32_e32 v248, 16, v140
	v_and_b32_e32 v249, 0xffff0000, v140
	v_lshlrev_b32_e32 v250, 16, v141
	v_and_b32_e32 v251, 0xffff0000, v141
	v_max_f32_e32 v248, v248, v248
	v_max_f32_e32 v249, v249, v249
	v_max_f32_e32 v250, v250, v250
	v_max_f32_e32 v251, v251, v251
	v_max_f32_e32 v248, 0x1e3ce508, v248
	v_max_f32_e32 v249, 0x1e3ce508, v249
	v_max_f32_e32 v250, 0x1e3ce508, v250
	v_max_f32_e32 v251, 0x1e3ce508, v251
	v_pk_mul_f32 v[118:119], v[118:119], v[248:249]
	v_pk_mul_f32 v[120:121], v[120:121], v[250:251]
	v_cvt_pk_bf16_f32 v138, v122, v123
	v_cvt_pk_bf16_f32 v139, v124, v125
	v_cvt_pk_bf16_f32 v140, v118, v119
	v_cvt_pk_bf16_f32 v141, v120, v121
	global_store_dwordx4 v[162:163], v[138:141], off offset:256
	v_lshl_add_u64 v[162:163], v[162:163], 0, s[4:5]
	s_waitcnt vmcnt(15)
	v_lshlrev_b32_e32 v248, 16, v178
	v_and_b32_e32 v249, 0xffff0000, v178
	v_lshlrev_b32_e32 v250, 16, v179
	v_and_b32_e32 v251, 0xffff0000, v179
	v_max_f32_e32 v248, v248, v248
	v_max_f32_e32 v249, v249, v249
	v_max_f32_e32 v250, v250, v250
	v_max_f32_e32 v251, v251, v251
	v_max_f32_e32 v248, 0x1e3ce508, v248
	v_max_f32_e32 v249, 0x1e3ce508, v249
	v_max_f32_e32 v250, 0x1e3ce508, v250
	v_max_f32_e32 v251, 0x1e3ce508, v251
	v_pk_mul_f32 v[114:115], v[114:115], v[248:249]
	v_pk_mul_f32 v[116:117], v[116:117], v[250:251]
	v_lshlrev_b32_e32 v248, 16, v180
	v_and_b32_e32 v249, 0xffff0000, v180
	v_lshlrev_b32_e32 v250, 16, v181
	v_and_b32_e32 v251, 0xffff0000, v181
	v_max_f32_e32 v248, v248, v248
	v_max_f32_e32 v249, v249, v249
	v_max_f32_e32 v250, v250, v250
	v_max_f32_e32 v251, v251, v251
	v_max_f32_e32 v248, 0x1e3ce508, v248
	v_max_f32_e32 v249, 0x1e3ce508, v249
	v_max_f32_e32 v250, 0x1e3ce508, v250
	v_max_f32_e32 v251, 0x1e3ce508, v251
	v_pk_mul_f32 v[110:111], v[110:111], v[248:249]
	v_pk_mul_f32 v[112:113], v[112:113], v[250:251]
	v_cvt_pk_bf16_f32 v178, v114, v115
	v_cvt_pk_bf16_f32 v179, v116, v117
	v_cvt_pk_bf16_f32 v180, v110, v111
	v_cvt_pk_bf16_f32 v181, v112, v113
	global_store_dwordx4 v[162:163], v[178:181], off
	s_waitcnt vmcnt(15)
; __device__ __forceinline__ unsigned pk2(float lo, float hi) { f32x2 v = {lo, hi}; bf16x2_t b = __builtin_convertvector(v, bf16x2_t); return __builtin_bit_cast(unsigned, b); }
;     __device__ __forceinline__ void operator()(const f32x4 (&acc)[2][2][4][2], const Unit& u, int wr, int wc, int fr, int fq) const {
;         const int row0 = u.pm * 256 + wr * 64 + fr, col0 = u.pn * 256 + wc * 32 + 8 * fq;
; #pragma unroll
;         for (int ai = 0; ai < 2; ++ai)
; #pragma unroll
;             for (int m = 0; m < 4; ++m) {
;                 const size_t row = (size_t)(row0 + ai * 128 + m * 16);
; #pragma unroll
;                 for (int bj = 0; bj < 2; ++bj) {
;                     const int col = col0 + bj * 128;
;                     const u32x4 g = *(const u32x4*)(P + row * PS + C_GATE + 4096 + col);
;                     f32x4 v0 = acc[ai][bj][m][0], v1 = acc[ai][bj][m][1];
;                     v0[0] *= fmaxf(bflo(g.x), 1e-20f); v0[1] *= fmaxf(bfhi(g.x), 1e-20f); v0[2] *= fmaxf(bflo(g.y), 1e-20f); v0[3] *= fmaxf(bfhi(g.y), 1e-20f);
;                     v1[0] *= fmaxf(bflo(g.z), 1e-20f); v1[1] *= fmaxf(bfhi(g.z), 1e-20f); v1[2] *= fmaxf(bflo(g.w), 1e-20f); v1[3] *= fmaxf(bfhi(g.w), 1e-20f);
;                     u32x4 w; w.x = pk2(v0[0], v0[1]); w.y = pk2(v0[2], v0[3]); w.z = pk2(v1[0], v1[1]); w.w = pk2(v1[2], v1[3]);
;                     *(u32x4*)(Yb + row * DM + col) = w;
	v_lshlrev_b32_e32 v248, 16, v182
	v_and_b32_e32 v249, 0xffff0000, v182
	v_lshlrev_b32_e32 v250, 16, v183
	v_and_b32_e32 v251, 0xffff0000, v183
	v_max_f32_e32 v248, v248, v248
	v_max_f32_e32 v249, v249, v249
	v_max_f32_e32 v250, v250, v250
	v_max_f32_e32 v251, v251, v251
	v_max_f32_e32 v248, 0x1e3ce508, v248
	v_max_f32_e32 v249, 0x1e3ce508, v249
	v_max_f32_e32 v250, 0x1e3ce508, v250
	v_max_f32_e32 v251, 0x1e3ce508, v251
	v_pk_mul_f32 v[106:107], v[106:107], v[248:249]
	v_pk_mul_f32 v[108:109], v[108:109], v[250:251]
	v_lshlrev_b32_e32 v248, 16, v184
	v_and_b32_e32 v249, 0xffff0000, v184
	v_lshlrev_b32_e32 v250, 16, v185
	v_and_b32_e32 v251, 0xffff0000, v185
	v_max_f32_e32 v248, v248, v248
	v_max_f32_e32 v249, v249, v249
	v_max_f32_e32 v250, v250, v250
	v_max_f32_e32 v251, v251, v251
	v_max_f32_e32 v248, 0x1e3ce508, v248
	v_max_f32_e32 v249, 0x1e3ce508, v249
	v_max_f32_e32 v250, 0x1e3ce508, v250
	v_max_f32_e32 v251, 0x1e3ce508, v251
	v_pk_mul_f32 v[102:103], v[102:103], v[248:249]
	v_pk_mul_f32 v[104:105], v[104:105], v[250:251]
	v_cvt_pk_bf16_f32 v182, v106, v107
	v_cvt_pk_bf16_f32 v183, v108, v109
	v_cvt_pk_bf16_f32 v184, v102, v103
	v_cvt_pk_bf16_f32 v185, v104, v105
	global_store_dwordx4 v[162:163], v[182:185], off offset:256
	v_lshl_add_u64 v[162:163], v[162:163], 0, s[4:5]
	s_waitcnt vmcnt(15)
	v_lshlrev_b32_e32 v248, 16, v186
	v_and_b32_e32 v249, 0xffff0000, v186
	v_lshlrev_b32_e32 v250, 16, v187
	v_and_b32_e32 v251, 0xffff0000, v187
	v_max_f32_e32 v248, v248, v248
	v_max_f32_e32 v249, v249, v249
	v_max_f32_e32 v250, v250, v250
	v_max_f32_e32 v251, v251, v251
	v_max_f32_e32 v248, 0x1e3ce508, v248
	v_max_f32_e32 v249, 0x1e3ce508, v249
	v_max_f32_e32 v250, 0x1e3ce508, v250
	v_max_f32_e32 v251, 0x1e3ce508, v251
	v_pk_mul_f32 v[98:99], v[98:99], v[248:249]
	v_pk_mul_f32 v[100:101], v[100:101], v[250:251]
	v_lshlrev_b32_e32 v248, 16, v188
	v_and_b32_e32 v249, 0xffff0000, v188
	v_lshlrev_b32_e32 v250, 16, v189
	v_and_b32_e32 v251, 0xffff0000, v189
	v_max_f32_e32 v248, v248, v248
	v_max_f32_e32 v249, v249, v249
	v_max_f32_e32 v250, v250, v250
	v_max_f32_e32 v251, v251, v251
	v_max_f32_e32 v248, 0x1e3ce508, v248
	v_max_f32_e32 v249, 0x1e3ce508, v249
	v_max_f32_e32 v250, 0x1e3ce508, v250
	v_max_f32_e32 v251, 0x1e3ce508, v251
	v_pk_mul_f32 v[94:95], v[94:95], v[248:249]
	v_pk_mul_f32 v[96:97], v[96:97], v[250:251]
	v_cvt_pk_bf16_f32 v186, v98, v99
	v_cvt_pk_bf16_f32 v187, v100, v101
	v_cvt_pk_bf16_f32 v188, v94, v95
	v_cvt_pk_bf16_f32 v189, v96, v97
	global_store_dwordx4 v[162:163], v[186:189], off
	s_waitcnt vmcnt(15)
	v_lshlrev_b32_e32 v248, 16, v190
	v_and_b32_e32 v249, 0xffff0000, v190
	v_lshlrev_b32_e32 v250, 16, v191
	v_and_b32_e32 v251, 0xffff0000, v191
	v_max_f32_e32 v248, v248, v248
	v_max_f32_e32 v249, v249, v249
	v_max_f32_e32 v250, v250, v250
	v_max_f32_e32 v251, v251, v251
	v_max_f32_e32 v248, 0x1e3ce508, v248
	v_max_f32_e32 v249, 0x1e3ce508, v249
	v_max_f32_e32 v250, 0x1e3ce508, v250
	v_max_f32_e32 v251, 0x1e3ce508, v251
	v_pk_mul_f32 v[90:91], v[90:91], v[248:249]
	v_pk_mul_f32 v[92:93], v[92:93], v[250:251]
	v_lshlrev_b32_e32 v248, 16, v192
	v_and_b32_e32 v249, 0xffff0000, v192
	v_lshlrev_b32_e32 v250, 16, v193
	v_and_b32_e32 v251, 0xffff0000, v193
	v_max_f32_e32 v248, v248, v248
	v_max_f32_e32 v249, v249, v249
	v_max_f32_e32 v250, v250, v250
	v_max_f32_e32 v251, v251, v251
	v_max_f32_e32 v248, 0x1e3ce508, v248
	v_max_f32_e32 v249, 0x1e3ce508, v249
	v_max_f32_e32 v250, 0x1e3ce508, v250
	v_max_f32_e32 v251, 0x1e3ce508, v251
	v_pk_mul_f32 v[86:87], v[86:87], v[248:249]
	v_pk_mul_f32 v[88:89], v[88:89], v[250:251]
	v_cvt_pk_bf16_f32 v190, v90, v91
	v_cvt_pk_bf16_f32 v191, v92, v93
	v_cvt_pk_bf16_f32 v192, v86, v87
	v_cvt_pk_bf16_f32 v193, v88, v89
	global_store_dwordx4 v[162:163], v[190:193], off offset:256
	v_lshl_add_u64 v[162:163], v[162:163], 0, s[4:5]
	s_waitcnt vmcnt(15)
	v_lshlrev_b32_e32 v248, 16, v194
	v_and_b32_e32 v249, 0xffff0000, v194
	v_lshlrev_b32_e32 v250, 16, v195
	v_and_b32_e32 v251, 0xffff0000, v195
	v_max_f32_e32 v248, v248, v248
	v_max_f32_e32 v249, v249, v249
	v_max_f32_e32 v250, v250, v250
	v_max_f32_e32 v251, v251, v251
	v_max_f32_e32 v248, 0x1e3ce508, v248
	v_max_f32_e32 v249, 0x1e3ce508, v249
	v_max_f32_e32 v250, 0x1e3ce508, v250
	v_max_f32_e32 v251, 0x1e3ce508, v251
	v_pk_mul_f32 v[82:83], v[82:83], v[248:249]
	v_pk_mul_f32 v[84:85], v[84:85], v[250:251]
	v_lshlrev_b32_e32 v248, 16, v196
	v_and_b32_e32 v249, 0xffff0000, v196
	v_lshlrev_b32_e32 v250, 16, v197
	v_and_b32_e32 v251, 0xffff0000, v197
	v_max_f32_e32 v248, v248, v248
	v_max_f32_e32 v249, v249, v249
	v_max_f32_e32 v250, v250, v250
	v_max_f32_e32 v251, v251, v251
	v_max_f32_e32 v248, 0x1e3ce508, v248
	v_max_f32_e32 v249, 0x1e3ce508, v249
	v_max_f32_e32 v250, 0x1e3ce508, v250
	v_max_f32_e32 v251, 0x1e3ce508, v251
	v_pk_mul_f32 v[78:79], v[78:79], v[248:249]
	v_pk_mul_f32 v[80:81], v[80:81], v[250:251]
	v_cvt_pk_bf16_f32 v194, v82, v83
	v_cvt_pk_bf16_f32 v195, v84, v85
	v_cvt_pk_bf16_f32 v196, v78, v79
	v_cvt_pk_bf16_f32 v197, v80, v81
	global_store_dwordx4 v[162:163], v[194:197], off
	s_waitcnt vmcnt(15)
; __device__ __forceinline__ unsigned pk2(float lo, float hi) { f32x2 v = {lo, hi}; bf16x2_t b = __builtin_convertvector(v, bf16x2_t); return __builtin_bit_cast(unsigned, b); }
;     __device__ __forceinline__ void operator()(const f32x4 (&acc)[2][2][4][2], const Unit& u, int wr, int wc, int fr, int fq) const {
;         const int row0 = u.pm * 256 + wr * 64 + fr, col0 = u.pn * 256 + wc * 32 + 8 * fq;
; #pragma unroll
;         for (int ai = 0; ai < 2; ++ai)
; #pragma unroll
;             for (int m = 0; m < 4; ++m) {
;                 const size_t row = (size_t)(row0 + ai * 128 + m * 16);
; #pragma unroll
;                 for (int bj = 0; bj < 2; ++bj) {
;                     const int col = col0 + bj * 128;
;                     const u32x4 g = *(const u32x4*)(P + row * PS + C_GATE + 4096 + col);
;                     f32x4 v0 = acc[ai][bj][m][0], v1 = acc[ai][bj][m][1];
;                     v0[0] *= fmaxf(bflo(g.x), 1e-20f); v0[1] *= fmaxf(bfhi(g.x), 1e-20f); v0[2] *= fmaxf(bflo(g.y), 1e-20f); v0[3] *= fmaxf(bfhi(g.y), 1e-20f);
;                     v1[0] *= fmaxf(bflo(g.z), 1e-20f); v1[1] *= fmaxf(bfhi(g.z), 1e-20f); v1[2] *= fmaxf(bflo(g.w), 1e-20f); v1[3] *= fmaxf(bfhi(g.w), 1e-20f);
;                     u32x4 w; w.x = pk2(v0[0], v0[1]); w.y = pk2(v0[2], v0[3]); w.z = pk2(v1[0], v1[1]); w.w = pk2(v1[2], v1[3]);
;                     *(u32x4*)(Yb + row * DM + col) = w;
	v_lshlrev_b32_e32 v248, 16, v198
	v_and_b32_e32 v249, 0xffff0000, v198
	v_lshlrev_b32_e32 v250, 16, v199
	v_and_b32_e32 v251, 0xffff0000, v199
	v_max_f32_e32 v248, v248, v248
	v_max_f32_e32 v249, v249, v249
	v_max_f32_e32 v250, v250, v250
	v_max_f32_e32 v251, v251, v251
	v_max_f32_e32 v248, 0x1e3ce508, v248
	v_max_f32_e32 v249, 0x1e3ce508, v249
	v_max_f32_e32 v250, 0x1e3ce508, v250
	v_max_f32_e32 v251, 0x1e3ce508, v251
	v_pk_mul_f32 v[74:75], v[74:75], v[248:249]
	v_pk_mul_f32 v[76:77], v[76:77], v[250:251]
	v_lshlrev_b32_e32 v248, 16, v200
	v_and_b32_e32 v249, 0xffff0000, v200
	v_lshlrev_b32_e32 v250, 16, v201
	v_and_b32_e32 v251, 0xffff0000, v201
	v_max_f32_e32 v248, v248, v248
	v_max_f32_e32 v249, v249, v249
	v_max_f32_e32 v250, v250, v250
	v_max_f32_e32 v251, v251, v251
	v_max_f32_e32 v248, 0x1e3ce508, v248
	v_max_f32_e32 v249, 0x1e3ce508, v249
	v_max_f32_e32 v250, 0x1e3ce508, v250
	v_max_f32_e32 v251, 0x1e3ce508, v251
	v_pk_mul_f32 v[70:71], v[70:71], v[248:249]
	v_pk_mul_f32 v[72:73], v[72:73], v[250:251]
	v_cvt_pk_bf16_f32 v198, v74, v75
	v_cvt_pk_bf16_f32 v199, v76, v77
	v_cvt_pk_bf16_f32 v200, v70, v71
	v_cvt_pk_bf16_f32 v201, v72, v73
	global_store_dwordx4 v[162:163], v[198:201], off offset:256
	s_mov_b32 s4, 0x50000
	v_lshl_add_u64 v[162:163], v[162:163], 0, s[4:5]
	s_mov_b32 s4, 0x10000
	s_waitcnt vmcnt(15)
	v_lshlrev_b32_e32 v248, 16, v202
	v_and_b32_e32 v249, 0xffff0000, v202
	v_lshlrev_b32_e32 v250, 16, v203
	v_and_b32_e32 v251, 0xffff0000, v203
	v_max_f32_e32 v248, v248, v248
	v_max_f32_e32 v249, v249, v249
	v_max_f32_e32 v250, v250, v250
	v_max_f32_e32 v251, v251, v251
	v_max_f32_e32 v248, 0x1e3ce508, v248
	v_max_f32_e32 v249, 0x1e3ce508, v249
	v_max_f32_e32 v250, 0x1e3ce508, v250
	v_max_f32_e32 v251, 0x1e3ce508, v251
	v_pk_mul_f32 v[66:67], v[66:67], v[248:249]
	v_pk_mul_f32 v[68:69], v[68:69], v[250:251]
	v_lshlrev_b32_e32 v248, 16, v204
	v_and_b32_e32 v249, 0xffff0000, v204
	v_lshlrev_b32_e32 v250, 16, v205
	v_and_b32_e32 v251, 0xffff0000, v205
	v_max_f32_e32 v248, v248, v248
	v_max_f32_e32 v249, v249, v249
	v_max_f32_e32 v250, v250, v250
	v_max_f32_e32 v251, v251, v251
	v_max_f32_e32 v248, 0x1e3ce508, v248
	v_max_f32_e32 v249, 0x1e3ce508, v249
	v_max_f32_e32 v250, 0x1e3ce508, v250
	v_max_f32_e32 v251, 0x1e3ce508, v251
	v_pk_mul_f32 v[62:63], v[62:63], v[248:249]
	v_pk_mul_f32 v[64:65], v[64:65], v[250:251]
	v_cvt_pk_bf16_f32 v202, v66, v67
	v_cvt_pk_bf16_f32 v203, v68, v69
	v_cvt_pk_bf16_f32 v204, v62, v63
	v_cvt_pk_bf16_f32 v205, v64, v65
	global_store_dwordx4 v[162:163], v[202:205], off
	s_waitcnt vmcnt(15)
	v_lshlrev_b32_e32 v248, 16, v206
	v_and_b32_e32 v249, 0xffff0000, v206
	v_lshlrev_b32_e32 v250, 16, v207
	v_and_b32_e32 v251, 0xffff0000, v207
	v_max_f32_e32 v248, v248, v248
	v_max_f32_e32 v249, v249, v249
	v_max_f32_e32 v250, v250, v250
	v_max_f32_e32 v251, v251, v251
	v_max_f32_e32 v248, 0x1e3ce508, v248
	v_max_f32_e32 v249, 0x1e3ce508, v249
	v_max_f32_e32 v250, 0x1e3ce508, v250
	v_max_f32_e32 v251, 0x1e3ce508, v251
	v_pk_mul_f32 v[58:59], v[58:59], v[248:249]
	v_pk_mul_f32 v[60:61], v[60:61], v[250:251]
	v_lshlrev_b32_e32 v248, 16, v208
	v_and_b32_e32 v249, 0xffff0000, v208
	v_lshlrev_b32_e32 v250, 16, v209
	v_and_b32_e32 v251, 0xffff0000, v209
	v_max_f32_e32 v248, v248, v248
	v_max_f32_e32 v249, v249, v249
	v_max_f32_e32 v250, v250, v250
	v_max_f32_e32 v251, v251, v251
	v_max_f32_e32 v248, 0x1e3ce508, v248
	v_max_f32_e32 v249, 0x1e3ce508, v249
	v_max_f32_e32 v250, 0x1e3ce508, v250
	v_max_f32_e32 v251, 0x1e3ce508, v251
	v_pk_mul_f32 v[54:55], v[54:55], v[248:249]
	v_pk_mul_f32 v[56:57], v[56:57], v[250:251]
	v_cvt_pk_bf16_f32 v206, v58, v59
	v_cvt_pk_bf16_f32 v207, v60, v61
	v_cvt_pk_bf16_f32 v208, v54, v55
	v_cvt_pk_bf16_f32 v209, v56, v57
	global_store_dwordx4 v[162:163], v[206:209], off offset:256
	v_lshl_add_u64 v[162:163], v[162:163], 0, s[4:5]
	s_waitcnt vmcnt(15)
	v_lshlrev_b32_e32 v248, 16, v210
	v_and_b32_e32 v249, 0xffff0000, v210
	v_lshlrev_b32_e32 v250, 16, v211
	v_and_b32_e32 v251, 0xffff0000, v211
	v_max_f32_e32 v248, v248, v248
	v_max_f32_e32 v249, v249, v249
	v_max_f32_e32 v250, v250, v250
	v_max_f32_e32 v251, v251, v251
	v_max_f32_e32 v248, 0x1e3ce508, v248
	v_max_f32_e32 v249, 0x1e3ce508, v249
	v_max_f32_e32 v250, 0x1e3ce508, v250
	v_max_f32_e32 v251, 0x1e3ce508, v251
	v_pk_mul_f32 v[50:51], v[50:51], v[248:249]
	v_pk_mul_f32 v[52:53], v[52:53], v[250:251]
	v_lshlrev_b32_e32 v248, 16, v212
	v_and_b32_e32 v249, 0xffff0000, v212
	v_lshlrev_b32_e32 v250, 16, v213
	v_and_b32_e32 v251, 0xffff0000, v213
	v_max_f32_e32 v248, v248, v248
	v_max_f32_e32 v249, v249, v249
	v_max_f32_e32 v250, v250, v250
	v_max_f32_e32 v251, v251, v251
	v_max_f32_e32 v248, 0x1e3ce508, v248
	v_max_f32_e32 v249, 0x1e3ce508, v249
	v_max_f32_e32 v250, 0x1e3ce508, v250
	v_max_f32_e32 v251, 0x1e3ce508, v251
	v_pk_mul_f32 v[46:47], v[46:47], v[248:249]
	v_pk_mul_f32 v[48:49], v[48:49], v[250:251]
	v_cvt_pk_bf16_f32 v210, v50, v51
	v_cvt_pk_bf16_f32 v211, v52, v53
	v_cvt_pk_bf16_f32 v212, v46, v47
	v_cvt_pk_bf16_f32 v213, v48, v49
	global_store_dwordx4 v[162:163], v[210:213], off
	s_waitcnt vmcnt(15)
; #define PG8_BAR __builtin_amdgcn_s_barrier()
; __device__ __forceinline__ unsigned pk2(float lo, float hi) { f32x2 v = {lo, hi}; bf16x2_t b = __builtin_convertvector(v, bf16x2_t); return __builtin_bit_cast(unsigned, b); }
; template <class Epi, class Sched, bool ALIGN_EPI = false, bool SP2 = false>
; __device__ __forceinline__ void gemm_phase(PG8_LAS unsigned char* lds, const Gemm g, const Sched& S, const Epi& E) {
;     ...
;         if (!has_next) break;
; #pragma unroll
;         for (int a = 0; a < 2; ++a)
; #pragma unroll
;             for (int b = 0; b < 2; ++b)
; #pragma unroll
;                 for (int m = 0; m < 4; ++m)
; #pragma unroll
;                     for (int n = 0; n < 2; ++n) acc[a][b][m][n] = (f32x4){0.f, 0.f, 0.f, 0.f};
;         cur = nxt; cA = nA; cB = nB; ++ui;
;         if constexpr (ALIGN_EPI) { if (wr == 1) PG8_BAR; }
;     __device__ __forceinline__ void operator()(const f32x4 (&acc)[2][2][4][2], const Unit& u, int wr, int wc, int fr, int fq) const {
;         const int row0 = u.pm * 256 + wr * 64 + fr, col0 = u.pn * 256 + wc * 32 + 8 * fq;
; #pragma unroll
;         for (int ai = 0; ai < 2; ++ai)
; #pragma unroll
;             for (int m = 0; m < 4; ++m) {
;                 const size_t row = (size_t)(row0 + ai * 128 + m * 16);
; #pragma unroll
;                 for (int bj = 0; bj < 2; ++bj) {
;                     const int col = col0 + bj * 128;
;                     const u32x4 g = *(const u32x4*)(P + row * PS + C_GATE + 4096 + col);
;                     f32x4 v0 = acc[ai][bj][m][0], v1 = acc[ai][bj][m][1];
;                     v0[0] *= fmaxf(bflo(g.x), 1e-20f); v0[1] *= fmaxf(bfhi(g.x), 1e-20f); v0[2] *= fmaxf(bflo(g.y), 1e-20f); v0[3] *= fmaxf(bfhi(g.y), 1e-20f);
;                     v1[0] *= fmaxf(bflo(g.z), 1e-20f); v1[1] *= fmaxf(bfhi(g.z), 1e-20f); v1[2] *= fmaxf(bflo(g.w), 1e-20f); v1[3] *= fmaxf(bfhi(g.w), 1e-20f);
;                     u32x4 w; w.x = pk2(v0[0], v0[1]); w.y = pk2(v0[2], v0[3]); w.z = pk2(v1[0], v1[1]); w.w = pk2(v1[2], v1[3]);
;                     *(u32x4*)(Yb + row * DM + col) = w;
	v_lshlrev_b32_e32 v248, 16, v214
	v_and_b32_e32 v249, 0xffff0000, v214
	v_lshlrev_b32_e32 v250, 16, v215
	v_and_b32_e32 v251, 0xffff0000, v215
	v_max_f32_e32 v248, v248, v248
	v_max_f32_e32 v249, v249, v249
	v_max_f32_e32 v250, v250, v250
	v_max_f32_e32 v251, v251, v251
	v_max_f32_e32 v248, 0x1e3ce508, v248
	v_max_f32_e32 v249, 0x1e3ce508, v249
	v_max_f32_e32 v250, 0x1e3ce508, v250
	v_max_f32_e32 v251, 0x1e3ce508, v251
	v_pk_mul_f32 v[42:43], v[42:43], v[248:249]
	v_pk_mul_f32 v[44:45], v[44:45], v[250:251]
	v_lshlrev_b32_e32 v248, 16, v216
	v_and_b32_e32 v249, 0xffff0000, v216
	v_lshlrev_b32_e32 v250, 16, v217
	v_and_b32_e32 v251, 0xffff0000, v217
	v_max_f32_e32 v248, v248, v248
	v_max_f32_e32 v249, v249, v249
	v_max_f32_e32 v250, v250, v250
	v_max_f32_e32 v251, v251, v251
	v_max_f32_e32 v248, 0x1e3ce508, v248
	v_max_f32_e32 v249, 0x1e3ce508, v249
	v_max_f32_e32 v250, 0x1e3ce508, v250
	v_max_f32_e32 v251, 0x1e3ce508, v251
	v_pk_mul_f32 v[38:39], v[38:39], v[248:249]
	v_pk_mul_f32 v[40:41], v[40:41], v[250:251]
	v_cvt_pk_bf16_f32 v214, v42, v43
	v_cvt_pk_bf16_f32 v215, v44, v45
	v_cvt_pk_bf16_f32 v216, v38, v39
	v_cvt_pk_bf16_f32 v217, v40, v41
	global_store_dwordx4 v[162:163], v[214:217], off offset:256
	v_lshl_add_u64 v[162:163], v[162:163], 0, s[4:5]
	s_waitcnt vmcnt(15)
	v_lshlrev_b32_e32 v248, 16, v218
	v_and_b32_e32 v249, 0xffff0000, v218
	v_lshlrev_b32_e32 v250, 16, v219
	v_and_b32_e32 v251, 0xffff0000, v219
	v_max_f32_e32 v248, v248, v248
	v_max_f32_e32 v249, v249, v249
	v_max_f32_e32 v250, v250, v250
	v_max_f32_e32 v251, v251, v251
	v_max_f32_e32 v248, 0x1e3ce508, v248
	v_max_f32_e32 v249, 0x1e3ce508, v249
	v_max_f32_e32 v250, 0x1e3ce508, v250
	v_max_f32_e32 v251, 0x1e3ce508, v251
	v_pk_mul_f32 v[28:29], v[28:29], v[248:249]
	v_pk_mul_f32 v[30:31], v[30:31], v[250:251]
	v_lshlrev_b32_e32 v248, 16, v220
	v_and_b32_e32 v249, 0xffff0000, v220
	v_lshlrev_b32_e32 v250, 16, v221
	v_and_b32_e32 v251, 0xffff0000, v221
	v_max_f32_e32 v248, v248, v248
	v_max_f32_e32 v249, v249, v249
	v_max_f32_e32 v250, v250, v250
	v_max_f32_e32 v251, v251, v251
	v_max_f32_e32 v248, 0x1e3ce508, v248
	v_max_f32_e32 v249, 0x1e3ce508, v249
	v_max_f32_e32 v250, 0x1e3ce508, v250
	v_max_f32_e32 v251, 0x1e3ce508, v251
	v_pk_mul_f32 v[24:25], v[24:25], v[248:249]
	v_pk_mul_f32 v[26:27], v[26:27], v[250:251]
	v_cvt_pk_bf16_f32 v218, v28, v29
	v_cvt_pk_bf16_f32 v219, v30, v31
	v_cvt_pk_bf16_f32 v220, v24, v25
	v_cvt_pk_bf16_f32 v221, v26, v27
	global_store_dwordx4 v[162:163], v[218:221], off
	s_waitcnt vmcnt(15)
	v_lshlrev_b32_e32 v248, 16, v222
	v_and_b32_e32 v249, 0xffff0000, v222
	v_lshlrev_b32_e32 v250, 16, v223
	v_and_b32_e32 v251, 0xffff0000, v223
	v_max_f32_e32 v248, v248, v248
	v_max_f32_e32 v249, v249, v249
	v_max_f32_e32 v250, v250, v250
	v_max_f32_e32 v251, v251, v251
	v_max_f32_e32 v248, 0x1e3ce508, v248
	v_max_f32_e32 v249, 0x1e3ce508, v249
	v_max_f32_e32 v250, 0x1e3ce508, v250
	v_max_f32_e32 v251, 0x1e3ce508, v251
	v_pk_mul_f32 v[20:21], v[20:21], v[248:249]
	v_pk_mul_f32 v[22:23], v[22:23], v[250:251]
	v_lshlrev_b32_e32 v248, 16, v224
	v_and_b32_e32 v249, 0xffff0000, v224
	v_lshlrev_b32_e32 v250, 16, v225
	v_and_b32_e32 v251, 0xffff0000, v225
	v_max_f32_e32 v248, v248, v248
	v_max_f32_e32 v249, v249, v249
	v_max_f32_e32 v250, v250, v250
	v_max_f32_e32 v251, v251, v251
	v_max_f32_e32 v248, 0x1e3ce508, v248
	v_max_f32_e32 v249, 0x1e3ce508, v249
	v_max_f32_e32 v250, 0x1e3ce508, v250
	v_max_f32_e32 v251, 0x1e3ce508, v251
	v_pk_mul_f32 v[16:17], v[16:17], v[248:249]
	v_pk_mul_f32 v[18:19], v[18:19], v[250:251]
	v_cvt_pk_bf16_f32 v222, v20, v21
	v_cvt_pk_bf16_f32 v223, v22, v23
	v_cvt_pk_bf16_f32 v224, v16, v17
	v_cvt_pk_bf16_f32 v225, v18, v19
	global_store_dwordx4 v[162:163], v[222:225], off offset:256
	v_lshl_add_u64 v[162:163], v[162:163], 0, s[4:5]
	s_waitcnt vmcnt(15)
	v_lshlrev_b32_e32 v248, 16, v226
	v_and_b32_e32 v249, 0xffff0000, v226
	v_lshlrev_b32_e32 v250, 16, v227
	v_and_b32_e32 v251, 0xffff0000, v227
	v_max_f32_e32 v248, v248, v248
	v_max_f32_e32 v249, v249, v249
	v_max_f32_e32 v250, v250, v250
	v_max_f32_e32 v251, v251, v251
	v_max_f32_e32 v248, 0x1e3ce508, v248
	v_max_f32_e32 v249, 0x1e3ce508, v249
	v_max_f32_e32 v250, 0x1e3ce508, v250
	v_max_f32_e32 v251, 0x1e3ce508, v251
	v_pk_mul_f32 v[12:13], v[12:13], v[248:249]
	v_pk_mul_f32 v[14:15], v[14:15], v[250:251]
	v_lshlrev_b32_e32 v248, 16, v228
	v_and_b32_e32 v249, 0xffff0000, v228
	v_lshlrev_b32_e32 v250, 16, v229
	v_and_b32_e32 v251, 0xffff0000, v229
	v_max_f32_e32 v248, v248, v248
	v_max_f32_e32 v249, v249, v249
	v_max_f32_e32 v250, v250, v250
	v_max_f32_e32 v251, v251, v251
	v_max_f32_e32 v248, 0x1e3ce508, v248
	v_max_f32_e32 v249, 0x1e3ce508, v249
	v_max_f32_e32 v250, 0x1e3ce508, v250
	v_max_f32_e32 v251, 0x1e3ce508, v251
	v_pk_mul_f32 v[8:9], v[8:9], v[248:249]
	v_pk_mul_f32 v[10:11], v[10:11], v[250:251]
	v_cvt_pk_bf16_f32 v226, v12, v13
	v_cvt_pk_bf16_f32 v227, v14, v15
	v_cvt_pk_bf16_f32 v228, v8, v9
	v_cvt_pk_bf16_f32 v229, v10, v11
	global_store_dwordx4 v[162:163], v[226:229], off
	s_waitcnt vmcnt(15)
	v_lshlrev_b32_e32 v248, 16, v230
	v_and_b32_e32 v249, 0xffff0000, v230
	v_lshlrev_b32_e32 v250, 16, v231
	v_and_b32_e32 v251, 0xffff0000, v231
	v_max_f32_e32 v248, v248, v248
	v_max_f32_e32 v249, v249, v249
	v_max_f32_e32 v250, v250, v250
	v_max_f32_e32 v251, v251, v251
	v_max_f32_e32 v248, 0x1e3ce508, v248
	v_max_f32_e32 v249, 0x1e3ce508, v249
	v_max_f32_e32 v250, 0x1e3ce508, v250
	v_max_f32_e32 v251, 0x1e3ce508, v251
	v_pk_mul_f32 v[4:5], v[4:5], v[248:249]
	v_pk_mul_f32 v[6:7], v[6:7], v[250:251]
	v_lshlrev_b32_e32 v248, 16, v232
	v_and_b32_e32 v249, 0xffff0000, v232
	v_lshlrev_b32_e32 v250, 16, v233
	v_and_b32_e32 v251, 0xffff0000, v233
	v_max_f32_e32 v248, v248, v248
	v_max_f32_e32 v249, v249, v249
	v_max_f32_e32 v250, v250, v250
	v_max_f32_e32 v251, v251, v251
	v_max_f32_e32 v248, 0x1e3ce508, v248
	v_max_f32_e32 v249, 0x1e3ce508, v249
	v_max_f32_e32 v250, 0x1e3ce508, v250
	v_max_f32_e32 v251, 0x1e3ce508, v251
	v_pk_mul_f32 v[0:1], v[0:1], v[248:249]
	v_pk_mul_f32 v[2:3], v[2:3], v[250:251]
	v_cvt_pk_bf16_f32 v230, v4, v5
	v_cvt_pk_bf16_f32 v231, v6, v7
	v_cvt_pk_bf16_f32 v232, v0, v1
	v_cvt_pk_bf16_f32 v233, v2, v3
	global_store_dwordx4 v[162:163], v[230:233], off offset:256
	s_andn2_b64 vcc, exec, s[56:57]
	s_mov_b64 s[0:1], -1
	s_cbranch_vccnz .LBB0_742
	s_andn2_b64 vcc, exec, s[38:39]
	s_cbranch_vccnz .LBB0_741
	s_barrier
	s_branch .LBB0_741

; __device__ __forceinline__ float fast_rcp(float x) { return __builtin_amdgcn_rcpf(x); }
;     __device__ __forceinline__ void mid(f32x4 (&acc)[2][2][4][2], const Unit& u, int wr, int wc, int fr, int fq, int t) const {
;         int fr_ = fr; asm volatile("" : "+v"(fr_));
;         const int row0 = u.pm * 256 + wr * 64 + fr_, col0 = u.pn * 256 + wc * 32 + 8 * fq, noff = C_GATE + (t == 8 ? 0 : 2048);
; #pragma unroll
;         for (int ai = 0; ai < 2; ++ai)
; #pragma unroll
;             for (int m = 0; m < 4; ++m) {
;                 const bf16_t* gp = P + (size_t)(row0 + ai * 128 + m * 16) * PS + noff + col0;
; #pragma unroll
;                 for (int bj = 0; bj < 2; ++bj) {
;                     const u32x4 gn = *(const u32x4*)(gp + bj * 128), gd = *(const u32x4*)(gp + bj * 128 + 2048);
;                     f32x4 r0, r1;
;                     r0[0] = bflo(gn.x) * fast_rcp(fmaxf(bflo(gd.x), 1e-20f)); r0[1] = bfhi(gn.x) * fast_rcp(fmaxf(bfhi(gd.x), 1e-20f));
;                     r0[2] = bflo(gn.y) * fast_rcp(fmaxf(bflo(gd.y), 1e-20f)); r0[3] = bfhi(gn.y) * fast_rcp(fmaxf(bfhi(gd.y), 1e-20f));
;                     r1[0] = bflo(gn.z) * fast_rcp(fmaxf(bflo(gd.z), 1e-20f)); r1[1] = bfhi(gn.z) * fast_rcp(fmaxf(bfhi(gd.z), 1e-20f));
;                     r1[2] = bflo(gn.w) * fast_rcp(fmaxf(bflo(gd.w), 1e-20f)); r1[3] = bfhi(gn.w) * fast_rcp(fmaxf(bfhi(gd.w), 1e-20f));
;                     acc[ai][bj][m][0] *= r0; acc[ai][bj][m][1] *= r1;
.LBB0_788:
	s_andn2_b64 vcc, exec, s[6:7]
	s_cbranch_vccnz .LBB0_790
	v_add_u32_e32 v34, s68, v173
	s_cmp_eq_u32 s12, 8
	v_mov_b64_e32 v[36:37], s[40:41]
	s_cselect_b32 s24, s20, 0x4000
	v_mad_i64_i32 v[36:37], vcc, v34, s90, v[36:37]
	s_mov_b32 s5, 0
	v_lshl_add_u64 v[36:37], v[36:37], 0, s[24:25]
	s_movk_i32 s4, 0x800
	v_lshl_add_u64 v[36:37], v[36:37], 0, v[164:165]
	v_lshl_add_u64 v[36:37], v[36:37], 0, s[4:5]
	s_mov_b32 s4, 0x60000
	global_load_dwordx4 v[134:137], v[36:37], off offset:-2048
	global_load_dwordx4 v[138:141], v[36:37], off offset:2048
	global_load_dwordx4 v[178:181], v[36:37], off offset:-1792
	global_load_dwordx4 v[182:185], v[36:37], off offset:2304
	v_lshl_add_u64 v[36:37], v[36:37], 0, s[4:5]
	global_load_dwordx4 v[186:189], v[36:37], off offset:-2048
	global_load_dwordx4 v[190:193], v[36:37], off offset:2048
	global_load_dwordx4 v[194:197], v[36:37], off offset:-1792
	global_load_dwordx4 v[198:201], v[36:37], off offset:2304
	v_lshl_add_u64 v[36:37], v[36:37], 0, s[4:5]
	global_load_dwordx4 v[202:205], v[36:37], off offset:-2048
	global_load_dwordx4 v[206:209], v[36:37], off offset:2048
	global_load_dwordx4 v[210:213], v[36:37], off offset:-1792
	global_load_dwordx4 v[214:217], v[36:37], off offset:2304
	v_lshl_add_u64 v[36:37], v[36:37], 0, s[4:5]
	global_load_dwordx4 v[218:221], v[36:37], off offset:-2048
	global_load_dwordx4 v[222:225], v[36:37], off offset:2048
	global_load_dwordx4 v[226:229], v[36:37], off offset:-1792
	global_load_dwordx4 v[230:233], v[36:37], off offset:2304
	v_lshl_add_u64 v[36:37], v[36:37], 0, s[4:5]
	s_mov_b32 s4, 0x180000
	v_lshl_add_u64 v[36:37], v[36:37], 0, s[4:5]
	s_mov_b32 s4, 0x60000
	s_waitcnt vmcnt(14)
	v_lshlrev_b32_e32 v248, 16, v138
	v_and_b32_e32 v249, 0xffff0000, v138
	v_lshlrev_b32_e32 v250, 16, v139
	v_and_b32_e32 v251, 0xffff0000, v139
	v_max_f32_e32 v248, v248, v248
	v_max_f32_e32 v249, v249, v249
	v_max_f32_e32 v250, v250, v250
	v_max_f32_e32 v251, v251, v251
	v_max_f32_e32 v248, 0x1e3ce508, v248
	v_max_f32_e32 v249, 0x1e3ce508, v249
	v_max_f32_e32 v250, 0x1e3ce508, v250
	v_max_f32_e32 v251, 0x1e3ce508, v251
	v_rcp_f32_e32 v248, v248
	v_rcp_f32_e32 v249, v249
	v_rcp_f32_e32 v250, v250
	v_rcp_f32_e32 v251, v251
	v_lshlrev_b32_e32 v252, 16, v134
	v_and_b32_e32 v253, 0xffff0000, v134
	v_lshlrev_b32_e32 v254, 16, v135
	v_and_b32_e32 v255, 0xffff0000, v135
	v_pk_mul_f32 v[248:249], v[248:249], v[252:253]
	v_pk_mul_f32 v[250:251], v[250:251], v[254:255]
	v_pk_mul_f32 v[130:131], v[130:131], v[248:249]
	v_pk_mul_f32 v[132:133], v[132:133], v[250:251]
	v_lshlrev_b32_e32 v248, 16, v140
	v_and_b32_e32 v249, 0xffff0000, v140
	v_lshlrev_b32_e32 v250, 16, v141
	v_and_b32_e32 v251, 0xffff0000, v141
	v_max_f32_e32 v248, v248, v248
	v_max_f32_e32 v249, v249, v249
	v_max_f32_e32 v250, v250, v250
	v_max_f32_e32 v251, v251, v251
	v_max_f32_e32 v248, 0x1e3ce508, v248
	v_max_f32_e32 v249, 0x1e3ce508, v249
	v_max_f32_e32 v250, 0x1e3ce508, v250
	v_max_f32_e32 v251, 0x1e3ce508, v251
	v_rcp_f32_e32 v248, v248
	v_rcp_f32_e32 v249, v249
	v_rcp_f32_e32 v250, v250
	v_rcp_f32_e32 v251, v251
	v_lshlrev_b32_e32 v252, 16, v136
	v_and_b32_e32 v253, 0xffff0000, v136
	v_lshlrev_b32_e32 v254, 16, v137
	v_and_b32_e32 v255, 0xffff0000, v137
	v_pk_mul_f32 v[248:249], v[248:249], v[252:253]
	v_pk_mul_f32 v[250:251], v[250:251], v[254:255]
	v_pk_mul_f32 v[126:127], v[126:127], v[248:249]
	v_pk_mul_f32 v[128:129], v[128:129], v[250:251]
	global_load_dwordx4 v[134:137], v[36:37], off offset:-2048
	global_load_dwordx4 v[138:141], v[36:37], off offset:2048
	s_waitcnt vmcnt(14)
	v_lshlrev_b32_e32 v248, 16, v182
	v_and_b32_e32 v249, 0xffff0000, v182
	v_lshlrev_b32_e32 v250, 16, v183
	v_and_b32_e32 v251, 0xffff0000, v183
	v_max_f32_e32 v248, v248, v248
	v_max_f32_e32 v249, v249, v249
	v_max_f32_e32 v250, v250, v250
	v_max_f32_e32 v251, v251, v251
	v_max_f32_e32 v248, 0x1e3ce508, v248
	v_max_f32_e32 v249, 0x1e3ce508, v249
	v_max_f32_e32 v250, 0x1e3ce508, v250
	v_max_f32_e32 v251, 0x1e3ce508, v251
	v_rcp_f32_e32 v248, v248
	v_rcp_f32_e32 v249, v249
	v_rcp_f32_e32 v250, v250
	v_rcp_f32_e32 v251, v251
	v_lshlrev_b32_e32 v252, 16, v178
	v_and_b32_e32 v253, 0xffff0000, v178
	v_lshlrev_b32_e32 v254, 16, v179
	v_and_b32_e32 v255, 0xffff0000, v179
	v_pk_mul_f32 v[248:249], v[248:249], v[252:253]
	v_pk_mul_f32 v[250:251], v[250:251], v[254:255]
	v_pk_mul_f32 v[122:123], v[122:123], v[248:249]
	v_pk_mul_f32 v[124:125], v[124:125], v[250:251]
	v_lshlrev_b32_e32 v248, 16, v184
	v_and_b32_e32 v249, 0xffff0000, v184
	v_lshlrev_b32_e32 v250, 16, v185
	v_and_b32_e32 v251, 0xffff0000, v185
	v_max_f32_e32 v248, v248, v248
	v_max_f32_e32 v249, v249, v249
	v_max_f32_e32 v250, v250, v250
	v_max_f32_e32 v251, v251, v251
	v_max_f32_e32 v248, 0x1e3ce508, v248
	v_max_f32_e32 v249, 0x1e3ce508, v249
	v_max_f32_e32 v250, 0x1e3ce508, v250
	v_max_f32_e32 v251, 0x1e3ce508, v251
	v_rcp_f32_e32 v248, v248
	v_rcp_f32_e32 v249, v249
	v_rcp_f32_e32 v250, v250
	v_rcp_f32_e32 v251, v251
	v_lshlrev_b32_e32 v252, 16, v180
	v_and_b32_e32 v253, 0xffff0000, v180
	v_lshlrev_b32_e32 v254, 16, v181
	v_and_b32_e32 v255, 0xffff0000, v181
	v_pk_mul_f32 v[248:249], v[248:249], v[252:253]
	v_pk_mul_f32 v[250:251], v[250:251], v[254:255]
	v_pk_mul_f32 v[118:119], v[118:119], v[248:249]
	v_pk_mul_f32 v[120:121], v[120:121], v[250:251]
	global_load_dwordx4 v[178:181], v[36:37], off offset:-1792
	global_load_dwordx4 v[182:185], v[36:37], off offset:2304
	v_lshl_add_u64 v[36:37], v[36:37], 0, s[4:5]
	s_waitcnt vmcnt(14)
; __device__ __forceinline__ float fast_rcp(float x) { return __builtin_amdgcn_rcpf(x); }
;     __device__ __forceinline__ void mid(f32x4 (&acc)[2][2][4][2], const Unit& u, int wr, int wc, int fr, int fq, int t) const {
;     ...
;                     const u32x4 gn = *(const u32x4*)(gp + bj * 128), gd = *(const u32x4*)(gp + bj * 128 + 2048);
;                     f32x4 r0, r1;
;                     r0[0] = bflo(gn.x) * fast_rcp(fmaxf(bflo(gd.x), 1e-20f)); r0[1] = bfhi(gn.x) * fast_rcp(fmaxf(bfhi(gd.x), 1e-20f));
;                     r0[2] = bflo(gn.y) * fast_rcp(fmaxf(bflo(gd.y), 1e-20f)); r0[3] = bfhi(gn.y) * fast_rcp(fmaxf(bfhi(gd.y), 1e-20f));
;                     r1[0] = bflo(gn.z) * fast_rcp(fmaxf(bflo(gd.z), 1e-20f)); r1[1] = bfhi(gn.z) * fast_rcp(fmaxf(bfhi(gd.z), 1e-20f));
;                     r1[2] = bflo(gn.w) * fast_rcp(fmaxf(bflo(gd.w), 1e-20f)); r1[3] = bfhi(gn.w) * fast_rcp(fmaxf(bfhi(gd.w), 1e-20f));
;                     acc[ai][bj][m][0] *= r0; acc[ai][bj][m][1] *= r1;
	v_lshlrev_b32_e32 v248, 16, v190
	v_and_b32_e32 v249, 0xffff0000, v190
	v_lshlrev_b32_e32 v250, 16, v191
	v_and_b32_e32 v251, 0xffff0000, v191
	v_max_f32_e32 v248, v248, v248
	v_max_f32_e32 v249, v249, v249
	v_max_f32_e32 v250, v250, v250
	v_max_f32_e32 v251, v251, v251
	v_max_f32_e32 v248, 0x1e3ce508, v248
	v_max_f32_e32 v249, 0x1e3ce508, v249
	v_max_f32_e32 v250, 0x1e3ce508, v250
	v_max_f32_e32 v251, 0x1e3ce508, v251
	v_rcp_f32_e32 v248, v248
	v_rcp_f32_e32 v249, v249
	v_rcp_f32_e32 v250, v250
	v_rcp_f32_e32 v251, v251
	v_lshlrev_b32_e32 v252, 16, v186
	v_and_b32_e32 v253, 0xffff0000, v186
	v_lshlrev_b32_e32 v254, 16, v187
	v_and_b32_e32 v255, 0xffff0000, v187
	v_pk_mul_f32 v[248:249], v[248:249], v[252:253]
	v_pk_mul_f32 v[250:251], v[250:251], v[254:255]
	v_pk_mul_f32 v[114:115], v[114:115], v[248:249]
	v_pk_mul_f32 v[116:117], v[116:117], v[250:251]
	v_lshlrev_b32_e32 v248, 16, v192
	v_and_b32_e32 v249, 0xffff0000, v192
	v_lshlrev_b32_e32 v250, 16, v193
	v_and_b32_e32 v251, 0xffff0000, v193
	v_max_f32_e32 v248, v248, v248
	v_max_f32_e32 v249, v249, v249
	v_max_f32_e32 v250, v250, v250
	v_max_f32_e32 v251, v251, v251
	v_max_f32_e32 v248, 0x1e3ce508, v248
	v_max_f32_e32 v249, 0x1e3ce508, v249
	v_max_f32_e32 v250, 0x1e3ce508, v250
	v_max_f32_e32 v251, 0x1e3ce508, v251
	v_rcp_f32_e32 v248, v248
	v_rcp_f32_e32 v249, v249
	v_rcp_f32_e32 v250, v250
	v_rcp_f32_e32 v251, v251
	v_lshlrev_b32_e32 v252, 16, v188
	v_and_b32_e32 v253, 0xffff0000, v188
	v_lshlrev_b32_e32 v254, 16, v189
	v_and_b32_e32 v255, 0xffff0000, v189
	v_pk_mul_f32 v[248:249], v[248:249], v[252:253]
	v_pk_mul_f32 v[250:251], v[250:251], v[254:255]
	v_pk_mul_f32 v[110:111], v[110:111], v[248:249]
	v_pk_mul_f32 v[112:113], v[112:113], v[250:251]
	global_load_dwordx4 v[186:189], v[36:37], off offset:-2048
	global_load_dwordx4 v[190:193], v[36:37], off offset:2048
	s_waitcnt vmcnt(14)
	v_lshlrev_b32_e32 v248, 16, v198
	v_and_b32_e32 v249, 0xffff0000, v198
	v_lshlrev_b32_e32 v250, 16, v199
	v_and_b32_e32 v251, 0xffff0000, v199
	v_max_f32_e32 v248, v248, v248
	v_max_f32_e32 v249, v249, v249
	v_max_f32_e32 v250, v250, v250
	v_max_f32_e32 v251, v251, v251
	v_max_f32_e32 v248, 0x1e3ce508, v248
	v_max_f32_e32 v249, 0x1e3ce508, v249
	v_max_f32_e32 v250, 0x1e3ce508, v250
	v_max_f32_e32 v251, 0x1e3ce508, v251
	v_rcp_f32_e32 v248, v248
	v_rcp_f32_e32 v249, v249
	v_rcp_f32_e32 v250, v250
	v_rcp_f32_e32 v251, v251
	v_lshlrev_b32_e32 v252, 16, v194
	v_and_b32_e32 v253, 0xffff0000, v194
	v_lshlrev_b32_e32 v254, 16, v195
	v_and_b32_e32 v255, 0xffff0000, v195
	v_pk_mul_f32 v[248:249], v[248:249], v[252:253]
	v_pk_mul_f32 v[250:251], v[250:251], v[254:255]
	v_pk_mul_f32 v[106:107], v[106:107], v[248:249]
	v_pk_mul_f32 v[108:109], v[108:109], v[250:251]
	v_lshlrev_b32_e32 v248, 16, v200
	v_and_b32_e32 v249, 0xffff0000, v200
	v_lshlrev_b32_e32 v250, 16, v201
	v_and_b32_e32 v251, 0xffff0000, v201
	v_max_f32_e32 v248, v248, v248
	v_max_f32_e32 v249, v249, v249
	v_max_f32_e32 v250, v250, v250
	v_max_f32_e32 v251, v251, v251
	v_max_f32_e32 v248, 0x1e3ce508, v248
	v_max_f32_e32 v249, 0x1e3ce508, v249
	v_max_f32_e32 v250, 0x1e3ce508, v250
	v_max_f32_e32 v251, 0x1e3ce508, v251
	v_rcp_f32_e32 v248, v248
	v_rcp_f32_e32 v249, v249
	v_rcp_f32_e32 v250, v250
	v_rcp_f32_e32 v251, v251
	v_lshlrev_b32_e32 v252, 16, v196
	v_and_b32_e32 v253, 0xffff0000, v196
	v_lshlrev_b32_e32 v254, 16, v197
	v_and_b32_e32 v255, 0xffff0000, v197
	v_pk_mul_f32 v[248:249], v[248:249], v[252:253]
	v_pk_mul_f32 v[250:251], v[250:251], v[254:255]
	v_pk_mul_f32 v[102:103], v[102:103], v[248:249]
	v_pk_mul_f32 v[104:105], v[104:105], v[250:251]
	global_load_dwordx4 v[194:197], v[36:37], off offset:-1792
	global_load_dwordx4 v[198:201], v[36:37], off offset:2304
	v_lshl_add_u64 v[36:37], v[36:37], 0, s[4:5]
	s_waitcnt vmcnt(14)
	v_lshlrev_b32_e32 v248, 16, v206
	v_and_b32_e32 v249, 0xffff0000, v206
	v_lshlrev_b32_e32 v250, 16, v207
	v_and_b32_e32 v251, 0xffff0000, v207
	v_max_f32_e32 v248, v248, v248
	v_max_f32_e32 v249, v249, v249
	v_max_f32_e32 v250, v250, v250
	v_max_f32_e32 v251, v251, v251
	v_max_f32_e32 v248, 0x1e3ce508, v248
	v_max_f32_e32 v249, 0x1e3ce508, v249
	v_max_f32_e32 v250, 0x1e3ce508, v250
	v_max_f32_e32 v251, 0x1e3ce508, v251
	v_rcp_f32_e32 v248, v248
	v_rcp_f32_e32 v249, v249
	v_rcp_f32_e32 v250, v250
	v_rcp_f32_e32 v251, v251
	v_lshlrev_b32_e32 v252, 16, v202
	v_and_b32_e32 v253, 0xffff0000, v202
	v_lshlrev_b32_e32 v254, 16, v203
	v_and_b32_e32 v255, 0xffff0000, v203
	v_pk_mul_f32 v[248:249], v[248:249], v[252:253]
	v_pk_mul_f32 v[250:251], v[250:251], v[254:255]
	v_pk_mul_f32 v[98:99], v[98:99], v[248:249]
	v_pk_mul_f32 v[100:101], v[100:101], v[250:251]
	v_lshlrev_b32_e32 v248, 16, v208
	v_and_b32_e32 v249, 0xffff0000, v208
	v_lshlrev_b32_e32 v250, 16, v209
	v_and_b32_e32 v251, 0xffff0000, v209
	v_max_f32_e32 v248, v248, v248
	v_max_f32_e32 v249, v249, v249
	v_max_f32_e32 v250, v250, v250
	v_max_f32_e32 v251, v251, v251
	v_max_f32_e32 v248, 0x1e3ce508, v248
	v_max_f32_e32 v249, 0x1e3ce508, v249
	v_max_f32_e32 v250, 0x1e3ce508, v250
	v_max_f32_e32 v251, 0x1e3ce508, v251
	v_rcp_f32_e32 v248, v248
	v_rcp_f32_e32 v249, v249
	v_rcp_f32_e32 v250, v250
	v_rcp_f32_e32 v251, v251
	v_lshlrev_b32_e32 v252, 16, v204
	v_and_b32_e32 v253, 0xffff0000, v204
	v_lshlrev_b32_e32 v254, 16, v205
	v_and_b32_e32 v255, 0xffff0000, v205
	v_pk_mul_f32 v[248:249], v[248:249], v[252:253]
	v_pk_mul_f32 v[250:251], v[250:251], v[254:255]
	v_pk_mul_f32 v[94:95], v[94:95], v[248:249]
	v_pk_mul_f32 v[96:97], v[96:97], v[250:251]
	global_load_dwordx4 v[202:205], v[36:37], off offset:-2048
	global_load_dwordx4 v[206:209], v[36:37], off offset:2048
	s_waitcnt vmcnt(14)
; __device__ __forceinline__ float fast_rcp(float x) { return __builtin_amdgcn_rcpf(x); }
;     __device__ __forceinline__ void mid(f32x4 (&acc)[2][2][4][2], const Unit& u, int wr, int wc, int fr, int fq, int t) const {
;     ...
;                     const u32x4 gn = *(const u32x4*)(gp + bj * 128), gd = *(const u32x4*)(gp + bj * 128 + 2048);
;                     f32x4 r0, r1;
;                     r0[0] = bflo(gn.x) * fast_rcp(fmaxf(bflo(gd.x), 1e-20f)); r0[1] = bfhi(gn.x) * fast_rcp(fmaxf(bfhi(gd.x), 1e-20f));
;                     r0[2] = bflo(gn.y) * fast_rcp(fmaxf(bflo(gd.y), 1e-20f)); r0[3] = bfhi(gn.y) * fast_rcp(fmaxf(bfhi(gd.y), 1e-20f));
;                     r1[0] = bflo(gn.z) * fast_rcp(fmaxf(bflo(gd.z), 1e-20f)); r1[1] = bfhi(gn.z) * fast_rcp(fmaxf(bfhi(gd.z), 1e-20f));
;                     r1[2] = bflo(gn.w) * fast_rcp(fmaxf(bflo(gd.w), 1e-20f)); r1[3] = bfhi(gn.w) * fast_rcp(fmaxf(bfhi(gd.w), 1e-20f));
;                     acc[ai][bj][m][0] *= r0; acc[ai][bj][m][1] *= r1;
	v_lshlrev_b32_e32 v248, 16, v214
	v_and_b32_e32 v249, 0xffff0000, v214
	v_lshlrev_b32_e32 v250, 16, v215
	v_and_b32_e32 v251, 0xffff0000, v215
	v_max_f32_e32 v248, v248, v248
	v_max_f32_e32 v249, v249, v249
	v_max_f32_e32 v250, v250, v250
	v_max_f32_e32 v251, v251, v251
	v_max_f32_e32 v248, 0x1e3ce508, v248
	v_max_f32_e32 v249, 0x1e3ce508, v249
	v_max_f32_e32 v250, 0x1e3ce508, v250
	v_max_f32_e32 v251, 0x1e3ce508, v251
	v_rcp_f32_e32 v248, v248
	v_rcp_f32_e32 v249, v249
	v_rcp_f32_e32 v250, v250
	v_rcp_f32_e32 v251, v251
	v_lshlrev_b32_e32 v252, 16, v210
	v_and_b32_e32 v253, 0xffff0000, v210
	v_lshlrev_b32_e32 v254, 16, v211
	v_and_b32_e32 v255, 0xffff0000, v211
	v_pk_mul_f32 v[248:249], v[248:249], v[252:253]
	v_pk_mul_f32 v[250:251], v[250:251], v[254:255]
	v_pk_mul_f32 v[90:91], v[90:91], v[248:249]
	v_pk_mul_f32 v[92:93], v[92:93], v[250:251]
	v_lshlrev_b32_e32 v248, 16, v216
	v_and_b32_e32 v249, 0xffff0000, v216
	v_lshlrev_b32_e32 v250, 16, v217
	v_and_b32_e32 v251, 0xffff0000, v217
	v_max_f32_e32 v248, v248, v248
	v_max_f32_e32 v249, v249, v249
	v_max_f32_e32 v250, v250, v250
	v_max_f32_e32 v251, v251, v251
	v_max_f32_e32 v248, 0x1e3ce508, v248
	v_max_f32_e32 v249, 0x1e3ce508, v249
	v_max_f32_e32 v250, 0x1e3ce508, v250
	v_max_f32_e32 v251, 0x1e3ce508, v251
	v_rcp_f32_e32 v248, v248
	v_rcp_f32_e32 v249, v249
	v_rcp_f32_e32 v250, v250
	v_rcp_f32_e32 v251, v251
	v_lshlrev_b32_e32 v252, 16, v212
	v_and_b32_e32 v253, 0xffff0000, v212
	v_lshlrev_b32_e32 v254, 16, v213
	v_and_b32_e32 v255, 0xffff0000, v213
	v_pk_mul_f32 v[248:249], v[248:249], v[252:253]
	v_pk_mul_f32 v[250:251], v[250:251], v[254:255]
	v_pk_mul_f32 v[86:87], v[86:87], v[248:249]
	v_pk_mul_f32 v[88:89], v[88:89], v[250:251]
	global_load_dwordx4 v[210:213], v[36:37], off offset:-1792
	global_load_dwordx4 v[214:217], v[36:37], off offset:2304
	v_lshl_add_u64 v[36:37], v[36:37], 0, s[4:5]
	s_waitcnt vmcnt(14)
	v_lshlrev_b32_e32 v248, 16, v222
	v_and_b32_e32 v249, 0xffff0000, v222
	v_lshlrev_b32_e32 v250, 16, v223
	v_and_b32_e32 v251, 0xffff0000, v223
	v_max_f32_e32 v248, v248, v248
	v_max_f32_e32 v249, v249, v249
	v_max_f32_e32 v250, v250, v250
	v_max_f32_e32 v251, v251, v251
	v_max_f32_e32 v248, 0x1e3ce508, v248
	v_max_f32_e32 v249, 0x1e3ce508, v249
	v_max_f32_e32 v250, 0x1e3ce508, v250
	v_max_f32_e32 v251, 0x1e3ce508, v251
	v_rcp_f32_e32 v248, v248
	v_rcp_f32_e32 v249, v249
	v_rcp_f32_e32 v250, v250
	v_rcp_f32_e32 v251, v251
	v_lshlrev_b32_e32 v252, 16, v218
	v_and_b32_e32 v253, 0xffff0000, v218
	v_lshlrev_b32_e32 v254, 16, v219
	v_and_b32_e32 v255, 0xffff0000, v219
	v_pk_mul_f32 v[248:249], v[248:249], v[252:253]
	v_pk_mul_f32 v[250:251], v[250:251], v[254:255]
	v_pk_mul_f32 v[82:83], v[82:83], v[248:249]
	v_pk_mul_f32 v[84:85], v[84:85], v[250:251]
	v_lshlrev_b32_e32 v248, 16, v224
	v_and_b32_e32 v249, 0xffff0000, v224
	v_lshlrev_b32_e32 v250, 16, v225
	v_and_b32_e32 v251, 0xffff0000, v225
	v_max_f32_e32 v248, v248, v248
	v_max_f32_e32 v249, v249, v249
	v_max_f32_e32 v250, v250, v250
	v_max_f32_e32 v251, v251, v251
	v_max_f32_e32 v248, 0x1e3ce508, v248
	v_max_f32_e32 v249, 0x1e3ce508, v249
	v_max_f32_e32 v250, 0x1e3ce508, v250
	v_max_f32_e32 v251, 0x1e3ce508, v251
	v_rcp_f32_e32 v248, v248
	v_rcp_f32_e32 v249, v249
	v_rcp_f32_e32 v250, v250
	v_rcp_f32_e32 v251, v251
	v_lshlrev_b32_e32 v252, 16, v220
	v_and_b32_e32 v253, 0xffff0000, v220
	v_lshlrev_b32_e32 v254, 16, v221
	v_and_b32_e32 v255, 0xffff0000, v221
	v_pk_mul_f32 v[248:249], v[248:249], v[252:253]
	v_pk_mul_f32 v[250:251], v[250:251], v[254:255]
	v_pk_mul_f32 v[78:79], v[78:79], v[248:249]
	v_pk_mul_f32 v[80:81], v[80:81], v[250:251]
	global_load_dwordx4 v[218:221], v[36:37], off offset:-2048
	global_load_dwordx4 v[222:225], v[36:37], off offset:2048
	s_waitcnt vmcnt(14)
	v_lshlrev_b32_e32 v248, 16, v230
	v_and_b32_e32 v249, 0xffff0000, v230
	v_lshlrev_b32_e32 v250, 16, v231
	v_and_b32_e32 v251, 0xffff0000, v231
	v_max_f32_e32 v248, v248, v248
	v_max_f32_e32 v249, v249, v249
	v_max_f32_e32 v250, v250, v250
	v_max_f32_e32 v251, v251, v251
	v_max_f32_e32 v248, 0x1e3ce508, v248
	v_max_f32_e32 v249, 0x1e3ce508, v249
	v_max_f32_e32 v250, 0x1e3ce508, v250
	v_max_f32_e32 v251, 0x1e3ce508, v251
	v_rcp_f32_e32 v248, v248
	v_rcp_f32_e32 v249, v249
	v_rcp_f32_e32 v250, v250
	v_rcp_f32_e32 v251, v251
	v_lshlrev_b32_e32 v252, 16, v226
	v_and_b32_e32 v253, 0xffff0000, v226
	v_lshlrev_b32_e32 v254, 16, v227
	v_and_b32_e32 v255, 0xffff0000, v227
	v_pk_mul_f32 v[248:249], v[248:249], v[252:253]
	v_pk_mul_f32 v[250:251], v[250:251], v[254:255]
	v_pk_mul_f32 v[74:75], v[74:75], v[248:249]
	v_pk_mul_f32 v[76:77], v[76:77], v[250:251]
	v_lshlrev_b32_e32 v248, 16, v232
	v_and_b32_e32 v249, 0xffff0000, v232
	v_lshlrev_b32_e32 v250, 16, v233
	v_and_b32_e32 v251, 0xffff0000, v233
	v_max_f32_e32 v248, v248, v248
	v_max_f32_e32 v249, v249, v249
	v_max_f32_e32 v250, v250, v250
	v_max_f32_e32 v251, v251, v251
	v_max_f32_e32 v248, 0x1e3ce508, v248
	v_max_f32_e32 v249, 0x1e3ce508, v249
	v_max_f32_e32 v250, 0x1e3ce508, v250
	v_max_f32_e32 v251, 0x1e3ce508, v251
	v_rcp_f32_e32 v248, v248
	v_rcp_f32_e32 v249, v249
	v_rcp_f32_e32 v250, v250
	v_rcp_f32_e32 v251, v251
	v_lshlrev_b32_e32 v252, 16, v228
	v_and_b32_e32 v253, 0xffff0000, v228
	v_lshlrev_b32_e32 v254, 16, v229
	v_and_b32_e32 v255, 0xffff0000, v229
	v_pk_mul_f32 v[248:249], v[248:249], v[252:253]
	v_pk_mul_f32 v[250:251], v[250:251], v[254:255]
	v_pk_mul_f32 v[70:71], v[70:71], v[248:249]
	v_pk_mul_f32 v[72:73], v[72:73], v[250:251]
	global_load_dwordx4 v[226:229], v[36:37], off offset:-1792
	global_load_dwordx4 v[230:233], v[36:37], off offset:2304
	v_lshl_add_u64 v[36:37], v[36:37], 0, s[4:5]
	s_waitcnt vmcnt(14)
; __device__ __forceinline__ float fast_rcp(float x) { return __builtin_amdgcn_rcpf(x); }
;     __device__ __forceinline__ void mid(f32x4 (&acc)[2][2][4][2], const Unit& u, int wr, int wc, int fr, int fq, int t) const {
;     ...
;                     const u32x4 gn = *(const u32x4*)(gp + bj * 128), gd = *(const u32x4*)(gp + bj * 128 + 2048);
;                     f32x4 r0, r1;
;                     r0[0] = bflo(gn.x) * fast_rcp(fmaxf(bflo(gd.x), 1e-20f)); r0[1] = bfhi(gn.x) * fast_rcp(fmaxf(bfhi(gd.x), 1e-20f));
;                     r0[2] = bflo(gn.y) * fast_rcp(fmaxf(bflo(gd.y), 1e-20f)); r0[3] = bfhi(gn.y) * fast_rcp(fmaxf(bfhi(gd.y), 1e-20f));
;                     r1[0] = bflo(gn.z) * fast_rcp(fmaxf(bflo(gd.z), 1e-20f)); r1[1] = bfhi(gn.z) * fast_rcp(fmaxf(bfhi(gd.z), 1e-20f));
;                     r1[2] = bflo(gn.w) * fast_rcp(fmaxf(bflo(gd.w), 1e-20f)); r1[3] = bfhi(gn.w) * fast_rcp(fmaxf(bfhi(gd.w), 1e-20f));
;                     acc[ai][bj][m][0] *= r0; acc[ai][bj][m][1] *= r1;
	v_lshlrev_b32_e32 v248, 16, v138
	v_and_b32_e32 v249, 0xffff0000, v138
	v_lshlrev_b32_e32 v250, 16, v139
	v_and_b32_e32 v251, 0xffff0000, v139
	v_max_f32_e32 v248, v248, v248
	v_max_f32_e32 v249, v249, v249
	v_max_f32_e32 v250, v250, v250
	v_max_f32_e32 v251, v251, v251
	v_max_f32_e32 v248, 0x1e3ce508, v248
	v_max_f32_e32 v249, 0x1e3ce508, v249
	v_max_f32_e32 v250, 0x1e3ce508, v250
	v_max_f32_e32 v251, 0x1e3ce508, v251
	v_rcp_f32_e32 v248, v248
	v_rcp_f32_e32 v249, v249
	v_rcp_f32_e32 v250, v250
	v_rcp_f32_e32 v251, v251
	v_lshlrev_b32_e32 v252, 16, v134
	v_and_b32_e32 v253, 0xffff0000, v134
	v_lshlrev_b32_e32 v254, 16, v135
	v_and_b32_e32 v255, 0xffff0000, v135
	v_pk_mul_f32 v[248:249], v[248:249], v[252:253]
	v_pk_mul_f32 v[250:251], v[250:251], v[254:255]
	v_pk_mul_f32 v[66:67], v[66:67], v[248:249]
	v_pk_mul_f32 v[68:69], v[68:69], v[250:251]
	v_lshlrev_b32_e32 v248, 16, v140
	v_and_b32_e32 v249, 0xffff0000, v140
	v_lshlrev_b32_e32 v250, 16, v141
	v_and_b32_e32 v251, 0xffff0000, v141
	v_max_f32_e32 v248, v248, v248
	v_max_f32_e32 v249, v249, v249
	v_max_f32_e32 v250, v250, v250
	v_max_f32_e32 v251, v251, v251
	v_max_f32_e32 v248, 0x1e3ce508, v248
	v_max_f32_e32 v249, 0x1e3ce508, v249
	v_max_f32_e32 v250, 0x1e3ce508, v250
	v_max_f32_e32 v251, 0x1e3ce508, v251
	v_rcp_f32_e32 v248, v248
	v_rcp_f32_e32 v249, v249
	v_rcp_f32_e32 v250, v250
	v_rcp_f32_e32 v251, v251
	v_lshlrev_b32_e32 v252, 16, v136
	v_and_b32_e32 v253, 0xffff0000, v136
	v_lshlrev_b32_e32 v254, 16, v137
	v_and_b32_e32 v255, 0xffff0000, v137
	v_pk_mul_f32 v[248:249], v[248:249], v[252:253]
	v_pk_mul_f32 v[250:251], v[250:251], v[254:255]
	v_pk_mul_f32 v[62:63], v[62:63], v[248:249]
	v_pk_mul_f32 v[64:65], v[64:65], v[250:251]
	s_waitcnt vmcnt(12)
	v_lshlrev_b32_e32 v248, 16, v182
	v_and_b32_e32 v249, 0xffff0000, v182
	v_lshlrev_b32_e32 v250, 16, v183
	v_and_b32_e32 v251, 0xffff0000, v183
	v_max_f32_e32 v248, v248, v248
	v_max_f32_e32 v249, v249, v249
	v_max_f32_e32 v250, v250, v250
	v_max_f32_e32 v251, v251, v251
	v_max_f32_e32 v248, 0x1e3ce508, v248
	v_max_f32_e32 v249, 0x1e3ce508, v249
	v_max_f32_e32 v250, 0x1e3ce508, v250
	v_max_f32_e32 v251, 0x1e3ce508, v251
	v_rcp_f32_e32 v248, v248
	v_rcp_f32_e32 v249, v249
	v_rcp_f32_e32 v250, v250
	v_rcp_f32_e32 v251, v251
	v_lshlrev_b32_e32 v252, 16, v178
	v_and_b32_e32 v253, 0xffff0000, v178
	v_lshlrev_b32_e32 v254, 16, v179
	v_and_b32_e32 v255, 0xffff0000, v179
	v_pk_mul_f32 v[248:249], v[248:249], v[252:253]
	v_pk_mul_f32 v[250:251], v[250:251], v[254:255]
	v_pk_mul_f32 v[58:59], v[58:59], v[248:249]
	v_pk_mul_f32 v[60:61], v[60:61], v[250:251]
	v_lshlrev_b32_e32 v248, 16, v184
	v_and_b32_e32 v249, 0xffff0000, v184
	v_lshlrev_b32_e32 v250, 16, v185
	v_and_b32_e32 v251, 0xffff0000, v185
	v_max_f32_e32 v248, v248, v248
	v_max_f32_e32 v249, v249, v249
	v_max_f32_e32 v250, v250, v250
	v_max_f32_e32 v251, v251, v251
	v_max_f32_e32 v248, 0x1e3ce508, v248
	v_max_f32_e32 v249, 0x1e3ce508, v249
	v_max_f32_e32 v250, 0x1e3ce508, v250
	v_max_f32_e32 v251, 0x1e3ce508, v251
	v_rcp_f32_e32 v248, v248
	v_rcp_f32_e32 v249, v249
	v_rcp_f32_e32 v250, v250
	v_rcp_f32_e32 v251, v251
	v_lshlrev_b32_e32 v252, 16, v180
	v_and_b32_e32 v253, 0xffff0000, v180
	v_lshlrev_b32_e32 v254, 16, v181
	v_and_b32_e32 v255, 0xffff0000, v181
	v_pk_mul_f32 v[248:249], v[248:249], v[252:253]
	v_pk_mul_f32 v[250:251], v[250:251], v[254:255]
	v_pk_mul_f32 v[54:55], v[54:55], v[248:249]
	v_pk_mul_f32 v[56:57], v[56:57], v[250:251]
	s_waitcnt vmcnt(10)
	v_lshlrev_b32_e32 v248, 16, v190
	v_and_b32_e32 v249, 0xffff0000, v190
	v_lshlrev_b32_e32 v250, 16, v191
	v_and_b32_e32 v251, 0xffff0000, v191
	v_max_f32_e32 v248, v248, v248
	v_max_f32_e32 v249, v249, v249
	v_max_f32_e32 v250, v250, v250
	v_max_f32_e32 v251, v251, v251
	v_max_f32_e32 v248, 0x1e3ce508, v248
	v_max_f32_e32 v249, 0x1e3ce508, v249
	v_max_f32_e32 v250, 0x1e3ce508, v250
	v_max_f32_e32 v251, 0x1e3ce508, v251
	v_rcp_f32_e32 v248, v248
	v_rcp_f32_e32 v249, v249
	v_rcp_f32_e32 v250, v250
	v_rcp_f32_e32 v251, v251
	v_lshlrev_b32_e32 v252, 16, v186
	v_and_b32_e32 v253, 0xffff0000, v186
	v_lshlrev_b32_e32 v254, 16, v187
	v_and_b32_e32 v255, 0xffff0000, v187
	v_pk_mul_f32 v[248:249], v[248:249], v[252:253]
	v_pk_mul_f32 v[250:251], v[250:251], v[254:255]
	v_pk_mul_f32 v[50:51], v[50:51], v[248:249]
	v_pk_mul_f32 v[52:53], v[52:53], v[250:251]
	v_lshlrev_b32_e32 v248, 16, v192
	v_and_b32_e32 v249, 0xffff0000, v192
	v_lshlrev_b32_e32 v250, 16, v193
	v_and_b32_e32 v251, 0xffff0000, v193
	v_max_f32_e32 v248, v248, v248
	v_max_f32_e32 v249, v249, v249
	v_max_f32_e32 v250, v250, v250
	v_max_f32_e32 v251, v251, v251
	v_max_f32_e32 v248, 0x1e3ce508, v248
	v_max_f32_e32 v249, 0x1e3ce508, v249
	v_max_f32_e32 v250, 0x1e3ce508, v250
	v_max_f32_e32 v251, 0x1e3ce508, v251
	v_rcp_f32_e32 v248, v248
	v_rcp_f32_e32 v249, v249
	v_rcp_f32_e32 v250, v250
	v_rcp_f32_e32 v251, v251
	v_lshlrev_b32_e32 v252, 16, v188
	v_and_b32_e32 v253, 0xffff0000, v188
	v_lshlrev_b32_e32 v254, 16, v189
	v_and_b32_e32 v255, 0xffff0000, v189
	v_pk_mul_f32 v[248:249], v[248:249], v[252:253]
	v_pk_mul_f32 v[250:251], v[250:251], v[254:255]
	v_pk_mul_f32 v[46:47], v[46:47], v[248:249]
	v_pk_mul_f32 v[48:49], v[48:49], v[250:251]
	s_waitcnt vmcnt(8)
; __device__ __forceinline__ float fast_rcp(float x) { return __builtin_amdgcn_rcpf(x); }
;     __device__ __forceinline__ void mid(f32x4 (&acc)[2][2][4][2], const Unit& u, int wr, int wc, int fr, int fq, int t) const {
;     ...
;                     const u32x4 gn = *(const u32x4*)(gp + bj * 128), gd = *(const u32x4*)(gp + bj * 128 + 2048);
;                     f32x4 r0, r1;
;                     r0[0] = bflo(gn.x) * fast_rcp(fmaxf(bflo(gd.x), 1e-20f)); r0[1] = bfhi(gn.x) * fast_rcp(fmaxf(bfhi(gd.x), 1e-20f));
;                     r0[2] = bflo(gn.y) * fast_rcp(fmaxf(bflo(gd.y), 1e-20f)); r0[3] = bfhi(gn.y) * fast_rcp(fmaxf(bfhi(gd.y), 1e-20f));
;                     r1[0] = bflo(gn.z) * fast_rcp(fmaxf(bflo(gd.z), 1e-20f)); r1[1] = bfhi(gn.z) * fast_rcp(fmaxf(bfhi(gd.z), 1e-20f));
;                     r1[2] = bflo(gn.w) * fast_rcp(fmaxf(bflo(gd.w), 1e-20f)); r1[3] = bfhi(gn.w) * fast_rcp(fmaxf(bfhi(gd.w), 1e-20f));
;                     acc[ai][bj][m][0] *= r0; acc[ai][bj][m][1] *= r1;
	v_lshlrev_b32_e32 v248, 16, v198
	v_and_b32_e32 v249, 0xffff0000, v198
	v_lshlrev_b32_e32 v250, 16, v199
	v_and_b32_e32 v251, 0xffff0000, v199
	v_max_f32_e32 v248, v248, v248
	v_max_f32_e32 v249, v249, v249
	v_max_f32_e32 v250, v250, v250
	v_max_f32_e32 v251, v251, v251
	v_max_f32_e32 v248, 0x1e3ce508, v248
	v_max_f32_e32 v249, 0x1e3ce508, v249
	v_max_f32_e32 v250, 0x1e3ce508, v250
	v_max_f32_e32 v251, 0x1e3ce508, v251
	v_rcp_f32_e32 v248, v248
	v_rcp_f32_e32 v249, v249
	v_rcp_f32_e32 v250, v250
	v_rcp_f32_e32 v251, v251
	v_lshlrev_b32_e32 v252, 16, v194
	v_and_b32_e32 v253, 0xffff0000, v194
	v_lshlrev_b32_e32 v254, 16, v195
	v_and_b32_e32 v255, 0xffff0000, v195
	v_pk_mul_f32 v[248:249], v[248:249], v[252:253]
	v_pk_mul_f32 v[250:251], v[250:251], v[254:255]
	v_pk_mul_f32 v[42:43], v[42:43], v[248:249]
	v_pk_mul_f32 v[44:45], v[44:45], v[250:251]
	v_lshlrev_b32_e32 v248, 16, v200
	v_and_b32_e32 v249, 0xffff0000, v200
	v_lshlrev_b32_e32 v250, 16, v201
	v_and_b32_e32 v251, 0xffff0000, v201
	v_max_f32_e32 v248, v248, v248
	v_max_f32_e32 v249, v249, v249
	v_max_f32_e32 v250, v250, v250
	v_max_f32_e32 v251, v251, v251
	v_max_f32_e32 v248, 0x1e3ce508, v248
	v_max_f32_e32 v249, 0x1e3ce508, v249
	v_max_f32_e32 v250, 0x1e3ce508, v250
	v_max_f32_e32 v251, 0x1e3ce508, v251
	v_rcp_f32_e32 v248, v248
	v_rcp_f32_e32 v249, v249
	v_rcp_f32_e32 v250, v250
	v_rcp_f32_e32 v251, v251
	v_lshlrev_b32_e32 v252, 16, v196
	v_and_b32_e32 v253, 0xffff0000, v196
	v_lshlrev_b32_e32 v254, 16, v197
	v_and_b32_e32 v255, 0xffff0000, v197
	v_pk_mul_f32 v[248:249], v[248:249], v[252:253]
	v_pk_mul_f32 v[250:251], v[250:251], v[254:255]
	v_pk_mul_f32 v[38:39], v[38:39], v[248:249]
	v_pk_mul_f32 v[40:41], v[40:41], v[250:251]
	s_waitcnt vmcnt(6)
	v_lshlrev_b32_e32 v248, 16, v206
	v_and_b32_e32 v249, 0xffff0000, v206
	v_lshlrev_b32_e32 v250, 16, v207
	v_and_b32_e32 v251, 0xffff0000, v207
	v_max_f32_e32 v248, v248, v248
	v_max_f32_e32 v249, v249, v249
	v_max_f32_e32 v250, v250, v250
	v_max_f32_e32 v251, v251, v251
	v_max_f32_e32 v248, 0x1e3ce508, v248
	v_max_f32_e32 v249, 0x1e3ce508, v249
	v_max_f32_e32 v250, 0x1e3ce508, v250
	v_max_f32_e32 v251, 0x1e3ce508, v251
	v_rcp_f32_e32 v248, v248
	v_rcp_f32_e32 v249, v249
	v_rcp_f32_e32 v250, v250
	v_rcp_f32_e32 v251, v251
	v_lshlrev_b32_e32 v252, 16, v202
	v_and_b32_e32 v253, 0xffff0000, v202
	v_lshlrev_b32_e32 v254, 16, v203
	v_and_b32_e32 v255, 0xffff0000, v203
	v_pk_mul_f32 v[248:249], v[248:249], v[252:253]
	v_pk_mul_f32 v[250:251], v[250:251], v[254:255]
	v_pk_mul_f32 v[28:29], v[28:29], v[248:249]
	v_pk_mul_f32 v[30:31], v[30:31], v[250:251]
	v_lshlrev_b32_e32 v248, 16, v208
	v_and_b32_e32 v249, 0xffff0000, v208
	v_lshlrev_b32_e32 v250, 16, v209
	v_and_b32_e32 v251, 0xffff0000, v209
	v_max_f32_e32 v248, v248, v248
	v_max_f32_e32 v249, v249, v249
	v_max_f32_e32 v250, v250, v250
	v_max_f32_e32 v251, v251, v251
	v_max_f32_e32 v248, 0x1e3ce508, v248
	v_max_f32_e32 v249, 0x1e3ce508, v249
	v_max_f32_e32 v250, 0x1e3ce508, v250
	v_max_f32_e32 v251, 0x1e3ce508, v251
	v_rcp_f32_e32 v248, v248
	v_rcp_f32_e32 v249, v249
	v_rcp_f32_e32 v250, v250
	v_rcp_f32_e32 v251, v251
	v_lshlrev_b32_e32 v252, 16, v204
	v_and_b32_e32 v253, 0xffff0000, v204
	v_lshlrev_b32_e32 v254, 16, v205
	v_and_b32_e32 v255, 0xffff0000, v205
	v_pk_mul_f32 v[248:249], v[248:249], v[252:253]
	v_pk_mul_f32 v[250:251], v[250:251], v[254:255]
	v_pk_mul_f32 v[24:25], v[24:25], v[248:249]
	v_pk_mul_f32 v[26:27], v[26:27], v[250:251]
	s_waitcnt vmcnt(4)
; __device__ __forceinline__ float fast_rcp(float x) { return __builtin_amdgcn_rcpf(x); }
;     __device__ __forceinline__ void mid(f32x4 (&acc)[2][2][4][2], const Unit& u, int wr, int wc, int fr, int fq, int t) const {
;     ...
;                     const u32x4 gn = *(const u32x4*)(gp + bj * 128), gd = *(const u32x4*)(gp + bj * 128 + 2048);
;                     f32x4 r0, r1;
;                     r0[0] = bflo(gn.x) * fast_rcp(fmaxf(bflo(gd.x), 1e-20f)); r0[1] = bfhi(gn.x) * fast_rcp(fmaxf(bfhi(gd.x), 1e-20f));
;                     r0[2] = bflo(gn.y) * fast_rcp(fmaxf(bflo(gd.y), 1e-20f)); r0[3] = bfhi(gn.y) * fast_rcp(fmaxf(bfhi(gd.y), 1e-20f));
;                     r1[0] = bflo(gn.z) * fast_rcp(fmaxf(bflo(gd.z), 1e-20f)); r1[1] = bfhi(gn.z) * fast_rcp(fmaxf(bfhi(gd.z), 1e-20f));
;                     r1[2] = bflo(gn.w) * fast_rcp(fmaxf(bflo(gd.w), 1e-20f)); r1[3] = bfhi(gn.w) * fast_rcp(fmaxf(bfhi(gd.w), 1e-20f));
;                     acc[ai][bj][m][0] *= r0; acc[ai][bj][m][1] *= r1;
	v_lshlrev_b32_e32 v248, 16, v214
	v_and_b32_e32 v249, 0xffff0000, v214
	v_lshlrev_b32_e32 v250, 16, v215
	v_and_b32_e32 v251, 0xffff0000, v215
	v_max_f32_e32 v248, v248, v248
	v_max_f32_e32 v249, v249, v249
	v_max_f32_e32 v250, v250, v250
	v_max_f32_e32 v251, v251, v251
	v_max_f32_e32 v248, 0x1e3ce508, v248
	v_max_f32_e32 v249, 0x1e3ce508, v249
	v_max_f32_e32 v250, 0x1e3ce508, v250
	v_max_f32_e32 v251, 0x1e3ce508, v251
	v_rcp_f32_e32 v248, v248
	v_rcp_f32_e32 v249, v249
	v_rcp_f32_e32 v250, v250
	v_rcp_f32_e32 v251, v251
	v_lshlrev_b32_e32 v252, 16, v210
	v_and_b32_e32 v253, 0xffff0000, v210
	v_lshlrev_b32_e32 v254, 16, v211
	v_and_b32_e32 v255, 0xffff0000, v211
	v_pk_mul_f32 v[248:249], v[248:249], v[252:253]
	v_pk_mul_f32 v[250:251], v[250:251], v[254:255]
	v_pk_mul_f32 v[20:21], v[20:21], v[248:249]
	v_pk_mul_f32 v[22:23], v[22:23], v[250:251]
	v_lshlrev_b32_e32 v248, 16, v216
	v_and_b32_e32 v249, 0xffff0000, v216
	v_lshlrev_b32_e32 v250, 16, v217
	v_and_b32_e32 v251, 0xffff0000, v217
	v_max_f32_e32 v248, v248, v248
	v_max_f32_e32 v249, v249, v249
	v_max_f32_e32 v250, v250, v250
	v_max_f32_e32 v251, v251, v251
	v_max_f32_e32 v248, 0x1e3ce508, v248
	v_max_f32_e32 v249, 0x1e3ce508, v249
	v_max_f32_e32 v250, 0x1e3ce508, v250
	v_max_f32_e32 v251, 0x1e3ce508, v251
	v_rcp_f32_e32 v248, v248
	v_rcp_f32_e32 v249, v249
	v_rcp_f32_e32 v250, v250
	v_rcp_f32_e32 v251, v251
	v_lshlrev_b32_e32 v252, 16, v212
	v_and_b32_e32 v253, 0xffff0000, v212
	v_lshlrev_b32_e32 v254, 16, v213
	v_and_b32_e32 v255, 0xffff0000, v213
	v_pk_mul_f32 v[248:249], v[248:249], v[252:253]
	v_pk_mul_f32 v[250:251], v[250:251], v[254:255]
	v_pk_mul_f32 v[16:17], v[16:17], v[248:249]
	v_pk_mul_f32 v[18:19], v[18:19], v[250:251]
	s_waitcnt vmcnt(2)
	v_lshlrev_b32_e32 v248, 16, v222
	v_and_b32_e32 v249, 0xffff0000, v222
	v_lshlrev_b32_e32 v250, 16, v223
	v_and_b32_e32 v251, 0xffff0000, v223
	v_max_f32_e32 v248, v248, v248
	v_max_f32_e32 v249, v249, v249
	v_max_f32_e32 v250, v250, v250
	v_max_f32_e32 v251, v251, v251
	v_max_f32_e32 v248, 0x1e3ce508, v248
	v_max_f32_e32 v249, 0x1e3ce508, v249
	v_max_f32_e32 v250, 0x1e3ce508, v250
	v_max_f32_e32 v251, 0x1e3ce508, v251
	v_rcp_f32_e32 v248, v248
	v_rcp_f32_e32 v249, v249
	v_rcp_f32_e32 v250, v250
	v_rcp_f32_e32 v251, v251
	v_lshlrev_b32_e32 v252, 16, v218
	v_and_b32_e32 v253, 0xffff0000, v218
	v_lshlrev_b32_e32 v254, 16, v219
	v_and_b32_e32 v255, 0xffff0000, v219
	v_pk_mul_f32 v[248:249], v[248:249], v[252:253]
	v_pk_mul_f32 v[250:251], v[250:251], v[254:255]
	v_pk_mul_f32 v[12:13], v[12:13], v[248:249]
	v_pk_mul_f32 v[14:15], v[14:15], v[250:251]
	v_lshlrev_b32_e32 v248, 16, v224
	v_and_b32_e32 v249, 0xffff0000, v224
	v_lshlrev_b32_e32 v250, 16, v225
	v_and_b32_e32 v251, 0xffff0000, v225
	v_max_f32_e32 v248, v248, v248
	v_max_f32_e32 v249, v249, v249
	v_max_f32_e32 v250, v250, v250
	v_max_f32_e32 v251, v251, v251
	v_max_f32_e32 v248, 0x1e3ce508, v248
	v_max_f32_e32 v249, 0x1e3ce508, v249
	v_max_f32_e32 v250, 0x1e3ce508, v250
	v_max_f32_e32 v251, 0x1e3ce508, v251
	v_rcp_f32_e32 v248, v248
	v_rcp_f32_e32 v249, v249
	v_rcp_f32_e32 v250, v250
	v_rcp_f32_e32 v251, v251
	v_lshlrev_b32_e32 v252, 16, v220
	v_and_b32_e32 v253, 0xffff0000, v220
	v_lshlrev_b32_e32 v254, 16, v221
	v_and_b32_e32 v255, 0xffff0000, v221
	v_pk_mul_f32 v[248:249], v[248:249], v[252:253]
	v_pk_mul_f32 v[250:251], v[250:251], v[254:255]
	v_pk_mul_f32 v[8:9], v[8:9], v[248:249]
	v_pk_mul_f32 v[10:11], v[10:11], v[250:251]
	s_waitcnt vmcnt(0)
	v_lshlrev_b32_e32 v248, 16, v230
	v_and_b32_e32 v249, 0xffff0000, v230
	v_lshlrev_b32_e32 v250, 16, v231
	v_and_b32_e32 v251, 0xffff0000, v231
	v_max_f32_e32 v248, v248, v248
	v_max_f32_e32 v249, v249, v249
	v_max_f32_e32 v250, v250, v250
	v_max_f32_e32 v251, v251, v251
	v_max_f32_e32 v248, 0x1e3ce508, v248
	v_max_f32_e32 v249, 0x1e3ce508, v249
	v_max_f32_e32 v250, 0x1e3ce508, v250
	v_max_f32_e32 v251, 0x1e3ce508, v251
	v_rcp_f32_e32 v248, v248
	v_rcp_f32_e32 v249, v249
	v_rcp_f32_e32 v250, v250
	v_rcp_f32_e32 v251, v251
	v_lshlrev_b32_e32 v252, 16, v226
	v_and_b32_e32 v253, 0xffff0000, v226
	v_lshlrev_b32_e32 v254, 16, v227
	v_and_b32_e32 v255, 0xffff0000, v227
	v_pk_mul_f32 v[248:249], v[248:249], v[252:253]
	v_pk_mul_f32 v[250:251], v[250:251], v[254:255]
	v_pk_mul_f32 v[4:5], v[4:5], v[248:249]
	v_pk_mul_f32 v[6:7], v[6:7], v[250:251]
	v_lshlrev_b32_e32 v248, 16, v232
	v_and_b32_e32 v249, 0xffff0000, v232
	v_lshlrev_b32_e32 v250, 16, v233
	v_and_b32_e32 v251, 0xffff0000, v233
	v_max_f32_e32 v248, v248, v248
	v_max_f32_e32 v249, v249, v249
	v_max_f32_e32 v250, v250, v250
	v_max_f32_e32 v251, v251, v251
	v_max_f32_e32 v248, 0x1e3ce508, v248
	v_max_f32_e32 v249, 0x1e3ce508, v249
	v_max_f32_e32 v250, 0x1e3ce508, v250
	v_max_f32_e32 v251, 0x1e3ce508, v251
	v_rcp_f32_e32 v248, v248
	v_rcp_f32_e32 v249, v249
	v_rcp_f32_e32 v250, v250
	v_rcp_f32_e32 v251, v251
	v_lshlrev_b32_e32 v252, 16, v228
	v_and_b32_e32 v253, 0xffff0000, v228
	v_lshlrev_b32_e32 v254, 16, v229
	v_and_b32_e32 v255, 0xffff0000, v229
	v_pk_mul_f32 v[248:249], v[248:249], v[252:253]
	v_pk_mul_f32 v[250:251], v[250:251], v[254:255]
	v_pk_mul_f32 v[0:1], v[0:1], v[248:249]
	v_pk_mul_f32 v[2:3], v[2:3], v[250:251]

; __device__ __forceinline__ unsigned pk2(float lo, float hi) { f32x2 v = {lo, hi}; bf16x2_t b = __builtin_convertvector(v, bf16x2_t); return __builtin_bit_cast(unsigned, b); }
;     __device__ __forceinline__ void operator()(const f32x4 (&acc)[2][2][4][2], const Unit& u, int wr, int wc, int fr, int fq) const {
;         const int row0 = u.pm * 256 + wr * 64 + fr, col0 = u.pn * 256 + wc * 32 + 8 * fq;
; #pragma unroll
;         for (int ai = 0; ai < 2; ++ai)
; #pragma unroll
;             for (int m = 0; m < 4; ++m) {
;                 const size_t row = (size_t)(row0 + ai * 128 + m * 16);
; #pragma unroll
;                 for (int bj = 0; bj < 2; ++bj) {
;                     const int col = col0 + bj * 128;
;                     const u32x4 g = *(const u32x4*)(P + row * PS + C_GATE + 4096 + col);
;                     f32x4 v0 = acc[ai][bj][m][0], v1 = acc[ai][bj][m][1];
;                     v0[0] *= fmaxf(bflo(g.x), 1e-20f); v0[1] *= fmaxf(bfhi(g.x), 1e-20f); v0[2] *= fmaxf(bflo(g.y), 1e-20f); v0[3] *= fmaxf(bfhi(g.y), 1e-20f);
;                     v1[0] *= fmaxf(bflo(g.z), 1e-20f); v1[1] *= fmaxf(bfhi(g.z), 1e-20f); v1[2] *= fmaxf(bflo(g.w), 1e-20f); v1[3] *= fmaxf(bfhi(g.w), 1e-20f);
;                     u32x4 w; w.x = pk2(v0[0], v0[1]); w.y = pk2(v0[2], v0[3]); w.z = pk2(v1[0], v1[1]); w.w = pk2(v1[2], v1[3]);
;                     *(u32x4*)(Yb + row * DM + col) = w;
.LBB0_795:
	v_lshl_add_u32 v34, s18, 8, v174
	v_mov_b64_e32 v[36:37], s[40:41]
	v_ashrrev_i32_e32 v159, 31, v158
	v_mad_i64_i32 v[36:37], vcc, v34, s90, v[36:37]
	v_lshlrev_b64 v[160:161], 1, v[158:159]
	v_lshl_add_u64 v[36:37], v[36:37], 0, s[36:37]
	v_mov_b32_e32 v164, v34
	v_ashrrev_i32_e32 v165, 31, v34
	v_lshl_add_u64 v[36:37], v[36:37], 0, v[160:161]
	v_lshlrev_b64 v[164:165], 12, v[164:165]
	v_lshl_add_u64 v[162:163], s[42:43], 0, v[164:165]
	v_lshl_add_u64 v[162:163], v[162:163], 0, v[160:161]
	s_mov_b32 s4, 0x60000
	s_mov_b32 s5, 0
	global_load_dwordx4 v[134:137], v[36:37], off
	global_load_dwordx4 v[138:141], v[36:37], off offset:256
	v_lshl_add_u64 v[36:37], v[36:37], 0, s[4:5]
	global_load_dwordx4 v[178:181], v[36:37], off
	global_load_dwordx4 v[182:185], v[36:37], off offset:256
	v_lshl_add_u64 v[36:37], v[36:37], 0, s[4:5]
	global_load_dwordx4 v[186:189], v[36:37], off
	global_load_dwordx4 v[190:193], v[36:37], off offset:256
	v_lshl_add_u64 v[36:37], v[36:37], 0, s[4:5]
	global_load_dwordx4 v[194:197], v[36:37], off
	global_load_dwordx4 v[198:201], v[36:37], off offset:256
	s_mov_b32 s4, 0x1e0000
	v_lshl_add_u64 v[36:37], v[36:37], 0, s[4:5]
	s_mov_b32 s4, 0x60000
	global_load_dwordx4 v[202:205], v[36:37], off
	global_load_dwordx4 v[206:209], v[36:37], off offset:256
	v_lshl_add_u64 v[36:37], v[36:37], 0, s[4:5]
	global_load_dwordx4 v[210:213], v[36:37], off
	global_load_dwordx4 v[214:217], v[36:37], off offset:256
	v_lshl_add_u64 v[36:37], v[36:37], 0, s[4:5]
	global_load_dwordx4 v[218:221], v[36:37], off
	global_load_dwordx4 v[222:225], v[36:37], off offset:256
	v_lshl_add_u64 v[36:37], v[36:37], 0, s[4:5]
	global_load_dwordx4 v[226:229], v[36:37], off
	global_load_dwordx4 v[230:233], v[36:37], off offset:256
	s_mov_b32 s4, 0x10000
	s_waitcnt vmcnt(15)
	v_lshlrev_b32_e32 v248, 16, v134
	v_and_b32_e32 v249, 0xffff0000, v134
	v_lshlrev_b32_e32 v250, 16, v135
	v_and_b32_e32 v251, 0xffff0000, v135
	v_max_f32_e32 v248, v248, v248
	v_max_f32_e32 v249, v249, v249
	v_max_f32_e32 v250, v250, v250
	v_max_f32_e32 v251, v251, v251
	v_max_f32_e32 v248, 0x1e3ce508, v248
	v_max_f32_e32 v249, 0x1e3ce508, v249
	v_max_f32_e32 v250, 0x1e3ce508, v250
	v_max_f32_e32 v251, 0x1e3ce508, v251
	v_pk_mul_f32 v[130:131], v[130:131], v[248:249]
	v_pk_mul_f32 v[132:133], v[132:133], v[250:251]
	v_lshlrev_b32_e32 v248, 16, v136
	v_and_b32_e32 v249, 0xffff0000, v136
	v_lshlrev_b32_e32 v250, 16, v137
	v_and_b32_e32 v251, 0xffff0000, v137
	v_max_f32_e32 v248, v248, v248
	v_max_f32_e32 v249, v249, v249
	v_max_f32_e32 v250, v250, v250
	v_max_f32_e32 v251, v251, v251
	v_max_f32_e32 v248, 0x1e3ce508, v248
	v_max_f32_e32 v249, 0x1e3ce508, v249
	v_max_f32_e32 v250, 0x1e3ce508, v250
	v_max_f32_e32 v251, 0x1e3ce508, v251
	v_pk_mul_f32 v[126:127], v[126:127], v[248:249]
	v_pk_mul_f32 v[128:129], v[128:129], v[250:251]
	v_cvt_pk_bf16_f32 v134, v130, v131
	v_cvt_pk_bf16_f32 v135, v132, v133
	v_cvt_pk_bf16_f32 v136, v126, v127
	v_cvt_pk_bf16_f32 v137, v128, v129
	global_store_dwordx4 v[162:163], v[134:137], off
	s_waitcnt vmcnt(15)
	v_lshlrev_b32_e32 v248, 16, v138
	v_and_b32_e32 v249, 0xffff0000, v138
	v_lshlrev_b32_e32 v250, 16, v139
	v_and_b32_e32 v251, 0xffff0000, v139
	v_max_f32_e32 v248, v248, v248
	v_max_f32_e32 v249, v249, v249
	v_max_f32_e32 v250, v250, v250
	v_max_f32_e32 v251, v251, v251
	v_max_f32_e32 v248, 0x1e3ce508, v248
	v_max_f32_e32 v249, 0x1e3ce508, v249
	v_max_f32_e32 v250, 0x1e3ce508, v250
	v_max_f32_e32 v251, 0x1e3ce508, v251
	v_pk_mul_f32 v[122:123], v[122:123], v[248:249]
	v_pk_mul_f32 v[124:125], v[124:125], v[250:251]
	v_lshlrev_b32_e32 v248, 16, v140
	v_and_b32_e32 v249, 0xffff0000, v140
	v_lshlrev_b32_e32 v250, 16, v141
	v_and_b32_e32 v251, 0xffff0000, v141
	v_max_f32_e32 v248, v248, v248
	v_max_f32_e32 v249, v249, v249
	v_max_f32_e32 v250, v250, v250
	v_max_f32_e32 v251, v251, v251
	v_max_f32_e32 v248, 0x1e3ce508, v248
	v_max_f32_e32 v249, 0x1e3ce508, v249
	v_max_f32_e32 v250, 0x1e3ce508, v250
	v_max_f32_e32 v251, 0x1e3ce508, v251
	v_pk_mul_f32 v[118:119], v[118:119], v[248:249]
	v_pk_mul_f32 v[120:121], v[120:121], v[250:251]
	v_cvt_pk_bf16_f32 v138, v122, v123
	v_cvt_pk_bf16_f32 v139, v124, v125
	v_cvt_pk_bf16_f32 v140, v118, v119
	v_cvt_pk_bf16_f32 v141, v120, v121
	global_store_dwordx4 v[162:163], v[138:141], off offset:256
	v_lshl_add_u64 v[162:163], v[162:163], 0, s[4:5]
	s_waitcnt vmcnt(15)
	v_lshlrev_b32_e32 v248, 16, v178
	v_and_b32_e32 v249, 0xffff0000, v178
	v_lshlrev_b32_e32 v250, 16, v179
	v_and_b32_e32 v251, 0xffff0000, v179
	v_max_f32_e32 v248, v248, v248
	v_max_f32_e32 v249, v249, v249
	v_max_f32_e32 v250, v250, v250
	v_max_f32_e32 v251, v251, v251
	v_max_f32_e32 v248, 0x1e3ce508, v248
	v_max_f32_e32 v249, 0x1e3ce508, v249
	v_max_f32_e32 v250, 0x1e3ce508, v250
	v_max_f32_e32 v251, 0x1e3ce508, v251
	v_pk_mul_f32 v[114:115], v[114:115], v[248:249]
	v_pk_mul_f32 v[116:117], v[116:117], v[250:251]
	v_lshlrev_b32_e32 v248, 16, v180
	v_and_b32_e32 v249, 0xffff0000, v180
	v_lshlrev_b32_e32 v250, 16, v181
	v_and_b32_e32 v251, 0xffff0000, v181
	v_max_f32_e32 v248, v248, v248
	v_max_f32_e32 v249, v249, v249
	v_max_f32_e32 v250, v250, v250
	v_max_f32_e32 v251, v251, v251
	v_max_f32_e32 v248, 0x1e3ce508, v248
	v_max_f32_e32 v249, 0x1e3ce508, v249
	v_max_f32_e32 v250, 0x1e3ce508, v250
	v_max_f32_e32 v251, 0x1e3ce508, v251
	v_pk_mul_f32 v[110:111], v[110:111], v[248:249]
	v_pk_mul_f32 v[112:113], v[112:113], v[250:251]
	v_cvt_pk_bf16_f32 v178, v114, v115
	v_cvt_pk_bf16_f32 v179, v116, v117
	v_cvt_pk_bf16_f32 v180, v110, v111
	v_cvt_pk_bf16_f32 v181, v112, v113
	global_store_dwordx4 v[162:163], v[178:181], off
	s_waitcnt vmcnt(15)
; __device__ __forceinline__ unsigned pk2(float lo, float hi) { f32x2 v = {lo, hi}; bf16x2_t b = __builtin_convertvector(v, bf16x2_t); return __builtin_bit_cast(unsigned, b); }
;     __device__ __forceinline__ void operator()(const f32x4 (&acc)[2][2][4][2], const Unit& u, int wr, int wc, int fr, int fq) const {
;         const int row0 = u.pm * 256 + wr * 64 + fr, col0 = u.pn * 256 + wc * 32 + 8 * fq;
; #pragma unroll
;         for (int ai = 0; ai < 2; ++ai)
; #pragma unroll
;             for (int m = 0; m < 4; ++m) {
;                 const size_t row = (size_t)(row0 + ai * 128 + m * 16);
; #pragma unroll
;                 for (int bj = 0; bj < 2; ++bj) {
;                     const int col = col0 + bj * 128;
;                     const u32x4 g = *(const u32x4*)(P + row * PS + C_GATE + 4096 + col);
;                     f32x4 v0 = acc[ai][bj][m][0], v1 = acc[ai][bj][m][1];
;                     v0[0] *= fmaxf(bflo(g.x), 1e-20f); v0[1] *= fmaxf(bfhi(g.x), 1e-20f); v0[2] *= fmaxf(bflo(g.y), 1e-20f); v0[3] *= fmaxf(bfhi(g.y), 1e-20f);
;                     v1[0] *= fmaxf(bflo(g.z), 1e-20f); v1[1] *= fmaxf(bfhi(g.z), 1e-20f); v1[2] *= fmaxf(bflo(g.w), 1e-20f); v1[3] *= fmaxf(bfhi(g.w), 1e-20f);
;                     u32x4 w; w.x = pk2(v0[0], v0[1]); w.y = pk2(v0[2], v0[3]); w.z = pk2(v1[0], v1[1]); w.w = pk2(v1[2], v1[3]);
;                     *(u32x4*)(Yb + row * DM + col) = w;
	v_lshlrev_b32_e32 v248, 16, v182
	v_and_b32_e32 v249, 0xffff0000, v182
	v_lshlrev_b32_e32 v250, 16, v183
	v_and_b32_e32 v251, 0xffff0000, v183
	v_max_f32_e32 v248, v248, v248
	v_max_f32_e32 v249, v249, v249
	v_max_f32_e32 v250, v250, v250
	v_max_f32_e32 v251, v251, v251
	v_max_f32_e32 v248, 0x1e3ce508, v248
	v_max_f32_e32 v249, 0x1e3ce508, v249
	v_max_f32_e32 v250, 0x1e3ce508, v250
	v_max_f32_e32 v251, 0x1e3ce508, v251
	v_pk_mul_f32 v[106:107], v[106:107], v[248:249]
	v_pk_mul_f32 v[108:109], v[108:109], v[250:251]
	v_lshlrev_b32_e32 v248, 16, v184
	v_and_b32_e32 v249, 0xffff0000, v184
	v_lshlrev_b32_e32 v250, 16, v185
	v_and_b32_e32 v251, 0xffff0000, v185
	v_max_f32_e32 v248, v248, v248
	v_max_f32_e32 v249, v249, v249
	v_max_f32_e32 v250, v250, v250
	v_max_f32_e32 v251, v251, v251
	v_max_f32_e32 v248, 0x1e3ce508, v248
	v_max_f32_e32 v249, 0x1e3ce508, v249
	v_max_f32_e32 v250, 0x1e3ce508, v250
	v_max_f32_e32 v251, 0x1e3ce508, v251
	v_pk_mul_f32 v[102:103], v[102:103], v[248:249]
	v_pk_mul_f32 v[104:105], v[104:105], v[250:251]
	v_cvt_pk_bf16_f32 v182, v106, v107
	v_cvt_pk_bf16_f32 v183, v108, v109
	v_cvt_pk_bf16_f32 v184, v102, v103
	v_cvt_pk_bf16_f32 v185, v104, v105
	global_store_dwordx4 v[162:163], v[182:185], off offset:256
	v_lshl_add_u64 v[162:163], v[162:163], 0, s[4:5]
	s_waitcnt vmcnt(15)
	v_lshlrev_b32_e32 v248, 16, v186
	v_and_b32_e32 v249, 0xffff0000, v186
	v_lshlrev_b32_e32 v250, 16, v187
	v_and_b32_e32 v251, 0xffff0000, v187
	v_max_f32_e32 v248, v248, v248
	v_max_f32_e32 v249, v249, v249
	v_max_f32_e32 v250, v250, v250
	v_max_f32_e32 v251, v251, v251
	v_max_f32_e32 v248, 0x1e3ce508, v248
	v_max_f32_e32 v249, 0x1e3ce508, v249
	v_max_f32_e32 v250, 0x1e3ce508, v250
	v_max_f32_e32 v251, 0x1e3ce508, v251
	v_pk_mul_f32 v[98:99], v[98:99], v[248:249]
	v_pk_mul_f32 v[100:101], v[100:101], v[250:251]
	v_lshlrev_b32_e32 v248, 16, v188
	v_and_b32_e32 v249, 0xffff0000, v188
	v_lshlrev_b32_e32 v250, 16, v189
	v_and_b32_e32 v251, 0xffff0000, v189
	v_max_f32_e32 v248, v248, v248
	v_max_f32_e32 v249, v249, v249
	v_max_f32_e32 v250, v250, v250
	v_max_f32_e32 v251, v251, v251
	v_max_f32_e32 v248, 0x1e3ce508, v248
	v_max_f32_e32 v249, 0x1e3ce508, v249
	v_max_f32_e32 v250, 0x1e3ce508, v250
	v_max_f32_e32 v251, 0x1e3ce508, v251
	v_pk_mul_f32 v[94:95], v[94:95], v[248:249]
	v_pk_mul_f32 v[96:97], v[96:97], v[250:251]
	v_cvt_pk_bf16_f32 v186, v98, v99
	v_cvt_pk_bf16_f32 v187, v100, v101
	v_cvt_pk_bf16_f32 v188, v94, v95
	v_cvt_pk_bf16_f32 v189, v96, v97
	global_store_dwordx4 v[162:163], v[186:189], off
	s_waitcnt vmcnt(15)
	v_lshlrev_b32_e32 v248, 16, v190
	v_and_b32_e32 v249, 0xffff0000, v190
	v_lshlrev_b32_e32 v250, 16, v191
	v_and_b32_e32 v251, 0xffff0000, v191
	v_max_f32_e32 v248, v248, v248
	v_max_f32_e32 v249, v249, v249
	v_max_f32_e32 v250, v250, v250
	v_max_f32_e32 v251, v251, v251
	v_max_f32_e32 v248, 0x1e3ce508, v248
	v_max_f32_e32 v249, 0x1e3ce508, v249
	v_max_f32_e32 v250, 0x1e3ce508, v250
	v_max_f32_e32 v251, 0x1e3ce508, v251
	v_pk_mul_f32 v[90:91], v[90:91], v[248:249]
	v_pk_mul_f32 v[92:93], v[92:93], v[250:251]
	v_lshlrev_b32_e32 v248, 16, v192
	v_and_b32_e32 v249, 0xffff0000, v192
	v_lshlrev_b32_e32 v250, 16, v193
	v_and_b32_e32 v251, 0xffff0000, v193
	v_max_f32_e32 v248, v248, v248
	v_max_f32_e32 v249, v249, v249
	v_max_f32_e32 v250, v250, v250
	v_max_f32_e32 v251, v251, v251
	v_max_f32_e32 v248, 0x1e3ce508, v248
	v_max_f32_e32 v249, 0x1e3ce508, v249
	v_max_f32_e32 v250, 0x1e3ce508, v250
	v_max_f32_e32 v251, 0x1e3ce508, v251
	v_pk_mul_f32 v[86:87], v[86:87], v[248:249]
	v_pk_mul_f32 v[88:89], v[88:89], v[250:251]
	v_cvt_pk_bf16_f32 v190, v90, v91
	v_cvt_pk_bf16_f32 v191, v92, v93
	v_cvt_pk_bf16_f32 v192, v86, v87
	v_cvt_pk_bf16_f32 v193, v88, v89
	global_store_dwordx4 v[162:163], v[190:193], off offset:256
	v_lshl_add_u64 v[162:163], v[162:163], 0, s[4:5]
	s_waitcnt vmcnt(15)
	v_lshlrev_b32_e32 v248, 16, v194
	v_and_b32_e32 v249, 0xffff0000, v194
	v_lshlrev_b32_e32 v250, 16, v195
	v_and_b32_e32 v251, 0xffff0000, v195
	v_max_f32_e32 v248, v248, v248
	v_max_f32_e32 v249, v249, v249
	v_max_f32_e32 v250, v250, v250
	v_max_f32_e32 v251, v251, v251
	v_max_f32_e32 v248, 0x1e3ce508, v248
	v_max_f32_e32 v249, 0x1e3ce508, v249
	v_max_f32_e32 v250, 0x1e3ce508, v250
	v_max_f32_e32 v251, 0x1e3ce508, v251
	v_pk_mul_f32 v[82:83], v[82:83], v[248:249]
	v_pk_mul_f32 v[84:85], v[84:85], v[250:251]
	v_lshlrev_b32_e32 v248, 16, v196
	v_and_b32_e32 v249, 0xffff0000, v196
	v_lshlrev_b32_e32 v250, 16, v197
	v_and_b32_e32 v251, 0xffff0000, v197
	v_max_f32_e32 v248, v248, v248
	v_max_f32_e32 v249, v249, v249
	v_max_f32_e32 v250, v250, v250
	v_max_f32_e32 v251, v251, v251
	v_max_f32_e32 v248, 0x1e3ce508, v248
	v_max_f32_e32 v249, 0x1e3ce508, v249
	v_max_f32_e32 v250, 0x1e3ce508, v250
	v_max_f32_e32 v251, 0x1e3ce508, v251
	v_pk_mul_f32 v[78:79], v[78:79], v[248:249]
	v_pk_mul_f32 v[80:81], v[80:81], v[250:251]
	v_cvt_pk_bf16_f32 v194, v82, v83
	v_cvt_pk_bf16_f32 v195, v84, v85
	v_cvt_pk_bf16_f32 v196, v78, v79
	v_cvt_pk_bf16_f32 v197, v80, v81
	global_store_dwordx4 v[162:163], v[194:197], off
	s_waitcnt vmcnt(15)
; __device__ __forceinline__ unsigned pk2(float lo, float hi) { f32x2 v = {lo, hi}; bf16x2_t b = __builtin_convertvector(v, bf16x2_t); return __builtin_bit_cast(unsigned, b); }
;     __device__ __forceinline__ void operator()(const f32x4 (&acc)[2][2][4][2], const Unit& u, int wr, int wc, int fr, int fq) const {
;         const int row0 = u.pm * 256 + wr * 64 + fr, col0 = u.pn * 256 + wc * 32 + 8 * fq;
; #pragma unroll
;         for (int ai = 0; ai < 2; ++ai)
; #pragma unroll
;             for (int m = 0; m < 4; ++m) {
;                 const size_t row = (size_t)(row0 + ai * 128 + m * 16);
; #pragma unroll
;                 for (int bj = 0; bj < 2; ++bj) {
;                     const int col = col0 + bj * 128;
;                     const u32x4 g = *(const u32x4*)(P + row * PS + C_GATE + 4096 + col);
;                     f32x4 v0 = acc[ai][bj][m][0], v1 = acc[ai][bj][m][1];
;                     v0[0] *= fmaxf(bflo(g.x), 1e-20f); v0[1] *= fmaxf(bfhi(g.x), 1e-20f); v0[2] *= fmaxf(bflo(g.y), 1e-20f); v0[3] *= fmaxf(bfhi(g.y), 1e-20f);
;                     v1[0] *= fmaxf(bflo(g.z), 1e-20f); v1[1] *= fmaxf(bfhi(g.z), 1e-20f); v1[2] *= fmaxf(bflo(g.w), 1e-20f); v1[3] *= fmaxf(bfhi(g.w), 1e-20f);
;                     u32x4 w; w.x = pk2(v0[0], v0[1]); w.y = pk2(v0[2], v0[3]); w.z = pk2(v1[0], v1[1]); w.w = pk2(v1[2], v1[3]);
;                     *(u32x4*)(Yb + row * DM + col) = w;
	v_lshlrev_b32_e32 v248, 16, v198
	v_and_b32_e32 v249, 0xffff0000, v198
	v_lshlrev_b32_e32 v250, 16, v199
	v_and_b32_e32 v251, 0xffff0000, v199
	v_max_f32_e32 v248, v248, v248
	v_max_f32_e32 v249, v249, v249
	v_max_f32_e32 v250, v250, v250
	v_max_f32_e32 v251, v251, v251
	v_max_f32_e32 v248, 0x1e3ce508, v248
	v_max_f32_e32 v249, 0x1e3ce508, v249
	v_max_f32_e32 v250, 0x1e3ce508, v250
	v_max_f32_e32 v251, 0x1e3ce508, v251
	v_pk_mul_f32 v[74:75], v[74:75], v[248:249]
	v_pk_mul_f32 v[76:77], v[76:77], v[250:251]
	v_lshlrev_b32_e32 v248, 16, v200
	v_and_b32_e32 v249, 0xffff0000, v200
	v_lshlrev_b32_e32 v250, 16, v201
	v_and_b32_e32 v251, 0xffff0000, v201
	v_max_f32_e32 v248, v248, v248
	v_max_f32_e32 v249, v249, v249
	v_max_f32_e32 v250, v250, v250
	v_max_f32_e32 v251, v251, v251
	v_max_f32_e32 v248, 0x1e3ce508, v248
	v_max_f32_e32 v249, 0x1e3ce508, v249
	v_max_f32_e32 v250, 0x1e3ce508, v250
	v_max_f32_e32 v251, 0x1e3ce508, v251
	v_pk_mul_f32 v[70:71], v[70:71], v[248:249]
	v_pk_mul_f32 v[72:73], v[72:73], v[250:251]
	v_cvt_pk_bf16_f32 v198, v74, v75
	v_cvt_pk_bf16_f32 v199, v76, v77
	v_cvt_pk_bf16_f32 v200, v70, v71
	v_cvt_pk_bf16_f32 v201, v72, v73
	global_store_dwordx4 v[162:163], v[198:201], off offset:256
	s_mov_b32 s4, 0x50000
	v_lshl_add_u64 v[162:163], v[162:163], 0, s[4:5]
	s_mov_b32 s4, 0x10000
	s_waitcnt vmcnt(15)
	v_lshlrev_b32_e32 v248, 16, v202
	v_and_b32_e32 v249, 0xffff0000, v202
	v_lshlrev_b32_e32 v250, 16, v203
	v_and_b32_e32 v251, 0xffff0000, v203
	v_max_f32_e32 v248, v248, v248
	v_max_f32_e32 v249, v249, v249
	v_max_f32_e32 v250, v250, v250
	v_max_f32_e32 v251, v251, v251
	v_max_f32_e32 v248, 0x1e3ce508, v248
	v_max_f32_e32 v249, 0x1e3ce508, v249
	v_max_f32_e32 v250, 0x1e3ce508, v250
	v_max_f32_e32 v251, 0x1e3ce508, v251
	v_pk_mul_f32 v[66:67], v[66:67], v[248:249]
	v_pk_mul_f32 v[68:69], v[68:69], v[250:251]
	v_lshlrev_b32_e32 v248, 16, v204
	v_and_b32_e32 v249, 0xffff0000, v204
	v_lshlrev_b32_e32 v250, 16, v205
	v_and_b32_e32 v251, 0xffff0000, v205
	v_max_f32_e32 v248, v248, v248
	v_max_f32_e32 v249, v249, v249
	v_max_f32_e32 v250, v250, v250
	v_max_f32_e32 v251, v251, v251
	v_max_f32_e32 v248, 0x1e3ce508, v248
	v_max_f32_e32 v249, 0x1e3ce508, v249
	v_max_f32_e32 v250, 0x1e3ce508, v250
	v_max_f32_e32 v251, 0x1e3ce508, v251
	v_pk_mul_f32 v[62:63], v[62:63], v[248:249]
	v_pk_mul_f32 v[64:65], v[64:65], v[250:251]
	v_cvt_pk_bf16_f32 v202, v66, v67
	v_cvt_pk_bf16_f32 v203, v68, v69
	v_cvt_pk_bf16_f32 v204, v62, v63
	v_cvt_pk_bf16_f32 v205, v64, v65
	global_store_dwordx4 v[162:163], v[202:205], off
	s_waitcnt vmcnt(15)
	v_lshlrev_b32_e32 v248, 16, v206
	v_and_b32_e32 v249, 0xffff0000, v206
	v_lshlrev_b32_e32 v250, 16, v207
	v_and_b32_e32 v251, 0xffff0000, v207
	v_max_f32_e32 v248, v248, v248
	v_max_f32_e32 v249, v249, v249
	v_max_f32_e32 v250, v250, v250
	v_max_f32_e32 v251, v251, v251
	v_max_f32_e32 v248, 0x1e3ce508, v248
	v_max_f32_e32 v249, 0x1e3ce508, v249
	v_max_f32_e32 v250, 0x1e3ce508, v250
	v_max_f32_e32 v251, 0x1e3ce508, v251
	v_pk_mul_f32 v[58:59], v[58:59], v[248:249]
	v_pk_mul_f32 v[60:61], v[60:61], v[250:251]
	v_lshlrev_b32_e32 v248, 16, v208
	v_and_b32_e32 v249, 0xffff0000, v208
	v_lshlrev_b32_e32 v250, 16, v209
	v_and_b32_e32 v251, 0xffff0000, v209
	v_max_f32_e32 v248, v248, v248
	v_max_f32_e32 v249, v249, v249
	v_max_f32_e32 v250, v250, v250
	v_max_f32_e32 v251, v251, v251
	v_max_f32_e32 v248, 0x1e3ce508, v248
	v_max_f32_e32 v249, 0x1e3ce508, v249
	v_max_f32_e32 v250, 0x1e3ce508, v250
	v_max_f32_e32 v251, 0x1e3ce508, v251
	v_pk_mul_f32 v[54:55], v[54:55], v[248:249]
	v_pk_mul_f32 v[56:57], v[56:57], v[250:251]
	v_cvt_pk_bf16_f32 v206, v58, v59
	v_cvt_pk_bf16_f32 v207, v60, v61
	v_cvt_pk_bf16_f32 v208, v54, v55
	v_cvt_pk_bf16_f32 v209, v56, v57
	global_store_dwordx4 v[162:163], v[206:209], off offset:256
	v_lshl_add_u64 v[162:163], v[162:163], 0, s[4:5]
	s_waitcnt vmcnt(15)
	v_lshlrev_b32_e32 v248, 16, v210
	v_and_b32_e32 v249, 0xffff0000, v210
	v_lshlrev_b32_e32 v250, 16, v211
	v_and_b32_e32 v251, 0xffff0000, v211
	v_max_f32_e32 v248, v248, v248
	v_max_f32_e32 v249, v249, v249
	v_max_f32_e32 v250, v250, v250
	v_max_f32_e32 v251, v251, v251
	v_max_f32_e32 v248, 0x1e3ce508, v248
	v_max_f32_e32 v249, 0x1e3ce508, v249
	v_max_f32_e32 v250, 0x1e3ce508, v250
	v_max_f32_e32 v251, 0x1e3ce508, v251
	v_pk_mul_f32 v[50:51], v[50:51], v[248:249]
	v_pk_mul_f32 v[52:53], v[52:53], v[250:251]
	v_lshlrev_b32_e32 v248, 16, v212
	v_and_b32_e32 v249, 0xffff0000, v212
	v_lshlrev_b32_e32 v250, 16, v213
	v_and_b32_e32 v251, 0xffff0000, v213
	v_max_f32_e32 v248, v248, v248
	v_max_f32_e32 v249, v249, v249
	v_max_f32_e32 v250, v250, v250
	v_max_f32_e32 v251, v251, v251
	v_max_f32_e32 v248, 0x1e3ce508, v248
	v_max_f32_e32 v249, 0x1e3ce508, v249
	v_max_f32_e32 v250, 0x1e3ce508, v250
	v_max_f32_e32 v251, 0x1e3ce508, v251
	v_pk_mul_f32 v[46:47], v[46:47], v[248:249]
	v_pk_mul_f32 v[48:49], v[48:49], v[250:251]
	v_cvt_pk_bf16_f32 v210, v50, v51
	v_cvt_pk_bf16_f32 v211, v52, v53
	v_cvt_pk_bf16_f32 v212, v46, v47
	v_cvt_pk_bf16_f32 v213, v48, v49
	global_store_dwordx4 v[162:163], v[210:213], off
	s_waitcnt vmcnt(15)
; __device__ __forceinline__ unsigned pk2(float lo, float hi) { f32x2 v = {lo, hi}; bf16x2_t b = __builtin_convertvector(v, bf16x2_t); return __builtin_bit_cast(unsigned, b); }
;     __device__ __forceinline__ void operator()(const f32x4 (&acc)[2][2][4][2], const Unit& u, int wr, int wc, int fr, int fq) const {
;         const int row0 = u.pm * 256 + wr * 64 + fr, col0 = u.pn * 256 + wc * 32 + 8 * fq;
; #pragma unroll
;         for (int ai = 0; ai < 2; ++ai)
; #pragma unroll
;             for (int m = 0; m < 4; ++m) {
;                 const size_t row = (size_t)(row0 + ai * 128 + m * 16);
; #pragma unroll
;                 for (int bj = 0; bj < 2; ++bj) {
;                     const int col = col0 + bj * 128;
;                     const u32x4 g = *(const u32x4*)(P + row * PS + C_GATE + 4096 + col);
;                     f32x4 v0 = acc[ai][bj][m][0], v1 = acc[ai][bj][m][1];
;                     v0[0] *= fmaxf(bflo(g.x), 1e-20f); v0[1] *= fmaxf(bfhi(g.x), 1e-20f); v0[2] *= fmaxf(bflo(g.y), 1e-20f); v0[3] *= fmaxf(bfhi(g.y), 1e-20f);
;                     v1[0] *= fmaxf(bflo(g.z), 1e-20f); v1[1] *= fmaxf(bfhi(g.z), 1e-20f); v1[2] *= fmaxf(bflo(g.w), 1e-20f); v1[3] *= fmaxf(bfhi(g.w), 1e-20f);
;                     u32x4 w; w.x = pk2(v0[0], v0[1]); w.y = pk2(v0[2], v0[3]); w.z = pk2(v1[0], v1[1]); w.w = pk2(v1[2], v1[3]);
;                     *(u32x4*)(Yb + row * DM + col) = w;
;                 }
;             }
;     }
	v_lshlrev_b32_e32 v248, 16, v214
	v_and_b32_e32 v249, 0xffff0000, v214
	v_lshlrev_b32_e32 v250, 16, v215
	v_and_b32_e32 v251, 0xffff0000, v215
	v_max_f32_e32 v248, v248, v248
	v_max_f32_e32 v249, v249, v249
	v_max_f32_e32 v250, v250, v250
	v_max_f32_e32 v251, v251, v251
	v_max_f32_e32 v248, 0x1e3ce508, v248
	v_max_f32_e32 v249, 0x1e3ce508, v249
	v_max_f32_e32 v250, 0x1e3ce508, v250
	v_max_f32_e32 v251, 0x1e3ce508, v251
	v_pk_mul_f32 v[42:43], v[42:43], v[248:249]
	v_pk_mul_f32 v[44:45], v[44:45], v[250:251]
	v_lshlrev_b32_e32 v248, 16, v216
	v_and_b32_e32 v249, 0xffff0000, v216
	v_lshlrev_b32_e32 v250, 16, v217
	v_and_b32_e32 v251, 0xffff0000, v217
	v_max_f32_e32 v248, v248, v248
	v_max_f32_e32 v249, v249, v249
	v_max_f32_e32 v250, v250, v250
	v_max_f32_e32 v251, v251, v251
	v_max_f32_e32 v248, 0x1e3ce508, v248
	v_max_f32_e32 v249, 0x1e3ce508, v249
	v_max_f32_e32 v250, 0x1e3ce508, v250
	v_max_f32_e32 v251, 0x1e3ce508, v251
	v_pk_mul_f32 v[38:39], v[38:39], v[248:249]
	v_pk_mul_f32 v[40:41], v[40:41], v[250:251]
	v_cvt_pk_bf16_f32 v214, v42, v43
	v_cvt_pk_bf16_f32 v215, v44, v45
	v_cvt_pk_bf16_f32 v216, v38, v39
	v_cvt_pk_bf16_f32 v217, v40, v41
	global_store_dwordx4 v[162:163], v[214:217], off offset:256
	v_lshl_add_u64 v[162:163], v[162:163], 0, s[4:5]
	s_waitcnt vmcnt(15)
	v_lshlrev_b32_e32 v248, 16, v218
	v_and_b32_e32 v249, 0xffff0000, v218
	v_lshlrev_b32_e32 v250, 16, v219
	v_and_b32_e32 v251, 0xffff0000, v219
	v_max_f32_e32 v248, v248, v248
	v_max_f32_e32 v249, v249, v249
	v_max_f32_e32 v250, v250, v250
	v_max_f32_e32 v251, v251, v251
	v_max_f32_e32 v248, 0x1e3ce508, v248
	v_max_f32_e32 v249, 0x1e3ce508, v249
	v_max_f32_e32 v250, 0x1e3ce508, v250
	v_max_f32_e32 v251, 0x1e3ce508, v251
	v_pk_mul_f32 v[28:29], v[28:29], v[248:249]
	v_pk_mul_f32 v[30:31], v[30:31], v[250:251]
	v_lshlrev_b32_e32 v248, 16, v220
	v_and_b32_e32 v249, 0xffff0000, v220
	v_lshlrev_b32_e32 v250, 16, v221
	v_and_b32_e32 v251, 0xffff0000, v221
	v_max_f32_e32 v248, v248, v248
	v_max_f32_e32 v249, v249, v249
	v_max_f32_e32 v250, v250, v250
	v_max_f32_e32 v251, v251, v251
	v_max_f32_e32 v248, 0x1e3ce508, v248
	v_max_f32_e32 v249, 0x1e3ce508, v249
	v_max_f32_e32 v250, 0x1e3ce508, v250
	v_max_f32_e32 v251, 0x1e3ce508, v251
	v_pk_mul_f32 v[24:25], v[24:25], v[248:249]
	v_pk_mul_f32 v[26:27], v[26:27], v[250:251]
	v_cvt_pk_bf16_f32 v218, v28, v29
	v_cvt_pk_bf16_f32 v219, v30, v31
	v_cvt_pk_bf16_f32 v220, v24, v25
	v_cvt_pk_bf16_f32 v221, v26, v27
	global_store_dwordx4 v[162:163], v[218:221], off
	s_waitcnt vmcnt(15)
	v_lshlrev_b32_e32 v248, 16, v222
	v_and_b32_e32 v249, 0xffff0000, v222
	v_lshlrev_b32_e32 v250, 16, v223
	v_and_b32_e32 v251, 0xffff0000, v223
	v_max_f32_e32 v248, v248, v248
	v_max_f32_e32 v249, v249, v249
	v_max_f32_e32 v250, v250, v250
	v_max_f32_e32 v251, v251, v251
	v_max_f32_e32 v248, 0x1e3ce508, v248
	v_max_f32_e32 v249, 0x1e3ce508, v249
	v_max_f32_e32 v250, 0x1e3ce508, v250
	v_max_f32_e32 v251, 0x1e3ce508, v251
	v_pk_mul_f32 v[20:21], v[20:21], v[248:249]
	v_pk_mul_f32 v[22:23], v[22:23], v[250:251]
	v_lshlrev_b32_e32 v248, 16, v224
	v_and_b32_e32 v249, 0xffff0000, v224
	v_lshlrev_b32_e32 v250, 16, v225
	v_and_b32_e32 v251, 0xffff0000, v225
	v_max_f32_e32 v248, v248, v248
	v_max_f32_e32 v249, v249, v249
	v_max_f32_e32 v250, v250, v250
	v_max_f32_e32 v251, v251, v251
	v_max_f32_e32 v248, 0x1e3ce508, v248
	v_max_f32_e32 v249, 0x1e3ce508, v249
	v_max_f32_e32 v250, 0x1e3ce508, v250
	v_max_f32_e32 v251, 0x1e3ce508, v251
	v_pk_mul_f32 v[16:17], v[16:17], v[248:249]
	v_pk_mul_f32 v[18:19], v[18:19], v[250:251]
	v_cvt_pk_bf16_f32 v222, v20, v21
	v_cvt_pk_bf16_f32 v223, v22, v23
	v_cvt_pk_bf16_f32 v224, v16, v17
	v_cvt_pk_bf16_f32 v225, v18, v19
	global_store_dwordx4 v[162:163], v[222:225], off offset:256
	v_lshl_add_u64 v[162:163], v[162:163], 0, s[4:5]
	s_waitcnt vmcnt(15)
	v_lshlrev_b32_e32 v248, 16, v226
	v_and_b32_e32 v249, 0xffff0000, v226
	v_lshlrev_b32_e32 v250, 16, v227
	v_and_b32_e32 v251, 0xffff0000, v227
	v_max_f32_e32 v248, v248, v248
	v_max_f32_e32 v249, v249, v249
	v_max_f32_e32 v250, v250, v250
	v_max_f32_e32 v251, v251, v251
	v_max_f32_e32 v248, 0x1e3ce508, v248
	v_max_f32_e32 v249, 0x1e3ce508, v249
	v_max_f32_e32 v250, 0x1e3ce508, v250
	v_max_f32_e32 v251, 0x1e3ce508, v251
	v_pk_mul_f32 v[12:13], v[12:13], v[248:249]
	v_pk_mul_f32 v[14:15], v[14:15], v[250:251]
	v_lshlrev_b32_e32 v248, 16, v228
	v_and_b32_e32 v249, 0xffff0000, v228
	v_lshlrev_b32_e32 v250, 16, v229
	v_and_b32_e32 v251, 0xffff0000, v229
	v_max_f32_e32 v248, v248, v248
	v_max_f32_e32 v249, v249, v249
	v_max_f32_e32 v250, v250, v250
	v_max_f32_e32 v251, v251, v251
	v_max_f32_e32 v248, 0x1e3ce508, v248
	v_max_f32_e32 v249, 0x1e3ce508, v249
	v_max_f32_e32 v250, 0x1e3ce508, v250
	v_max_f32_e32 v251, 0x1e3ce508, v251
	v_pk_mul_f32 v[8:9], v[8:9], v[248:249]
	v_pk_mul_f32 v[10:11], v[10:11], v[250:251]
	v_cvt_pk_bf16_f32 v226, v12, v13
	v_cvt_pk_bf16_f32 v227, v14, v15
	v_cvt_pk_bf16_f32 v228, v8, v9
	v_cvt_pk_bf16_f32 v229, v10, v11
	global_store_dwordx4 v[162:163], v[226:229], off
	s_waitcnt vmcnt(15)
	v_lshlrev_b32_e32 v248, 16, v230
	v_and_b32_e32 v249, 0xffff0000, v230
	v_lshlrev_b32_e32 v250, 16, v231
	v_and_b32_e32 v251, 0xffff0000, v231
	v_max_f32_e32 v248, v248, v248
	v_max_f32_e32 v249, v249, v249
	v_max_f32_e32 v250, v250, v250
	v_max_f32_e32 v251, v251, v251
	v_max_f32_e32 v248, 0x1e3ce508, v248
	v_max_f32_e32 v249, 0x1e3ce508, v249
	v_max_f32_e32 v250, 0x1e3ce508, v250
	v_max_f32_e32 v251, 0x1e3ce508, v251
	v_pk_mul_f32 v[4:5], v[4:5], v[248:249]
	v_pk_mul_f32 v[6:7], v[6:7], v[250:251]
	v_lshlrev_b32_e32 v248, 16, v232
	v_and_b32_e32 v249, 0xffff0000, v232
	v_lshlrev_b32_e32 v250, 16, v233
	v_and_b32_e32 v251, 0xffff0000, v233
	v_max_f32_e32 v248, v248, v248
	v_max_f32_e32 v249, v249, v249
	v_max_f32_e32 v250, v250, v250
	v_max_f32_e32 v251, v251, v251
	v_max_f32_e32 v248, 0x1e3ce508, v248
	v_max_f32_e32 v249, 0x1e3ce508, v249
	v_max_f32_e32 v250, 0x1e3ce508, v250
	v_max_f32_e32 v251, 0x1e3ce508, v251
	v_pk_mul_f32 v[0:1], v[0:1], v[248:249]
	v_pk_mul_f32 v[2:3], v[2:3], v[250:251]
	v_cvt_pk_bf16_f32 v230, v4, v5
	v_cvt_pk_bf16_f32 v231, v6, v7
	v_cvt_pk_bf16_f32 v232, v0, v1
	v_cvt_pk_bf16_f32 v233, v2, v3
	global_store_dwordx4 v[162:163], v[230:233], off offset:256
	s_andn2_b64 vcc, exec, s[56:57]
	s_mov_b64 s[0:1], -1
	s_cbranch_vccnz .LBB0_776
	s_andn2_b64 vcc, exec, s[38:39]
	s_cbranch_vccnz .LBB0_775
	s_barrier
	s_branch .LBB0_775

;     __device__ __forceinline__ void operator()(const f32x4 (&acc)[2][2][4][2], const Unit& u, int wr, int wc, int fr, int fq) const {
;         const bool isc = u.pm >= 64;
;         const int row0 = (isc ? (u.pm - 64) * 256 : u.pm * 256) + wr * 64 + fr, col0 = u.pn * 256 + wc * 32 + 8 * fq;
;         const float* src = isc ? srcC : srcL; float* dst = isc ? dstC : dstL;
;         const float* gv = gate + (isc ? 2 : (u.pm >> 5)) * ADA;
; #pragma unroll
;         for (int bj = 0; bj < 2; ++bj) {
;             const int col = col0 + bj * 128;
;             const f32x4 g0 = *(const f32x4*)(gv + col), g1 = *(const f32x4*)(gv + col + 4);
; #pragma unroll
;             for (int ai = 0; ai < 2; ++ai)
; #pragma unroll
;                 for (int m = 0; m < 4; ++m) {
;                     const size_t off = (size_t)(row0 + ai * 128 + m * 16) * DM + col;
;                     const f32x4 s0 = *(const f32x4*)(src + off), s1 = *(const f32x4*)(src + off + 4);
;                     *(f32x4*)(dst + off) = s0 + g0 * acc[ai][bj][m][0];
;                     *(f32x4*)(dst + off + 4) = s1 + g1 * acc[ai][bj][m][1];
;                 }
;         }
;     }
.LBB0_873:
	s_lshl_b32 s4, s66, 8
	s_add_i32 s5, s4, 0xffffc000
	s_lshr_b32 s6, s66, 5
	s_cmp_gt_i32 s66, 63
	s_cselect_b32 s4, s5, s4
	s_mulk_i32 s6, 0x3000
	v_add_u32_e32 v162, s4, v164
	s_cselect_b32 s4, 0x6000, s6
	v_lshl_or_b32 v160, s65, 8, v173
	s_cselect_b32 s45, s57, s55
	s_cselect_b32 s44, s58, s56
	s_cselect_b32 s43, s54, s41
	s_cselect_b32 s42, s53, s40
	s_ashr_i32 s5, s4, 31
	v_ashrrev_i32_e32 v163, 31, v162
	s_lshl_b64 s[4:5], s[4:5], 2
	v_ashrrev_i32_e32 v161, 31, v160
	v_lshlrev_b64 v[156:157], 11, v[162:163]
	s_add_u32 s4, s59, s4
	v_lshl_add_u64 v[156:157], v[156:157], 0, v[160:161]
	s_addc_u32 s5, s60, s5
	v_lshlrev_b64 v[158:159], 2, v[156:157]
	v_lshl_add_u64 v[154:155], v[160:161], 2, s[4:5]
	global_load_dwordx4 v[232:235], v[154:155], off
	global_load_dwordx4 v[236:239], v[154:155], off offset:16
	global_load_dwordx4 v[248:251], v[154:155], off offset:512
	global_load_dwordx4 v[252:255], v[154:155], off offset:528
	v_mov_b64_e32 v[156:157], v[158:159]
	s_mov_b32 s4, 0x20000
	s_mov_b32 s5, 0
	v_lshl_add_u64 v[160:161], s[44:45], 0, v[156:157]
	global_load_dwordx4 v[132:135], v[160:161], off
	global_load_dwordx4 v[136:139], v[160:161], off offset:16
	global_load_dwordx4 v[176:179], v[160:161], off offset:512
	global_load_dwordx4 v[180:183], v[160:161], off offset:528
	v_lshl_add_u64 v[156:157], v[156:157], 0, s[4:5]
	v_lshl_add_u64 v[160:161], s[44:45], 0, v[156:157]
	global_load_dwordx4 v[184:187], v[160:161], off
	global_load_dwordx4 v[188:191], v[160:161], off offset:16
	global_load_dwordx4 v[192:195], v[160:161], off offset:512
	global_load_dwordx4 v[196:199], v[160:161], off offset:528
	v_lshl_add_u64 v[156:157], v[156:157], 0, s[4:5]
	v_lshl_add_u64 v[160:161], s[44:45], 0, v[156:157]
	global_load_dwordx4 v[200:203], v[160:161], off
	global_load_dwordx4 v[204:207], v[160:161], off offset:16
	global_load_dwordx4 v[208:211], v[160:161], off offset:512
	global_load_dwordx4 v[212:215], v[160:161], off offset:528
	v_lshl_add_u64 v[156:157], v[156:157], 0, s[4:5]
	v_lshl_add_u64 v[160:161], s[44:45], 0, v[156:157]
	global_load_dwordx4 v[216:219], v[160:161], off
	global_load_dwordx4 v[220:223], v[160:161], off offset:16
	global_load_dwordx4 v[224:227], v[160:161], off offset:512
	global_load_dwordx4 v[228:231], v[160:161], off offset:528
	s_mov_b32 s4, 0xa0000
	v_lshl_add_u64 v[156:157], v[156:157], 0, s[4:5]
	s_mov_b32 s4, 0x20000
	s_waitcnt vmcnt(12)
	v_pk_fma_f32 v[128:129], v[128:129], v[232:233], v[132:133]
	v_pk_fma_f32 v[130:131], v[130:131], v[234:235], v[134:135]
	v_pk_fma_f32 v[124:125], v[124:125], v[236:237], v[136:137]
	v_pk_fma_f32 v[126:127], v[126:127], v[238:239], v[138:139]
	v_pk_fma_f32 v[64:65], v[64:65], v[248:249], v[176:177]
	v_pk_fma_f32 v[66:67], v[66:67], v[250:251], v[178:179]
	v_pk_fma_f32 v[60:61], v[60:61], v[252:253], v[180:181]
	v_pk_fma_f32 v[62:63], v[62:63], v[254:255], v[182:183]
	v_lshl_add_u64 v[162:163], s[42:43], 0, v[158:159]
	global_store_dwordx4 v[162:163], v[128:131], off
	global_store_dwordx4 v[162:163], v[124:127], off offset:16
	global_store_dwordx4 v[162:163], v[64:67], off offset:512
	global_store_dwordx4 v[162:163], v[60:63], off offset:528
	v_lshl_add_u64 v[158:159], v[158:159], 0, s[4:5]
	v_lshl_add_u64 v[160:161], s[44:45], 0, v[156:157]
	global_load_dwordx4 v[132:135], v[160:161], off
	global_load_dwordx4 v[136:139], v[160:161], off offset:16
	global_load_dwordx4 v[176:179], v[160:161], off offset:512
	global_load_dwordx4 v[180:183], v[160:161], off offset:528
	v_lshl_add_u64 v[156:157], v[156:157], 0, s[4:5]
	s_waitcnt vmcnt(16)
	v_pk_fma_f32 v[120:121], v[120:121], v[232:233], v[184:185]
	v_pk_fma_f32 v[122:123], v[122:123], v[234:235], v[186:187]
	v_pk_fma_f32 v[116:117], v[116:117], v[236:237], v[188:189]
	v_pk_fma_f32 v[118:119], v[118:119], v[238:239], v[190:191]
	v_pk_fma_f32 v[56:57], v[56:57], v[248:249], v[192:193]
	v_pk_fma_f32 v[58:59], v[58:59], v[250:251], v[194:195]
	v_pk_fma_f32 v[52:53], v[52:53], v[252:253], v[196:197]
	v_pk_fma_f32 v[54:55], v[54:55], v[254:255], v[198:199]
	v_lshl_add_u64 v[162:163], s[42:43], 0, v[158:159]
	global_store_dwordx4 v[162:163], v[120:123], off
	global_store_dwordx4 v[162:163], v[116:119], off offset:16
	global_store_dwordx4 v[162:163], v[56:59], off offset:512
	global_store_dwordx4 v[162:163], v[52:55], off offset:528
	v_lshl_add_u64 v[158:159], v[158:159], 0, s[4:5]
	v_lshl_add_u64 v[160:161], s[44:45], 0, v[156:157]
	global_load_dwordx4 v[184:187], v[160:161], off
	global_load_dwordx4 v[188:191], v[160:161], off offset:16
	global_load_dwordx4 v[192:195], v[160:161], off offset:512
	global_load_dwordx4 v[196:199], v[160:161], off offset:528
	v_lshl_add_u64 v[156:157], v[156:157], 0, s[4:5]
	s_waitcnt vmcnt(20)
;     __device__ __forceinline__ void operator()(const f32x4 (&acc)[2][2][4][2], const Unit& u, int wr, int wc, int fr, int fq) const {
;         const bool isc = u.pm >= 64;
;         const int row0 = (isc ? (u.pm - 64) * 256 : u.pm * 256) + wr * 64 + fr, col0 = u.pn * 256 + wc * 32 + 8 * fq;
;         const float* src = isc ? srcC : srcL; float* dst = isc ? dstC : dstL;
;         const float* gv = gate + (isc ? 2 : (u.pm >> 5)) * ADA;
; #pragma unroll
;         for (int bj = 0; bj < 2; ++bj) {
;             const int col = col0 + bj * 128;
;             const f32x4 g0 = *(const f32x4*)(gv + col), g1 = *(const f32x4*)(gv + col + 4);
; #pragma unroll
;             for (int ai = 0; ai < 2; ++ai)
; #pragma unroll
;                 for (int m = 0; m < 4; ++m) {
;                     const size_t off = (size_t)(row0 + ai * 128 + m * 16) * DM + col;
;                     const f32x4 s0 = *(const f32x4*)(src + off), s1 = *(const f32x4*)(src + off + 4);
;                     *(f32x4*)(dst + off) = s0 + g0 * acc[ai][bj][m][0];
;                     *(f32x4*)(dst + off + 4) = s1 + g1 * acc[ai][bj][m][1];
;                 }
;         }
;     }
	v_pk_fma_f32 v[112:113], v[112:113], v[232:233], v[200:201]
	v_pk_fma_f32 v[114:115], v[114:115], v[234:235], v[202:203]
	v_pk_fma_f32 v[108:109], v[108:109], v[236:237], v[204:205]
	v_pk_fma_f32 v[110:111], v[110:111], v[238:239], v[206:207]
	v_pk_fma_f32 v[48:49], v[48:49], v[248:249], v[208:209]
	v_pk_fma_f32 v[50:51], v[50:51], v[250:251], v[210:211]
	v_pk_fma_f32 v[44:45], v[44:45], v[252:253], v[212:213]
	v_pk_fma_f32 v[46:47], v[46:47], v[254:255], v[214:215]
	v_lshl_add_u64 v[162:163], s[42:43], 0, v[158:159]
	global_store_dwordx4 v[162:163], v[112:115], off
	global_store_dwordx4 v[162:163], v[108:111], off offset:16
	global_store_dwordx4 v[162:163], v[48:51], off offset:512
	global_store_dwordx4 v[162:163], v[44:47], off offset:528
	v_lshl_add_u64 v[158:159], v[158:159], 0, s[4:5]
	v_lshl_add_u64 v[160:161], s[44:45], 0, v[156:157]
	global_load_dwordx4 v[200:203], v[160:161], off
	global_load_dwordx4 v[204:207], v[160:161], off offset:16
	global_load_dwordx4 v[208:211], v[160:161], off offset:512
	global_load_dwordx4 v[212:215], v[160:161], off offset:528
	v_lshl_add_u64 v[156:157], v[156:157], 0, s[4:5]
	s_waitcnt vmcnt(24)
	v_pk_fma_f32 v[104:105], v[104:105], v[232:233], v[216:217]
	v_pk_fma_f32 v[106:107], v[106:107], v[234:235], v[218:219]
	v_pk_fma_f32 v[100:101], v[100:101], v[236:237], v[220:221]
	v_pk_fma_f32 v[102:103], v[102:103], v[238:239], v[222:223]
	v_pk_fma_f32 v[40:41], v[40:41], v[248:249], v[224:225]
	v_pk_fma_f32 v[42:43], v[42:43], v[250:251], v[226:227]
	v_pk_fma_f32 v[36:37], v[36:37], v[252:253], v[228:229]
	v_pk_fma_f32 v[38:39], v[38:39], v[254:255], v[230:231]
	v_lshl_add_u64 v[162:163], s[42:43], 0, v[158:159]
	global_store_dwordx4 v[162:163], v[104:107], off
	global_store_dwordx4 v[162:163], v[100:103], off offset:16
	global_store_dwordx4 v[162:163], v[40:43], off offset:512
	global_store_dwordx4 v[162:163], v[36:39], off offset:528
	s_mov_b32 s4, 0xa0000
	v_lshl_add_u64 v[158:159], v[158:159], 0, s[4:5]
	s_mov_b32 s4, 0x20000
	v_lshl_add_u64 v[160:161], s[44:45], 0, v[156:157]
	global_load_dwordx4 v[216:219], v[160:161], off
	global_load_dwordx4 v[220:223], v[160:161], off offset:16
	global_load_dwordx4 v[224:227], v[160:161], off offset:512
	global_load_dwordx4 v[228:231], v[160:161], off offset:528
	s_waitcnt vmcnt(24)
	v_pk_fma_f32 v[96:97], v[96:97], v[232:233], v[132:133]
	v_pk_fma_f32 v[98:99], v[98:99], v[234:235], v[134:135]
	v_pk_fma_f32 v[92:93], v[92:93], v[236:237], v[136:137]
	v_pk_fma_f32 v[94:95], v[94:95], v[238:239], v[138:139]
	v_pk_fma_f32 v[28:29], v[28:29], v[248:249], v[176:177]
	v_pk_fma_f32 v[30:31], v[30:31], v[250:251], v[178:179]
	v_pk_fma_f32 v[24:25], v[24:25], v[252:253], v[180:181]
	v_pk_fma_f32 v[26:27], v[26:27], v[254:255], v[182:183]
	v_lshl_add_u64 v[162:163], s[42:43], 0, v[158:159]
	global_store_dwordx4 v[162:163], v[96:99], off
	global_store_dwordx4 v[162:163], v[92:95], off offset:16
	global_store_dwordx4 v[162:163], v[28:31], off offset:512
	global_store_dwordx4 v[162:163], v[24:27], off offset:528
	v_lshl_add_u64 v[158:159], v[158:159], 0, s[4:5]
	s_waitcnt vmcnt(20)
	v_pk_fma_f32 v[88:89], v[88:89], v[232:233], v[184:185]
	v_pk_fma_f32 v[90:91], v[90:91], v[234:235], v[186:187]
	v_pk_fma_f32 v[84:85], v[84:85], v[236:237], v[188:189]
	v_pk_fma_f32 v[86:87], v[86:87], v[238:239], v[190:191]
	v_pk_fma_f32 v[20:21], v[20:21], v[248:249], v[192:193]
	v_pk_fma_f32 v[22:23], v[22:23], v[250:251], v[194:195]
	v_pk_fma_f32 v[16:17], v[16:17], v[252:253], v[196:197]
	v_pk_fma_f32 v[18:19], v[18:19], v[254:255], v[198:199]
	v_lshl_add_u64 v[162:163], s[42:43], 0, v[158:159]
	global_store_dwordx4 v[162:163], v[88:91], off
	global_store_dwordx4 v[162:163], v[84:87], off offset:16
	global_store_dwordx4 v[162:163], v[20:23], off offset:512
	global_store_dwordx4 v[162:163], v[16:19], off offset:528
	v_lshl_add_u64 v[158:159], v[158:159], 0, s[4:5]
	s_waitcnt vmcnt(16)
	v_pk_fma_f32 v[80:81], v[80:81], v[232:233], v[200:201]
	v_pk_fma_f32 v[82:83], v[82:83], v[234:235], v[202:203]
	v_pk_fma_f32 v[76:77], v[76:77], v[236:237], v[204:205]
	v_pk_fma_f32 v[78:79], v[78:79], v[238:239], v[206:207]
	v_pk_fma_f32 v[12:13], v[12:13], v[248:249], v[208:209]
	v_pk_fma_f32 v[14:15], v[14:15], v[250:251], v[210:211]
	v_pk_fma_f32 v[8:9], v[8:9], v[252:253], v[212:213]
	v_pk_fma_f32 v[10:11], v[10:11], v[254:255], v[214:215]
	v_lshl_add_u64 v[162:163], s[42:43], 0, v[158:159]
	global_store_dwordx4 v[162:163], v[80:83], off
	global_store_dwordx4 v[162:163], v[76:79], off offset:16
	global_store_dwordx4 v[162:163], v[12:15], off offset:512
	global_store_dwordx4 v[162:163], v[8:11], off offset:528
	v_lshl_add_u64 v[158:159], v[158:159], 0, s[4:5]
	s_waitcnt vmcnt(12)
	v_pk_fma_f32 v[72:73], v[72:73], v[232:233], v[216:217]
	v_pk_fma_f32 v[74:75], v[74:75], v[234:235], v[218:219]
	v_pk_fma_f32 v[68:69], v[68:69], v[236:237], v[220:221]
	v_pk_fma_f32 v[70:71], v[70:71], v[238:239], v[222:223]
	v_pk_fma_f32 v[4:5], v[4:5], v[248:249], v[224:225]
	v_pk_fma_f32 v[6:7], v[6:7], v[250:251], v[226:227]
	v_pk_fma_f32 v[0:1], v[0:1], v[252:253], v[228:229]
	v_pk_fma_f32 v[2:3], v[2:3], v[254:255], v[230:231]
	v_lshl_add_u64 v[162:163], s[42:43], 0, v[158:159]
	global_store_dwordx4 v[162:163], v[72:75], off
	global_store_dwordx4 v[162:163], v[68:71], off offset:16
	global_store_dwordx4 v[162:163], v[4:7], off offset:512
	global_store_dwordx4 v[162:163], v[0:3], off offset:528
	s_mov_b64 s[6:7], -1
	s_mov_b64 s[4:5], 0x160000
	s_andn2_b64 vcc, exec, s[26:27]
	s_cbranch_vccnz .LBB0_856
	s_andn2_b64 vcc, exec, s[0:1]
	s_cbranch_vccnz .LBB0_855
	s_barrier
	s_branch .LBB0_855

;     __device__ __forceinline__ void operator()(const f32x4 (&acc)[2][2][4][2], const Unit& u, int wr, int wc, int fr, int fq) const {
;         const bool isc = u.pm >= 64;
;         const int row0 = (isc ? (u.pm - 64) * 256 : u.pm * 256) + wr * 64 + fr, col0 = u.pn * 256 + wc * 32 + 8 * fq;
;         const float* src = isc ? srcC : srcL; float* dst = isc ? dstC : dstL;
;         const float* gv = gate + (isc ? 2 : (u.pm >> 5)) * ADA;
; #pragma unroll
;         for (int bj = 0; bj < 2; ++bj) {
;             const int col = col0 + bj * 128;
;             const f32x4 g0 = *(const f32x4*)(gv + col), g1 = *(const f32x4*)(gv + col + 4);
; #pragma unroll
;             for (int ai = 0; ai < 2; ++ai)
; #pragma unroll
;                 for (int m = 0; m < 4; ++m) {
;                     const size_t off = (size_t)(row0 + ai * 128 + m * 16) * DM + col;
;                     const f32x4 s0 = *(const f32x4*)(src + off), s1 = *(const f32x4*)(src + off + 4);
;                     *(f32x4*)(dst + off) = s0 + g0 * acc[ai][bj][m][0];
;                     *(f32x4*)(dst + off + 4) = s1 + g1 * acc[ai][bj][m][1];
;                 }
;         }
;     }
.LBB0_1100:
	s_lshl_b32 s4, s62, 8
	s_add_i32 s5, s4, 0xffffc000
	s_lshr_b32 s6, s62, 5
	s_cmp_gt_i32 s62, 63
	s_cselect_b32 s4, s5, s4
	s_mulk_i32 s6, 0x3000
	v_add_u32_e32 v178, s4, v158
	s_cselect_b32 s4, 0x6000, s6
	s_cselect_b32 s27, s52, s41
	s_cselect_b32 s26, s51, s40
	s_ashr_i32 s5, s4, 31
	v_lshl_or_b32 v132, s61, 8, v160
	s_lshl_b64 s[4:5], s[4:5], 2
	v_ashrrev_i32_e32 v179, 31, v178
	s_add_u32 s4, s53, s4
	v_ashrrev_i32_e32 v133, 31, v132
	v_lshlrev_b64 v[156:157], 13, v[178:179]
	s_addc_u32 s5, s54, s5
	v_lshlrev_b64 v[180:181], 2, v[132:133]
	v_lshl_add_u64 v[156:157], s[26:27], 0, v[156:157]
	v_lshl_add_u64 v[154:155], s[4:5], 0, v[180:181]
	v_lshl_add_u64 v[156:157], v[156:157], 0, v[180:181]
	global_load_dwordx4 v[232:235], v[154:155], off
	global_load_dwordx4 v[236:239], v[154:155], off offset:16
	global_load_dwordx4 v[248:251], v[154:155], off offset:512
	global_load_dwordx4 v[252:255], v[154:155], off offset:528
	v_mov_b64_e32 v[240:241], v[156:157]
	v_mov_b64_e32 v[246:247], v[240:241]
	s_mov_b32 s4, 0x20000
	s_mov_b32 s5, 0
	global_load_dwordx4 v[132:135], v[246:247], off
	global_load_dwordx4 v[136:139], v[246:247], off offset:16
	global_load_dwordx4 v[154:157], v[246:247], off offset:512
	global_load_dwordx4 v[162:165], v[246:247], off offset:528
	v_lshl_add_u64 v[246:247], v[246:247], 0, s[4:5]
	global_load_dwordx4 v[174:177], v[246:247], off
	global_load_dwordx4 v[178:181], v[246:247], off offset:16
	global_load_dwordx4 v[182:185], v[246:247], off offset:512
	global_load_dwordx4 v[186:189], v[246:247], off offset:528
	v_lshl_add_u64 v[246:247], v[246:247], 0, s[4:5]
	global_load_dwordx4 v[190:193], v[246:247], off
	global_load_dwordx4 v[194:197], v[246:247], off offset:16
	global_load_dwordx4 v[198:201], v[246:247], off offset:512
	global_load_dwordx4 v[202:205], v[246:247], off offset:528
	v_lshl_add_u64 v[246:247], v[246:247], 0, s[4:5]
	global_load_dwordx4 v[206:209], v[246:247], off
	global_load_dwordx4 v[210:213], v[246:247], off offset:16
	global_load_dwordx4 v[214:217], v[246:247], off offset:512
	global_load_dwordx4 v[218:221], v[246:247], off offset:528
	s_mov_b32 s4, 0xa0000
	v_lshl_add_u64 v[246:247], v[246:247], 0, s[4:5]
	s_mov_b32 s4, 0x20000
	s_waitcnt vmcnt(12)
	v_pk_fma_f32 v[128:129], v[128:129], v[232:233], v[132:133]
	v_pk_fma_f32 v[130:131], v[130:131], v[234:235], v[134:135]
	v_pk_fma_f32 v[124:125], v[124:125], v[236:237], v[136:137]
	v_pk_fma_f32 v[126:127], v[126:127], v[238:239], v[138:139]
	v_pk_fma_f32 v[64:65], v[64:65], v[248:249], v[154:155]
	v_pk_fma_f32 v[66:67], v[66:67], v[250:251], v[156:157]
	v_pk_fma_f32 v[60:61], v[60:61], v[252:253], v[162:163]
	v_pk_fma_f32 v[62:63], v[62:63], v[254:255], v[164:165]
	global_store_dwordx4 v[240:241], v[128:131], off
	global_store_dwordx4 v[240:241], v[124:127], off offset:16
	global_store_dwordx4 v[240:241], v[64:67], off offset:512
	global_store_dwordx4 v[240:241], v[60:63], off offset:528
	v_lshl_add_u64 v[240:241], v[240:241], 0, s[4:5]
	global_load_dwordx4 v[132:135], v[246:247], off
	global_load_dwordx4 v[136:139], v[246:247], off offset:16
	global_load_dwordx4 v[154:157], v[246:247], off offset:512
	global_load_dwordx4 v[162:165], v[246:247], off offset:528
	v_lshl_add_u64 v[246:247], v[246:247], 0, s[4:5]
	s_waitcnt vmcnt(16)
	v_pk_fma_f32 v[120:121], v[120:121], v[232:233], v[174:175]
	v_pk_fma_f32 v[122:123], v[122:123], v[234:235], v[176:177]
	v_pk_fma_f32 v[116:117], v[116:117], v[236:237], v[178:179]
	v_pk_fma_f32 v[118:119], v[118:119], v[238:239], v[180:181]
	v_pk_fma_f32 v[56:57], v[56:57], v[248:249], v[182:183]
	v_pk_fma_f32 v[58:59], v[58:59], v[250:251], v[184:185]
	v_pk_fma_f32 v[52:53], v[52:53], v[252:253], v[186:187]
	v_pk_fma_f32 v[54:55], v[54:55], v[254:255], v[188:189]
	global_store_dwordx4 v[240:241], v[120:123], off
	global_store_dwordx4 v[240:241], v[116:119], off offset:16
	global_store_dwordx4 v[240:241], v[56:59], off offset:512
	global_store_dwordx4 v[240:241], v[52:55], off offset:528
	v_lshl_add_u64 v[240:241], v[240:241], 0, s[4:5]
	global_load_dwordx4 v[174:177], v[246:247], off
	global_load_dwordx4 v[178:181], v[246:247], off offset:16
	global_load_dwordx4 v[182:185], v[246:247], off offset:512
	global_load_dwordx4 v[186:189], v[246:247], off offset:528
	v_lshl_add_u64 v[246:247], v[246:247], 0, s[4:5]
	s_waitcnt vmcnt(20)
;     __device__ __forceinline__ void operator()(const f32x4 (&acc)[2][2][4][2], const Unit& u, int wr, int wc, int fr, int fq) const {
;         const bool isc = u.pm >= 64;
;         const int row0 = (isc ? (u.pm - 64) * 256 : u.pm * 256) + wr * 64 + fr, col0 = u.pn * 256 + wc * 32 + 8 * fq;
;         const float* src = isc ? srcC : srcL; float* dst = isc ? dstC : dstL;
;         const float* gv = gate + (isc ? 2 : (u.pm >> 5)) * ADA;
; #pragma unroll
;         for (int bj = 0; bj < 2; ++bj) {
;             const int col = col0 + bj * 128;
;             const f32x4 g0 = *(const f32x4*)(gv + col), g1 = *(const f32x4*)(gv + col + 4);
; #pragma unroll
;             for (int ai = 0; ai < 2; ++ai)
; #pragma unroll
;                 for (int m = 0; m < 4; ++m) {
;                     const size_t off = (size_t)(row0 + ai * 128 + m * 16) * DM + col;
;                     const f32x4 s0 = *(const f32x4*)(src + off), s1 = *(const f32x4*)(src + off + 4);
;                     *(f32x4*)(dst + off) = s0 + g0 * acc[ai][bj][m][0];
;                     *(f32x4*)(dst + off + 4) = s1 + g1 * acc[ai][bj][m][1];
;                 }
;         }
;     }
	v_pk_fma_f32 v[112:113], v[112:113], v[232:233], v[190:191]
	v_pk_fma_f32 v[114:115], v[114:115], v[234:235], v[192:193]
	v_pk_fma_f32 v[108:109], v[108:109], v[236:237], v[194:195]
	v_pk_fma_f32 v[110:111], v[110:111], v[238:239], v[196:197]
	v_pk_fma_f32 v[48:49], v[48:49], v[248:249], v[198:199]
	v_pk_fma_f32 v[50:51], v[50:51], v[250:251], v[200:201]
	v_pk_fma_f32 v[44:45], v[44:45], v[252:253], v[202:203]
	v_pk_fma_f32 v[46:47], v[46:47], v[254:255], v[204:205]
	global_store_dwordx4 v[240:241], v[112:115], off
	global_store_dwordx4 v[240:241], v[108:111], off offset:16
	global_store_dwordx4 v[240:241], v[48:51], off offset:512
	global_store_dwordx4 v[240:241], v[44:47], off offset:528
	v_lshl_add_u64 v[240:241], v[240:241], 0, s[4:5]
	global_load_dwordx4 v[190:193], v[246:247], off
	global_load_dwordx4 v[194:197], v[246:247], off offset:16
	global_load_dwordx4 v[198:201], v[246:247], off offset:512
	global_load_dwordx4 v[202:205], v[246:247], off offset:528
	v_lshl_add_u64 v[246:247], v[246:247], 0, s[4:5]
	s_waitcnt vmcnt(24)
	v_pk_fma_f32 v[104:105], v[104:105], v[232:233], v[206:207]
	v_pk_fma_f32 v[106:107], v[106:107], v[234:235], v[208:209]
	v_pk_fma_f32 v[100:101], v[100:101], v[236:237], v[210:211]
	v_pk_fma_f32 v[102:103], v[102:103], v[238:239], v[212:213]
	v_pk_fma_f32 v[40:41], v[40:41], v[248:249], v[214:215]
	v_pk_fma_f32 v[42:43], v[42:43], v[250:251], v[216:217]
	v_pk_fma_f32 v[36:37], v[36:37], v[252:253], v[218:219]
	v_pk_fma_f32 v[38:39], v[38:39], v[254:255], v[220:221]
	global_store_dwordx4 v[240:241], v[104:107], off
	global_store_dwordx4 v[240:241], v[100:103], off offset:16
	global_store_dwordx4 v[240:241], v[40:43], off offset:512
	global_store_dwordx4 v[240:241], v[36:39], off offset:528
	s_mov_b32 s4, 0xa0000
	v_lshl_add_u64 v[240:241], v[240:241], 0, s[4:5]
	s_mov_b32 s4, 0x20000
	global_load_dwordx4 v[206:209], v[246:247], off
	global_load_dwordx4 v[210:213], v[246:247], off offset:16
	global_load_dwordx4 v[214:217], v[246:247], off offset:512
	global_load_dwordx4 v[218:221], v[246:247], off offset:528
	s_waitcnt vmcnt(24)
	v_pk_fma_f32 v[96:97], v[96:97], v[232:233], v[132:133]
	v_pk_fma_f32 v[98:99], v[98:99], v[234:235], v[134:135]
	v_pk_fma_f32 v[92:93], v[92:93], v[236:237], v[136:137]
	v_pk_fma_f32 v[94:95], v[94:95], v[238:239], v[138:139]
	v_pk_fma_f32 v[28:29], v[28:29], v[248:249], v[154:155]
	v_pk_fma_f32 v[30:31], v[30:31], v[250:251], v[156:157]
	v_pk_fma_f32 v[24:25], v[24:25], v[252:253], v[162:163]
	v_pk_fma_f32 v[26:27], v[26:27], v[254:255], v[164:165]
	global_store_dwordx4 v[240:241], v[96:99], off
	global_store_dwordx4 v[240:241], v[92:95], off offset:16
	global_store_dwordx4 v[240:241], v[28:31], off offset:512
	global_store_dwordx4 v[240:241], v[24:27], off offset:528
	v_lshl_add_u64 v[240:241], v[240:241], 0, s[4:5]
	s_waitcnt vmcnt(20)
	v_pk_fma_f32 v[88:89], v[88:89], v[232:233], v[174:175]
	v_pk_fma_f32 v[90:91], v[90:91], v[234:235], v[176:177]
	v_pk_fma_f32 v[84:85], v[84:85], v[236:237], v[178:179]
	v_pk_fma_f32 v[86:87], v[86:87], v[238:239], v[180:181]
	v_pk_fma_f32 v[20:21], v[20:21], v[248:249], v[182:183]
	v_pk_fma_f32 v[22:23], v[22:23], v[250:251], v[184:185]
	v_pk_fma_f32 v[16:17], v[16:17], v[252:253], v[186:187]
	v_pk_fma_f32 v[18:19], v[18:19], v[254:255], v[188:189]
	global_store_dwordx4 v[240:241], v[88:91], off
	global_store_dwordx4 v[240:241], v[84:87], off offset:16
	global_store_dwordx4 v[240:241], v[20:23], off offset:512
	global_store_dwordx4 v[240:241], v[16:19], off offset:528
	v_lshl_add_u64 v[240:241], v[240:241], 0, s[4:5]
	s_waitcnt vmcnt(16)
	v_pk_fma_f32 v[80:81], v[80:81], v[232:233], v[190:191]
	v_pk_fma_f32 v[82:83], v[82:83], v[234:235], v[192:193]
	v_pk_fma_f32 v[76:77], v[76:77], v[236:237], v[194:195]
	v_pk_fma_f32 v[78:79], v[78:79], v[238:239], v[196:197]
	v_pk_fma_f32 v[12:13], v[12:13], v[248:249], v[198:199]
	v_pk_fma_f32 v[14:15], v[14:15], v[250:251], v[200:201]
	v_pk_fma_f32 v[8:9], v[8:9], v[252:253], v[202:203]
	v_pk_fma_f32 v[10:11], v[10:11], v[254:255], v[204:205]
	global_store_dwordx4 v[240:241], v[80:83], off
	global_store_dwordx4 v[240:241], v[76:79], off offset:16
	global_store_dwordx4 v[240:241], v[12:15], off offset:512
	global_store_dwordx4 v[240:241], v[8:11], off offset:528
	v_lshl_add_u64 v[240:241], v[240:241], 0, s[4:5]
	s_waitcnt vmcnt(12)
	v_pk_fma_f32 v[72:73], v[72:73], v[232:233], v[206:207]
	v_pk_fma_f32 v[74:75], v[74:75], v[234:235], v[208:209]
	v_pk_fma_f32 v[68:69], v[68:69], v[236:237], v[210:211]
	v_pk_fma_f32 v[70:71], v[70:71], v[238:239], v[212:213]
	v_pk_fma_f32 v[4:5], v[4:5], v[248:249], v[214:215]
	v_pk_fma_f32 v[6:7], v[6:7], v[250:251], v[216:217]
	v_pk_fma_f32 v[0:1], v[0:1], v[252:253], v[218:219]
	v_pk_fma_f32 v[2:3], v[2:3], v[254:255], v[220:221]
	global_store_dwordx4 v[240:241], v[72:75], off
	global_store_dwordx4 v[240:241], v[68:71], off offset:16
	global_store_dwordx4 v[240:241], v[4:7], off offset:512
	global_store_dwordx4 v[240:241], v[0:3], off offset:528
	s_mov_b64 s[6:7], -1
	s_mov_b64 s[4:5], 0x160000
	s_and_b64 vcc, exec, s[38:39]
	s_cbranch_vccnz .LBB0_1081
	s_andn2_b64 vcc, exec, s[0:1]
	s_cbranch_vccnz .LBB0_1080
	s_barrier
	s_branch .LBB0_1080
